# v22: + GEMM loop redundant setprio/waitcnt removal, pass1 QK chain LDS reads software-pipelined, P3 epilogue sumsq hoists
# baseline (speedup 1.0000x reference)
; #define PG8_STAGE(bufoff, gbase, voff) do { _Pragma("unroll") for (int _i = 0; _i < 2; ++_i) \
;         __builtin_amdgcn_global_load_lds((const unsigned*)((const char*)(gbase) + (voff)[_i]), (PG8_LAS unsigned*)(lds + (bufoff) + ldsw + _i * 8192), 16, 0, 0); } while (0)
; #define PG8_LDA(dst, b, h) do { _Pragma("unroll") for (int m = 0; m < 4; ++m) _Pragma("unroll") for (int k = 0; k < 2; ++k) dst[m][k] = *(const PG8_LAS bf16x8*)(lds + PG8_SA(b, h) + aoff + m * 2048 + k * 1024); } while (0)
; #define PG8_LDB(dst, b, h) do { _Pragma("unroll") for (int n = 0; n < 2; ++n) _Pragma("unroll") for (int k = 0; k < 2; ++k) dst[n][k] = *(const PG8_LAS bf16x8*)(lds + PG8_SB(b, h) + boff + n * 2048 + k * 1024); } while (0)
; #define PG8_MMA(ai, bj, At, Bt) do { __builtin_amdgcn_s_setprio(1); _Pragma("unroll") for (int m = 0; m < 4; ++m) _Pragma("unroll") for (int n = 0; n < 2; ++n) _Pragma("unroll") for (int k = 0; k < 2; ++k) \
;         acc[ai][bj][m][n] = __builtin_amdgcn_mfma_f32_16x16x32_bf16(Bt[n][k], At[m][k], acc[ai][bj][m][n], 0, 0, 0); __builtin_amdgcn_s_setprio(0); } while (0)
; #define PG8_WAIT_V(n) asm volatile("s_waitcnt vmcnt(" #n ")" ::: "memory")
; #define PG8_WAIT_L(n) asm volatile("s_waitcnt lgkmcnt(" #n ")" ::: "memory")
; #define PG8_BAR __builtin_amdgcn_s_barrier()
; #define PG8_SCHED __builtin_amdgcn_sched_barrier(0)
; template <class Epi, class Sched, bool ALIGN_EPI = false, bool SP2 = false>
; __device__ __forceinline__ void gemm_phase(PG8_LAS unsigned char* lds, const Gemm g, const Sched& S, const Epi& E) {
;     ...
;             PG8_LDB(B0, 0, 0); PG8_LDB(B1, 0, 1); PG8_SCHED; PG8_LDA(At, 0, 0); PG8_STAGE(PG8_SA(1, 1), a1 + hstep, voffA);
;             PG8_WAIT_V(8); PG8_WAIT_L(0); PG8_BAR; PG8_MMA(0, 0, At, B0); PG8_MMA(0, 1, At, B1); PG8_BAR; PG8_SCHED;
;             PG8_LDA(At, 0, 1); PG8_STAGE(PG8_SB(0, 0), b2, voffB); PG8_STAGE(PG8_SB(0, 1), b2 + hstep, voffB); PG8_STAGE(PG8_SA(0, 0), a2, voffA);
;             PG8_WAIT_V(8); PG8_WAIT_L(0); PG8_BAR; PG8_MMA(1, 0, At, B0); PG8_MMA(1, 1, At, B1); PG8_BAR; PG8_SCHED;
.LBB0_192:
	ds_read_b128 v[150:153], v147
	ds_read_b128 v[154:157], v147 offset:1024
	ds_read_b128 v[158:161], v147 offset:2048
	ds_read_b128 v[162:165], v147 offset:3072
	ds_read_b128 v[166:169], v148
	ds_read_b128 v[170:173], v148 offset:1024
	ds_read_b128 v[174:177], v148 offset:2048
	ds_read_b128 v[178:181], v148 offset:3072
	s_add_u32 s24, s22, 0xfffc0080
	s_addc_u32 s25, s23, -1
	s_cmp_eq_u32 s54, 12
	s_cselect_b32 s31, s15, s25
	s_cselect_b32 s30, s50, s24
	s_cselect_b32 s25, s9, s53
	s_cselect_b32 s24, s51, s52
	v_lshl_add_u64 v[186:187], s[22:23], 0, v[136:137]
	s_add_i32 m0, s21, 0xc000
	ds_read_b128 v[182:185], v149
	ds_read_b128 v[192:195], v149 offset:1024
	ds_read_b128 v[196:199], v149 offset:2048
	ds_read_b128 v[200:203], v149 offset:3072
	ds_read_b128 v[204:207], v149 offset:4096
	ds_read_b128 v[208:211], v149 offset:5120
	ds_read_b128 v[212:215], v149 offset:6144
	ds_read_b128 v[216:219], v149 offset:7168
	global_load_lds_dwordx4 v[186:187], off
	v_lshl_add_u64 v[186:187], s[22:23], 0, v[138:139]
	s_add_i32 m0, s21, 0xe000
	s_nop 0
	global_load_lds_dwordx4 v[186:187], off
	s_waitcnt vmcnt(8)
	s_waitcnt lgkmcnt(0)
	s_barrier
	s_setprio 1
	v_mfma_f32_16x16x32_bf16 v[124:127], v[150:153], v[182:185], v[124:127]
	v_mfma_f32_16x16x32_bf16 v[120:123], v[158:161], v[182:185], v[120:123]
	v_mfma_f32_16x16x32_bf16 v[108:111], v[150:153], v[196:199], v[108:111]
	v_mfma_f32_16x16x32_bf16 v[104:107], v[158:161], v[196:199], v[104:107]
	v_mfma_f32_16x16x32_bf16 v[92:95], v[150:153], v[204:207], v[92:95]
	v_mfma_f32_16x16x32_bf16 v[88:91], v[158:161], v[204:207], v[88:91]
	v_mfma_f32_16x16x32_bf16 v[76:79], v[150:153], v[212:215], v[76:79]
	v_mfma_f32_16x16x32_bf16 v[72:75], v[158:161], v[212:215], v[72:75]
	v_mfma_f32_16x16x32_bf16 v[124:127], v[154:157], v[192:195], v[124:127]
	v_mfma_f32_16x16x32_bf16 v[120:123], v[162:165], v[192:195], v[120:123]
	v_mfma_f32_16x16x32_bf16 v[108:111], v[154:157], v[200:203], v[108:111]
	v_mfma_f32_16x16x32_bf16 v[104:107], v[162:165], v[200:203], v[104:107]
	v_mfma_f32_16x16x32_bf16 v[92:95], v[154:157], v[208:211], v[92:95]
	v_mfma_f32_16x16x32_bf16 v[88:91], v[162:165], v[208:211], v[88:91]
	v_mfma_f32_16x16x32_bf16 v[76:79], v[154:157], v[216:219], v[76:79]
	v_mfma_f32_16x16x32_bf16 v[72:75], v[162:165], v[216:219], v[72:75]
	v_mfma_f32_16x16x32_bf16 v[116:119], v[166:169], v[182:185], v[116:119]
	v_mfma_f32_16x16x32_bf16 v[112:115], v[174:177], v[182:185], v[112:115]
	v_mfma_f32_16x16x32_bf16 v[100:103], v[166:169], v[196:199], v[100:103]
	v_mfma_f32_16x16x32_bf16 v[96:99], v[174:177], v[196:199], v[96:99]
	v_mfma_f32_16x16x32_bf16 v[84:87], v[166:169], v[204:207], v[84:87]
	v_mfma_f32_16x16x32_bf16 v[80:83], v[174:177], v[204:207], v[80:83]
	v_mfma_f32_16x16x32_bf16 v[68:71], v[166:169], v[212:215], v[68:71]
	v_mfma_f32_16x16x32_bf16 v[64:67], v[174:177], v[212:215], v[64:67]
	v_mfma_f32_16x16x32_bf16 v[116:119], v[170:173], v[192:195], v[116:119]
	v_mfma_f32_16x16x32_bf16 v[112:115], v[178:181], v[192:195], v[112:115]
	v_mfma_f32_16x16x32_bf16 v[100:103], v[170:173], v[200:203], v[100:103]
	v_mfma_f32_16x16x32_bf16 v[96:99], v[178:181], v[200:203], v[96:99]
	v_mfma_f32_16x16x32_bf16 v[84:87], v[170:173], v[208:211], v[84:87]
	v_mfma_f32_16x16x32_bf16 v[80:83], v[178:181], v[208:211], v[80:83]
	v_mfma_f32_16x16x32_bf16 v[68:71], v[170:173], v[216:219], v[68:71]
	v_mfma_f32_16x16x32_bf16 v[64:67], v[178:181], v[216:219], v[64:67]
	s_setprio 0
	s_barrier
	s_add_i32 s55, s46, s35
	v_lshl_add_u64 v[186:187], s[24:25], 0, v[132:133]
	s_mov_b32 m0, s55
	ds_read_b128 v[182:185], v149 offset:16384
	ds_read_b128 v[192:195], v149 offset:17408
	ds_read_b128 v[196:199], v149 offset:18432
	ds_read_b128 v[200:203], v149 offset:19456
	ds_read_b128 v[204:207], v149 offset:20480
	ds_read_b128 v[208:211], v149 offset:21504
	ds_read_b128 v[212:215], v149 offset:22528
	ds_read_b128 v[216:219], v149 offset:23552
	global_load_lds_dwordx4 v[186:187], off
	s_add_i32 m0, s55, 0x2000
	s_add_u32 s56, s24, 0x40000
	v_lshl_add_u64 v[220:221], s[24:25], 0, v[128:129]
	s_addc_u32 s57, s25, 0
	s_add_i32 s55, s47, s35
	global_load_lds_dwordx4 v[220:221], off
	v_lshl_add_u64 v[222:223], s[56:57], 0, v[132:133]
	s_mov_b32 m0, s55
	v_lshl_add_u64 v[224:225], s[30:31], 0, v[130:131]
	global_load_lds_dwordx4 v[222:223], off
	v_lshl_add_u64 v[222:223], s[56:57], 0, v[128:129]
	s_add_i32 m0, s55, 0x2000
	s_nop 0
	global_load_lds_dwordx4 v[222:223], off
	v_lshl_add_u64 v[222:223], s[30:31], 0, v[134:135]
	s_mov_b32 m0, s21
	s_nop 0
	global_load_lds_dwordx4 v[222:223], off
	s_mov_b32 m0, s38
	s_nop 0
	global_load_lds_dwordx4 v[224:225], off
	s_waitcnt vmcnt(8)
	s_waitcnt lgkmcnt(0)
	s_barrier
; #define PG8_STAGE(bufoff, gbase, voff) do { _Pragma("unroll") for (int _i = 0; _i < 2; ++_i) \
;         __builtin_amdgcn_global_load_lds((const unsigned*)((const char*)(gbase) + (voff)[_i]), (PG8_LAS unsigned*)(lds + (bufoff) + ldsw + _i * 8192), 16, 0, 0); } while (0)
; #define PG8_LDA(dst, b, h) do { _Pragma("unroll") for (int m = 0; m < 4; ++m) _Pragma("unroll") for (int k = 0; k < 2; ++k) dst[m][k] = *(const PG8_LAS bf16x8*)(lds + PG8_SA(b, h) + aoff + m * 2048 + k * 1024); } while (0)
; #define PG8_LDB(dst, b, h) do { _Pragma("unroll") for (int n = 0; n < 2; ++n) _Pragma("unroll") for (int k = 0; k < 2; ++k) dst[n][k] = *(const PG8_LAS bf16x8*)(lds + PG8_SB(b, h) + boff + n * 2048 + k * 1024); } while (0)
; #define PG8_MMA(ai, bj, At, Bt) do { __builtin_amdgcn_s_setprio(1); _Pragma("unroll") for (int m = 0; m < 4; ++m) _Pragma("unroll") for (int n = 0; n < 2; ++n) _Pragma("unroll") for (int k = 0; k < 2; ++k) \
;         acc[ai][bj][m][n] = __builtin_amdgcn_mfma_f32_16x16x32_bf16(Bt[n][k], At[m][k], acc[ai][bj][m][n], 0, 0, 0); __builtin_amdgcn_s_setprio(0); } while (0)
; #define PG8_WAIT_V(n) asm volatile("s_waitcnt vmcnt(" #n ")" ::: "memory")
; #define PG8_WAIT_L(n) asm volatile("s_waitcnt lgkmcnt(" #n ")" ::: "memory")
; #define PG8_BAR __builtin_amdgcn_s_barrier()
; #define PG8_SCHED __builtin_amdgcn_sched_barrier(0)
; template <class Epi, class Sched, bool ALIGN_EPI = false, bool SP2 = false>
; __device__ __forceinline__ void gemm_phase(PG8_LAS unsigned char* lds, const Gemm g, const Sched& S, const Epi& E) {
;     ...
;             PG8_LDA(At, 0, 1); PG8_STAGE(PG8_SB(0, 0), b2, voffB); PG8_STAGE(PG8_SB(0, 1), b2 + hstep, voffB); PG8_STAGE(PG8_SA(0, 0), a2, voffA);
;             PG8_WAIT_V(8); PG8_WAIT_L(0); PG8_BAR; PG8_MMA(1, 0, At, B0); PG8_MMA(1, 1, At, B1); PG8_BAR; PG8_SCHED;
;             PG8_LDB(B0, 1, 0); PG8_LDB(B1, 1, 1); PG8_SCHED; PG8_LDA(At, 1, 0); PG8_STAGE(PG8_SA(0, 1), a2 + hstep, voffA);
;             PG8_WAIT_V(8); PG8_WAIT_L(0); PG8_BAR; PG8_MMA(0, 0, At, B0); PG8_MMA(0, 1, At, B1); PG8_BAR; PG8_SCHED;
	s_setprio 1
	v_mfma_f32_16x16x32_bf16 v[60:63], v[150:153], v[182:185], v[60:63]
	v_mfma_f32_16x16x32_bf16 v[56:59], v[158:161], v[182:185], v[56:59]
	v_mfma_f32_16x16x32_bf16 v[44:47], v[150:153], v[196:199], v[44:47]
	v_mfma_f32_16x16x32_bf16 v[40:43], v[158:161], v[196:199], v[40:43]
	v_mfma_f32_16x16x32_bf16 v[28:31], v[150:153], v[204:207], v[28:31]
	v_mfma_f32_16x16x32_bf16 v[24:27], v[158:161], v[204:207], v[24:27]
	v_mfma_f32_16x16x32_bf16 v[12:15], v[150:153], v[212:215], v[12:15]
	v_mfma_f32_16x16x32_bf16 v[8:11], v[158:161], v[212:215], v[8:11]
	v_mfma_f32_16x16x32_bf16 v[60:63], v[154:157], v[192:195], v[60:63]
	v_mfma_f32_16x16x32_bf16 v[56:59], v[162:165], v[192:195], v[56:59]
	v_mfma_f32_16x16x32_bf16 v[44:47], v[154:157], v[200:203], v[44:47]
	v_mfma_f32_16x16x32_bf16 v[40:43], v[162:165], v[200:203], v[40:43]
	v_mfma_f32_16x16x32_bf16 v[28:31], v[154:157], v[208:211], v[28:31]
	v_mfma_f32_16x16x32_bf16 v[24:27], v[162:165], v[208:211], v[24:27]
	v_mfma_f32_16x16x32_bf16 v[12:15], v[154:157], v[216:219], v[12:15]
	v_mfma_f32_16x16x32_bf16 v[8:11], v[162:165], v[216:219], v[8:11]
	v_mfma_f32_16x16x32_bf16 v[52:55], v[166:169], v[182:185], v[52:55]
	v_mfma_f32_16x16x32_bf16 v[48:51], v[174:177], v[182:185], v[48:51]
	v_mfma_f32_16x16x32_bf16 v[36:39], v[166:169], v[196:199], v[36:39]
	v_mfma_f32_16x16x32_bf16 v[32:35], v[174:177], v[196:199], v[32:35]
	v_mfma_f32_16x16x32_bf16 v[20:23], v[166:169], v[204:207], v[20:23]
	v_mfma_f32_16x16x32_bf16 v[16:19], v[174:177], v[204:207], v[16:19]
	v_mfma_f32_16x16x32_bf16 v[4:7], v[166:169], v[212:215], v[4:7]
	v_mfma_f32_16x16x32_bf16 v[0:3], v[174:177], v[212:215], v[0:3]
	v_mfma_f32_16x16x32_bf16 v[52:55], v[170:173], v[192:195], v[52:55]
	v_mfma_f32_16x16x32_bf16 v[48:51], v[178:181], v[192:195], v[48:51]
	v_mfma_f32_16x16x32_bf16 v[36:39], v[170:173], v[200:203], v[36:39]
	v_mfma_f32_16x16x32_bf16 v[32:35], v[178:181], v[200:203], v[32:35]
	v_mfma_f32_16x16x32_bf16 v[20:23], v[170:173], v[208:211], v[20:23]
	v_mfma_f32_16x16x32_bf16 v[16:19], v[178:181], v[208:211], v[16:19]
	v_mfma_f32_16x16x32_bf16 v[4:7], v[170:173], v[216:219], v[4:7]
	v_mfma_f32_16x16x32_bf16 v[0:3], v[178:181], v[216:219], v[0:3]
	s_setprio 0
	s_barrier
	s_add_i32 s55, 0, 0x18000
	s_add_i32 s56, 0, 0x1c000
	v_add_u32_e32 v162, s55, v145
	v_add_u32_e32 v178, s56, v145
	ds_read_b128 v[150:153], v162
	ds_read_b128 v[154:157], v162 offset:1024
	ds_read_b128 v[158:161], v162 offset:2048
	ds_read_b128 v[162:165], v162 offset:3072
	ds_read_b128 v[166:169], v178
	ds_read_b128 v[170:173], v178 offset:1024
	ds_read_b128 v[174:177], v178 offset:2048
	ds_read_b128 v[178:181], v178 offset:3072
	s_add_u32 s30, s30, 0x40000
	s_addc_u32 s31, s31, 0
	s_mov_b32 m0, s39
	v_lshl_add_u64 v[226:227], s[30:31], 0, v[134:135]
	ds_read_b128 v[182:185], v149 offset:32768
	ds_read_b128 v[192:195], v149 offset:33792
	ds_read_b128 v[196:199], v149 offset:34816
	ds_read_b128 v[200:203], v149 offset:35840
	ds_read_b128 v[204:207], v149 offset:36864
	ds_read_b128 v[208:211], v149 offset:37888
	ds_read_b128 v[212:215], v149 offset:38912
	ds_read_b128 v[216:219], v149 offset:39936
	global_load_lds_dwordx4 v[226:227], off
	v_lshl_add_u64 v[226:227], s[30:31], 0, v[130:131]
	s_mov_b32 m0, s40
	s_nop 0
	global_load_lds_dwordx4 v[226:227], off
	s_waitcnt vmcnt(8)
	s_waitcnt lgkmcnt(0)
	s_barrier
	s_setprio 1
	v_mfma_f32_16x16x32_bf16 v[124:127], v[150:153], v[182:185], v[124:127]
	v_mfma_f32_16x16x32_bf16 v[120:123], v[158:161], v[182:185], v[120:123]
	v_mfma_f32_16x16x32_bf16 v[108:111], v[150:153], v[196:199], v[108:111]
	v_mfma_f32_16x16x32_bf16 v[104:107], v[158:161], v[196:199], v[104:107]
	v_mfma_f32_16x16x32_bf16 v[92:95], v[150:153], v[204:207], v[92:95]
	v_mfma_f32_16x16x32_bf16 v[88:91], v[158:161], v[204:207], v[88:91]
	v_mfma_f32_16x16x32_bf16 v[76:79], v[150:153], v[212:215], v[76:79]
	v_mfma_f32_16x16x32_bf16 v[72:75], v[158:161], v[212:215], v[72:75]
	v_mfma_f32_16x16x32_bf16 v[124:127], v[154:157], v[192:195], v[124:127]
	v_mfma_f32_16x16x32_bf16 v[120:123], v[162:165], v[192:195], v[120:123]
	v_mfma_f32_16x16x32_bf16 v[108:111], v[154:157], v[200:203], v[108:111]
	v_mfma_f32_16x16x32_bf16 v[104:107], v[162:165], v[200:203], v[104:107]
	v_mfma_f32_16x16x32_bf16 v[92:95], v[154:157], v[208:211], v[92:95]
	v_mfma_f32_16x16x32_bf16 v[88:91], v[162:165], v[208:211], v[88:91]
	v_mfma_f32_16x16x32_bf16 v[76:79], v[154:157], v[216:219], v[76:79]
	v_mfma_f32_16x16x32_bf16 v[72:75], v[162:165], v[216:219], v[72:75]
	v_mfma_f32_16x16x32_bf16 v[116:119], v[166:169], v[182:185], v[116:119]
	v_mfma_f32_16x16x32_bf16 v[112:115], v[174:177], v[182:185], v[112:115]
	v_mfma_f32_16x16x32_bf16 v[100:103], v[166:169], v[196:199], v[100:103]
	v_mfma_f32_16x16x32_bf16 v[96:99], v[174:177], v[196:199], v[96:99]
	v_mfma_f32_16x16x32_bf16 v[84:87], v[166:169], v[204:207], v[84:87]
	v_mfma_f32_16x16x32_bf16 v[80:83], v[174:177], v[204:207], v[80:83]
	v_mfma_f32_16x16x32_bf16 v[68:71], v[166:169], v[212:215], v[68:71]
	v_mfma_f32_16x16x32_bf16 v[64:67], v[174:177], v[212:215], v[64:67]
	v_mfma_f32_16x16x32_bf16 v[116:119], v[170:173], v[192:195], v[116:119]
	v_mfma_f32_16x16x32_bf16 v[112:115], v[178:181], v[192:195], v[112:115]
	v_mfma_f32_16x16x32_bf16 v[100:103], v[170:173], v[200:203], v[100:103]
	v_mfma_f32_16x16x32_bf16 v[96:99], v[178:181], v[200:203], v[96:99]
	v_mfma_f32_16x16x32_bf16 v[84:87], v[170:173], v[208:211], v[84:87]
	v_mfma_f32_16x16x32_bf16 v[80:83], v[178:181], v[208:211], v[80:83]
	v_mfma_f32_16x16x32_bf16 v[68:71], v[170:173], v[216:219], v[68:71]
	v_mfma_f32_16x16x32_bf16 v[64:67], v[178:181], v[216:219], v[64:67]
	s_setprio 0
	s_barrier
; #define PG8_STAGE(bufoff, gbase, voff) do { _Pragma("unroll") for (int _i = 0; _i < 2; ++_i) \
;         __builtin_amdgcn_global_load_lds((const unsigned*)((const char*)(gbase) + (voff)[_i]), (PG8_LAS unsigned*)(lds + (bufoff) + ldsw + _i * 8192), 16, 0, 0); } while (0)
; #define PG8_LDA(dst, b, h) do { _Pragma("unroll") for (int m = 0; m < 4; ++m) _Pragma("unroll") for (int k = 0; k < 2; ++k) dst[m][k] = *(const PG8_LAS bf16x8*)(lds + PG8_SA(b, h) + aoff + m * 2048 + k * 1024); } while (0)
; #define PG8_MMA(ai, bj, At, Bt) do { __builtin_amdgcn_s_setprio(1); _Pragma("unroll") for (int m = 0; m < 4; ++m) _Pragma("unroll") for (int n = 0; n < 2; ++n) _Pragma("unroll") for (int k = 0; k < 2; ++k) \
;         acc[ai][bj][m][n] = __builtin_amdgcn_mfma_f32_16x16x32_bf16(Bt[n][k], At[m][k], acc[ai][bj][m][n], 0, 0, 0); __builtin_amdgcn_s_setprio(0); } while (0)
; #define PG8_WAIT_V(n) asm volatile("s_waitcnt vmcnt(" #n ")" ::: "memory")
; #define PG8_WAIT_L(n) asm volatile("s_waitcnt lgkmcnt(" #n ")" ::: "memory")
; #define PG8_BAR __builtin_amdgcn_s_barrier()
; #define PG8_SCHED __builtin_amdgcn_sched_barrier(0)
; template <class Epi, class Sched, bool ALIGN_EPI = false, bool SP2 = false>
; __device__ __forceinline__ void gemm_phase(PG8_LAS unsigned char* lds, const Gemm g, const Sched& S, const Epi& E) {
;     ...
;             PG8_LDA(At, 1, 1); PG8_STAGE(PG8_SB(1, 0), b3, voffB); PG8_STAGE(PG8_SB(1, 1), b3 + hstep, voffB); PG8_STAGE(PG8_SA(1, 0), a3, voffA);
;             PG8_WAIT_V(8); PG8_WAIT_L(0); PG8_BAR; PG8_MMA(1, 0, At, B0); PG8_MMA(1, 1, At, B1); PG8_BAR; PG8_SCHED;
;     ...
;         if constexpr (ALIGN_EPI) { if (wr == 0) PG8_BAR; }
;         if constexpr (!Epi::AFTER_DRAIN) { E(acc, cur, wr, wc, fr, fq); S.done(cur); }
	s_add_i32 s30, s55, s35
	v_lshl_add_u64 v[186:187], v[186:187], 0, s[4:5]
	s_mov_b32 m0, s30
	ds_read_b128 v[182:185], v149 offset:49152
	ds_read_b128 v[192:195], v149 offset:50176
	ds_read_b128 v[196:199], v149 offset:51200
	ds_read_b128 v[200:203], v149 offset:52224
	ds_read_b128 v[204:207], v149 offset:53248
	ds_read_b128 v[208:211], v149 offset:54272
	ds_read_b128 v[212:215], v149 offset:55296
	ds_read_b128 v[216:219], v149 offset:56320
	global_load_lds_dwordx4 v[186:187], off
	s_add_i32 m0, s30, 0x2000
	s_add_u32 s24, s24, 0x40080
	v_lshl_add_u64 v[186:187], v[220:221], 0, s[4:5]
	s_addc_u32 s25, s25, 0
	s_add_i32 s30, s56, s35
	global_load_lds_dwordx4 v[186:187], off
	v_lshl_add_u64 v[186:187], s[24:25], 0, v[132:133]
	s_mov_b32 m0, s30
	s_nop 0
	global_load_lds_dwordx4 v[186:187], off
	v_lshl_add_u64 v[186:187], s[24:25], 0, v[128:129]
	s_add_i32 m0, s30, 0x2000
	s_nop 0
	global_load_lds_dwordx4 v[186:187], off
	v_lshl_add_u64 v[186:187], v[222:223], 0, s[4:5]
	s_mov_b32 m0, s42
	s_nop 0
	global_load_lds_dwordx4 v[186:187], off
	v_lshl_add_u64 v[186:187], v[224:225], 0, s[4:5]
	s_mov_b32 m0, s43
	s_nop 0
	global_load_lds_dwordx4 v[186:187], off
	s_waitcnt vmcnt(8)
	s_waitcnt lgkmcnt(0)
	s_barrier
	s_setprio 1
	v_mfma_f32_16x16x32_bf16 v[60:63], v[150:153], v[182:185], v[60:63]
	v_mfma_f32_16x16x32_bf16 v[56:59], v[158:161], v[182:185], v[56:59]
	v_mfma_f32_16x16x32_bf16 v[44:47], v[150:153], v[196:199], v[44:47]
	v_mfma_f32_16x16x32_bf16 v[40:43], v[158:161], v[196:199], v[40:43]
	v_mfma_f32_16x16x32_bf16 v[28:31], v[150:153], v[204:207], v[28:31]
	v_mfma_f32_16x16x32_bf16 v[24:27], v[158:161], v[204:207], v[24:27]
	v_mfma_f32_16x16x32_bf16 v[12:15], v[150:153], v[212:215], v[12:15]
	v_mfma_f32_16x16x32_bf16 v[8:11], v[158:161], v[212:215], v[8:11]
	v_mfma_f32_16x16x32_bf16 v[60:63], v[154:157], v[192:195], v[60:63]
	v_mfma_f32_16x16x32_bf16 v[56:59], v[162:165], v[192:195], v[56:59]
	v_mfma_f32_16x16x32_bf16 v[44:47], v[154:157], v[200:203], v[44:47]
	v_mfma_f32_16x16x32_bf16 v[40:43], v[162:165], v[200:203], v[40:43]
	v_mfma_f32_16x16x32_bf16 v[28:31], v[154:157], v[208:211], v[28:31]
	v_mfma_f32_16x16x32_bf16 v[24:27], v[162:165], v[208:211], v[24:27]
	v_mfma_f32_16x16x32_bf16 v[12:15], v[154:157], v[216:219], v[12:15]
	v_mfma_f32_16x16x32_bf16 v[8:11], v[162:165], v[216:219], v[8:11]
	v_mfma_f32_16x16x32_bf16 v[52:55], v[166:169], v[182:185], v[52:55]
	v_mfma_f32_16x16x32_bf16 v[48:51], v[174:177], v[182:185], v[48:51]
	v_mfma_f32_16x16x32_bf16 v[36:39], v[166:169], v[196:199], v[36:39]
	v_mfma_f32_16x16x32_bf16 v[32:35], v[174:177], v[196:199], v[32:35]
	v_mfma_f32_16x16x32_bf16 v[20:23], v[166:169], v[204:207], v[20:23]
	v_mfma_f32_16x16x32_bf16 v[16:19], v[174:177], v[204:207], v[16:19]
	v_mfma_f32_16x16x32_bf16 v[4:7], v[166:169], v[212:215], v[4:7]
	v_mfma_f32_16x16x32_bf16 v[0:3], v[174:177], v[212:215], v[0:3]
	v_mfma_f32_16x16x32_bf16 v[52:55], v[170:173], v[192:195], v[52:55]
	v_mfma_f32_16x16x32_bf16 v[48:51], v[178:181], v[192:195], v[48:51]
	v_mfma_f32_16x16x32_bf16 v[36:39], v[170:173], v[200:203], v[36:39]
	v_mfma_f32_16x16x32_bf16 v[32:35], v[178:181], v[200:203], v[32:35]
	v_mfma_f32_16x16x32_bf16 v[20:23], v[170:173], v[208:211], v[20:23]
	v_mfma_f32_16x16x32_bf16 v[16:19], v[178:181], v[208:211], v[16:19]
	v_mfma_f32_16x16x32_bf16 v[4:7], v[170:173], v[216:219], v[4:7]
	v_mfma_f32_16x16x32_bf16 v[0:3], v[178:181], v[216:219], v[0:3]
	s_setprio 0
	s_barrier
	s_add_i32 s54, s54, 2
	s_add_u32 s22, s22, 0x100
	s_addc_u32 s23, s23, 0
	s_add_u32 s52, s52, 0x100
	s_addc_u32 s53, s53, 0
	s_cmp_gt_u32 s54, 13
	s_cbranch_scc0 .LBB0_192
	s_and_b64 vcc, exec, s[6:7]
	s_cbranch_vccz .LBB0_195
	s_barrier

; #define PG8_STAGE(bufoff, gbase, voff) do { _Pragma("unroll") for (int _i = 0; _i < 2; ++_i) \
;         __builtin_amdgcn_global_load_lds((const unsigned*)((const char*)(gbase) + (voff)[_i]), (PG8_LAS unsigned*)(lds + (bufoff) + ldsw + _i * 8192), 16, 0, 0); } while (0)
; #define PG8_LDA(dst, b, h) do { _Pragma("unroll") for (int m = 0; m < 4; ++m) _Pragma("unroll") for (int k = 0; k < 2; ++k) dst[m][k] = *(const PG8_LAS bf16x8*)(lds + PG8_SA(b, h) + aoff + m * 2048 + k * 1024); } while (0)
; #define PG8_LDB(dst, b, h) do { _Pragma("unroll") for (int n = 0; n < 2; ++n) _Pragma("unroll") for (int k = 0; k < 2; ++k) dst[n][k] = *(const PG8_LAS bf16x8*)(lds + PG8_SB(b, h) + boff + n * 2048 + k * 1024); } while (0)
; #define PG8_MMA(ai, bj, At, Bt) do { __builtin_amdgcn_s_setprio(1); _Pragma("unroll") for (int m = 0; m < 4; ++m) _Pragma("unroll") for (int n = 0; n < 2; ++n) _Pragma("unroll") for (int k = 0; k < 2; ++k) \
;         acc[ai][bj][m][n] = __builtin_amdgcn_mfma_f32_16x16x32_bf16(Bt[n][k], At[m][k], acc[ai][bj][m][n], 0, 0, 0); __builtin_amdgcn_s_setprio(0); } while (0)
; #define PG8_WAIT_V(n) asm volatile("s_waitcnt vmcnt(" #n ")" ::: "memory")
; #define PG8_WAIT_L(n) asm volatile("s_waitcnt lgkmcnt(" #n ")" ::: "memory")
; #define PG8_BAR __builtin_amdgcn_s_barrier()
; #define PG8_SCHED __builtin_amdgcn_sched_barrier(0)
; template <class Epi, class Sched, bool ALIGN_EPI = false, bool SP2 = false>
; __device__ __forceinline__ void gemm_phase(PG8_LAS unsigned char* lds, const Gemm g, const Sched& S, const Epi& E) {
;     ...
;             PG8_LDB(B0, 0, 0); PG8_LDB(B1, 0, 1); PG8_SCHED; PG8_LDA(At, 0, 0); PG8_STAGE(PG8_SA(1, 1), a1 + hstep, voffA);
;             PG8_WAIT_V(8); PG8_WAIT_L(0); PG8_BAR; PG8_MMA(0, 0, At, B0); PG8_MMA(0, 1, At, B1); PG8_BAR; PG8_SCHED;
;             PG8_LDA(At, 0, 1); PG8_STAGE(PG8_SB(0, 0), b2, voffB); PG8_STAGE(PG8_SB(0, 1), b2 + hstep, voffB); PG8_STAGE(PG8_SA(0, 0), a2, voffA);
;             PG8_WAIT_V(8); PG8_WAIT_L(0); PG8_BAR; PG8_MMA(1, 0, At, B0); PG8_MMA(1, 1, At, B1); PG8_BAR; PG8_SCHED;
.LBB0_274:
	ds_read_b128 v[128:131], v161
	ds_read_b128 v[132:135], v161 offset:1024
	ds_read_b128 v[152:155], v161 offset:2048
	ds_read_b128 v[166:169], v161 offset:3072
	ds_read_b128 v[170:173], v162
	ds_read_b128 v[174:177], v162 offset:1024
	ds_read_b128 v[178:181], v162 offset:2048
	ds_read_b128 v[182:185], v162 offset:3072
	s_add_u32 s34, s8, 0x100
	s_addc_u32 s35, s9, 0
	s_cmp_eq_u32 s60, 40
	s_cselect_b32 s39, s1, s35
	s_cselect_b32 s38, s0, s34
	s_cselect_b32 s37, s31, s59
	s_cselect_b32 s36, s30, s58
	v_lshl_add_u64 v[156:157], s[8:9], 0, v[144:145]
	s_add_i32 m0, s42, 0xc000
	ds_read_b128 v[192:195], v163
	ds_read_b128 v[196:199], v163 offset:1024
	ds_read_b128 v[200:203], v163 offset:2048
	ds_read_b128 v[204:207], v163 offset:3072
	ds_read_b128 v[208:211], v163 offset:4096
	ds_read_b128 v[212:215], v163 offset:5120
	ds_read_b128 v[216:219], v163 offset:6144
	ds_read_b128 v[220:223], v163 offset:7168
	global_load_lds_dwordx4 v[156:157], off
	v_lshl_add_u64 v[156:157], s[8:9], 0, v[146:147]
	s_add_i32 m0, s42, 0xe000
	s_nop 0
	global_load_lds_dwordx4 v[156:157], off
	s_waitcnt vmcnt(8)
	s_waitcnt lgkmcnt(0)
	s_barrier
	s_setprio 1
	v_mfma_f32_16x16x32_bf16 v[124:127], v[128:131], v[192:195], v[124:127]
	v_mfma_f32_16x16x32_bf16 v[120:123], v[152:155], v[192:195], v[120:123]
	v_mfma_f32_16x16x32_bf16 v[108:111], v[128:131], v[200:203], v[108:111]
	v_mfma_f32_16x16x32_bf16 v[104:107], v[152:155], v[200:203], v[104:107]
	v_mfma_f32_16x16x32_bf16 v[92:95], v[128:131], v[208:211], v[92:95]
	v_mfma_f32_16x16x32_bf16 v[88:91], v[152:155], v[208:211], v[88:91]
	v_mfma_f32_16x16x32_bf16 v[76:79], v[128:131], v[216:219], v[76:79]
	v_mfma_f32_16x16x32_bf16 v[72:75], v[152:155], v[216:219], v[72:75]
	v_mfma_f32_16x16x32_bf16 v[124:127], v[132:135], v[196:199], v[124:127]
	v_mfma_f32_16x16x32_bf16 v[120:123], v[166:169], v[196:199], v[120:123]
	v_mfma_f32_16x16x32_bf16 v[108:111], v[132:135], v[204:207], v[108:111]
	v_mfma_f32_16x16x32_bf16 v[104:107], v[166:169], v[204:207], v[104:107]
	v_mfma_f32_16x16x32_bf16 v[92:95], v[132:135], v[212:215], v[92:95]
	v_mfma_f32_16x16x32_bf16 v[88:91], v[166:169], v[212:215], v[88:91]
	v_mfma_f32_16x16x32_bf16 v[76:79], v[132:135], v[220:223], v[76:79]
	v_mfma_f32_16x16x32_bf16 v[72:75], v[166:169], v[220:223], v[72:75]
	v_mfma_f32_16x16x32_bf16 v[116:119], v[170:173], v[192:195], v[116:119]
	v_mfma_f32_16x16x32_bf16 v[112:115], v[178:181], v[192:195], v[112:115]
	v_mfma_f32_16x16x32_bf16 v[100:103], v[170:173], v[200:203], v[100:103]
	v_mfma_f32_16x16x32_bf16 v[96:99], v[178:181], v[200:203], v[96:99]
	v_mfma_f32_16x16x32_bf16 v[84:87], v[170:173], v[208:211], v[84:87]
	v_mfma_f32_16x16x32_bf16 v[80:83], v[178:181], v[208:211], v[80:83]
	v_mfma_f32_16x16x32_bf16 v[68:71], v[170:173], v[216:219], v[68:71]
	v_mfma_f32_16x16x32_bf16 v[64:67], v[178:181], v[216:219], v[64:67]
	v_mfma_f32_16x16x32_bf16 v[116:119], v[174:177], v[196:199], v[116:119]
	v_mfma_f32_16x16x32_bf16 v[112:115], v[182:185], v[196:199], v[112:115]
	v_mfma_f32_16x16x32_bf16 v[100:103], v[174:177], v[204:207], v[100:103]
	v_mfma_f32_16x16x32_bf16 v[96:99], v[182:185], v[204:207], v[96:99]
	v_mfma_f32_16x16x32_bf16 v[84:87], v[174:177], v[212:215], v[84:87]
	v_mfma_f32_16x16x32_bf16 v[80:83], v[182:185], v[212:215], v[80:83]
	v_mfma_f32_16x16x32_bf16 v[68:71], v[174:177], v[220:223], v[68:71]
	v_mfma_f32_16x16x32_bf16 v[64:67], v[182:185], v[220:223], v[64:67]
	s_setprio 0
	s_barrier
	s_add_i32 s8, s52, s41
	v_lshl_add_u64 v[156:157], s[36:37], 0, v[138:139]
	s_mov_b32 m0, s8
	ds_read_b128 v[192:195], v163 offset:16384
	ds_read_b128 v[196:199], v163 offset:17408
	ds_read_b128 v[200:203], v163 offset:18432
	ds_read_b128 v[204:207], v163 offset:19456
	ds_read_b128 v[208:211], v163 offset:20480
	ds_read_b128 v[212:215], v163 offset:21504
	ds_read_b128 v[216:219], v163 offset:22528
	ds_read_b128 v[220:223], v163 offset:23552
	global_load_lds_dwordx4 v[156:157], off
	s_add_i32 m0, s8, 0x2000
	s_add_u32 s8, s36, 0xb0000
	v_lshl_add_u64 v[186:187], s[36:37], 0, v[142:143]
	s_addc_u32 s9, s37, 0
	s_add_i32 s61, s53, s41
	global_load_lds_dwordx4 v[186:187], off
	v_lshl_add_u64 v[224:225], s[8:9], 0, v[138:139]
	s_mov_b32 m0, s61
	v_lshl_add_u64 v[226:227], s[38:39], 0, v[140:141]
	global_load_lds_dwordx4 v[224:225], off
	v_lshl_add_u64 v[224:225], s[8:9], 0, v[142:143]
	s_add_i32 m0, s61, 0x2000
	s_nop 0
	global_load_lds_dwordx4 v[224:225], off
	v_lshl_add_u64 v[224:225], s[38:39], 0, v[136:137]
	s_mov_b32 m0, s42
	s_nop 0
	global_load_lds_dwordx4 v[224:225], off
	s_mov_b32 m0, s43
	s_nop 0
	global_load_lds_dwordx4 v[226:227], off
	s_waitcnt vmcnt(8)
	s_waitcnt lgkmcnt(0)
	s_barrier
; #define PG8_STAGE(bufoff, gbase, voff) do { _Pragma("unroll") for (int _i = 0; _i < 2; ++_i) \
;         __builtin_amdgcn_global_load_lds((const unsigned*)((const char*)(gbase) + (voff)[_i]), (PG8_LAS unsigned*)(lds + (bufoff) + ldsw + _i * 8192), 16, 0, 0); } while (0)
; #define PG8_LDA(dst, b, h) do { _Pragma("unroll") for (int m = 0; m < 4; ++m) _Pragma("unroll") for (int k = 0; k < 2; ++k) dst[m][k] = *(const PG8_LAS bf16x8*)(lds + PG8_SA(b, h) + aoff + m * 2048 + k * 1024); } while (0)
; #define PG8_LDB(dst, b, h) do { _Pragma("unroll") for (int n = 0; n < 2; ++n) _Pragma("unroll") for (int k = 0; k < 2; ++k) dst[n][k] = *(const PG8_LAS bf16x8*)(lds + PG8_SB(b, h) + boff + n * 2048 + k * 1024); } while (0)
; #define PG8_MMA(ai, bj, At, Bt) do { __builtin_amdgcn_s_setprio(1); _Pragma("unroll") for (int m = 0; m < 4; ++m) _Pragma("unroll") for (int n = 0; n < 2; ++n) _Pragma("unroll") for (int k = 0; k < 2; ++k) \
;         acc[ai][bj][m][n] = __builtin_amdgcn_mfma_f32_16x16x32_bf16(Bt[n][k], At[m][k], acc[ai][bj][m][n], 0, 0, 0); __builtin_amdgcn_s_setprio(0); } while (0)
; #define PG8_WAIT_V(n) asm volatile("s_waitcnt vmcnt(" #n ")" ::: "memory")
; #define PG8_WAIT_L(n) asm volatile("s_waitcnt lgkmcnt(" #n ")" ::: "memory")
; #define PG8_BAR __builtin_amdgcn_s_barrier()
; #define PG8_SCHED __builtin_amdgcn_sched_barrier(0)
; template <class Epi, class Sched, bool ALIGN_EPI = false, bool SP2 = false>
; __device__ __forceinline__ void gemm_phase(PG8_LAS unsigned char* lds, const Gemm g, const Sched& S, const Epi& E) {
;     ...
;             PG8_WAIT_V(8); PG8_WAIT_L(0); PG8_BAR; PG8_MMA(0, 0, At, B0); PG8_MMA(0, 1, At, B1); PG8_BAR; PG8_SCHED;
;             PG8_LDA(At, 0, 1); PG8_STAGE(PG8_SB(0, 0), b2, voffB); PG8_STAGE(PG8_SB(0, 1), b2 + hstep, voffB); PG8_STAGE(PG8_SA(0, 0), a2, voffA);
;             PG8_WAIT_V(8); PG8_WAIT_L(0); PG8_BAR; PG8_MMA(1, 0, At, B0); PG8_MMA(1, 1, At, B1); PG8_BAR; PG8_SCHED;
;             PG8_LDB(B0, 1, 0); PG8_LDB(B1, 1, 1); PG8_SCHED; PG8_LDA(At, 1, 0); PG8_STAGE(PG8_SA(0, 1), a2 + hstep, voffA);
	s_setprio 1
	v_mfma_f32_16x16x32_bf16 v[60:63], v[128:131], v[192:195], v[60:63]
	v_mfma_f32_16x16x32_bf16 v[56:59], v[152:155], v[192:195], v[56:59]
	v_mfma_f32_16x16x32_bf16 v[44:47], v[128:131], v[200:203], v[44:47]
	v_mfma_f32_16x16x32_bf16 v[40:43], v[152:155], v[200:203], v[40:43]
	v_mfma_f32_16x16x32_bf16 v[28:31], v[128:131], v[208:211], v[28:31]
	v_mfma_f32_16x16x32_bf16 v[24:27], v[152:155], v[208:211], v[24:27]
	v_mfma_f32_16x16x32_bf16 v[12:15], v[128:131], v[216:219], v[12:15]
	v_mfma_f32_16x16x32_bf16 v[8:11], v[152:155], v[216:219], v[8:11]
	v_mfma_f32_16x16x32_bf16 v[60:63], v[132:135], v[196:199], v[60:63]
	v_mfma_f32_16x16x32_bf16 v[56:59], v[166:169], v[196:199], v[56:59]
	v_mfma_f32_16x16x32_bf16 v[44:47], v[132:135], v[204:207], v[44:47]
	v_mfma_f32_16x16x32_bf16 v[40:43], v[166:169], v[204:207], v[40:43]
	v_mfma_f32_16x16x32_bf16 v[28:31], v[132:135], v[212:215], v[28:31]
	v_mfma_f32_16x16x32_bf16 v[24:27], v[166:169], v[212:215], v[24:27]
	v_mfma_f32_16x16x32_bf16 v[12:15], v[132:135], v[220:223], v[12:15]
	v_mfma_f32_16x16x32_bf16 v[8:11], v[166:169], v[220:223], v[8:11]
	v_mfma_f32_16x16x32_bf16 v[52:55], v[170:173], v[192:195], v[52:55]
	v_mfma_f32_16x16x32_bf16 v[48:51], v[178:181], v[192:195], v[48:51]
	v_mfma_f32_16x16x32_bf16 v[36:39], v[170:173], v[200:203], v[36:39]
	v_mfma_f32_16x16x32_bf16 v[32:35], v[178:181], v[200:203], v[32:35]
	v_mfma_f32_16x16x32_bf16 v[20:23], v[170:173], v[208:211], v[20:23]
	v_mfma_f32_16x16x32_bf16 v[16:19], v[178:181], v[208:211], v[16:19]
	v_mfma_f32_16x16x32_bf16 v[4:7], v[170:173], v[216:219], v[4:7]
	v_mfma_f32_16x16x32_bf16 v[0:3], v[178:181], v[216:219], v[0:3]
	v_mfma_f32_16x16x32_bf16 v[52:55], v[174:177], v[196:199], v[52:55]
	v_mfma_f32_16x16x32_bf16 v[48:51], v[182:185], v[196:199], v[48:51]
	v_mfma_f32_16x16x32_bf16 v[36:39], v[174:177], v[204:207], v[36:39]
	v_mfma_f32_16x16x32_bf16 v[32:35], v[182:185], v[204:207], v[32:35]
	v_mfma_f32_16x16x32_bf16 v[20:23], v[174:177], v[212:215], v[20:23]
	v_mfma_f32_16x16x32_bf16 v[16:19], v[182:185], v[212:215], v[16:19]
	v_mfma_f32_16x16x32_bf16 v[4:7], v[174:177], v[220:223], v[4:7]
	v_mfma_f32_16x16x32_bf16 v[0:3], v[182:185], v[220:223], v[0:3]
	s_setprio 0
	s_barrier
	s_add_i32 s61, 0, 0x18000
	v_add_u32_e32 v165, s61, v159
	s_add_i32 s62, 0, 0x1c000
	ds_read_b128 v[128:131], v165
	ds_read_b128 v[132:135], v165 offset:1024
	ds_read_b128 v[152:155], v165 offset:2048
	ds_read_b128 v[166:169], v165 offset:3072
	v_add_u32_e32 v165, s62, v159
	ds_read_b128 v[170:173], v165
	ds_read_b128 v[174:177], v165 offset:1024
	ds_read_b128 v[178:181], v165 offset:2048
	ds_read_b128 v[182:185], v165 offset:3072
	s_add_u32 s8, s38, 0xb0000
	s_addc_u32 s9, s39, 0
	s_mov_b32 m0, s44
	v_lshl_add_u64 v[228:229], s[8:9], 0, v[136:137]
	ds_read_b128 v[192:195], v163 offset:32768
	ds_read_b128 v[196:199], v163 offset:33792
	ds_read_b128 v[200:203], v163 offset:34816
	ds_read_b128 v[204:207], v163 offset:35840
	ds_read_b128 v[208:211], v163 offset:36864
	ds_read_b128 v[212:215], v163 offset:37888
	ds_read_b128 v[216:219], v163 offset:38912
	ds_read_b128 v[220:223], v163 offset:39936
	global_load_lds_dwordx4 v[228:229], off
	v_lshl_add_u64 v[228:229], s[8:9], 0, v[140:141]
	s_mov_b32 m0, s45
	s_nop 0
	global_load_lds_dwordx4 v[228:229], off
	s_waitcnt vmcnt(8)
	s_waitcnt lgkmcnt(0)
	s_barrier
	s_setprio 1
	v_mfma_f32_16x16x32_bf16 v[124:127], v[128:131], v[192:195], v[124:127]
	v_mfma_f32_16x16x32_bf16 v[120:123], v[152:155], v[192:195], v[120:123]
	v_mfma_f32_16x16x32_bf16 v[108:111], v[128:131], v[200:203], v[108:111]
	v_mfma_f32_16x16x32_bf16 v[104:107], v[152:155], v[200:203], v[104:107]
	v_mfma_f32_16x16x32_bf16 v[92:95], v[128:131], v[208:211], v[92:95]
	v_mfma_f32_16x16x32_bf16 v[88:91], v[152:155], v[208:211], v[88:91]
	v_mfma_f32_16x16x32_bf16 v[76:79], v[128:131], v[216:219], v[76:79]
	v_mfma_f32_16x16x32_bf16 v[72:75], v[152:155], v[216:219], v[72:75]
	v_mfma_f32_16x16x32_bf16 v[124:127], v[132:135], v[196:199], v[124:127]
	v_mfma_f32_16x16x32_bf16 v[120:123], v[166:169], v[196:199], v[120:123]
	v_mfma_f32_16x16x32_bf16 v[108:111], v[132:135], v[204:207], v[108:111]
	v_mfma_f32_16x16x32_bf16 v[104:107], v[166:169], v[204:207], v[104:107]
	v_mfma_f32_16x16x32_bf16 v[92:95], v[132:135], v[212:215], v[92:95]
	v_mfma_f32_16x16x32_bf16 v[88:91], v[166:169], v[212:215], v[88:91]
	v_mfma_f32_16x16x32_bf16 v[76:79], v[132:135], v[220:223], v[76:79]
	v_mfma_f32_16x16x32_bf16 v[72:75], v[166:169], v[220:223], v[72:75]
	v_mfma_f32_16x16x32_bf16 v[116:119], v[170:173], v[192:195], v[116:119]
	v_mfma_f32_16x16x32_bf16 v[112:115], v[178:181], v[192:195], v[112:115]
	v_mfma_f32_16x16x32_bf16 v[100:103], v[170:173], v[200:203], v[100:103]
	v_mfma_f32_16x16x32_bf16 v[96:99], v[178:181], v[200:203], v[96:99]
	v_mfma_f32_16x16x32_bf16 v[84:87], v[170:173], v[208:211], v[84:87]
	v_mfma_f32_16x16x32_bf16 v[80:83], v[178:181], v[208:211], v[80:83]
	v_mfma_f32_16x16x32_bf16 v[68:71], v[170:173], v[216:219], v[68:71]
	v_mfma_f32_16x16x32_bf16 v[64:67], v[178:181], v[216:219], v[64:67]
	v_mfma_f32_16x16x32_bf16 v[116:119], v[174:177], v[196:199], v[116:119]
	v_mfma_f32_16x16x32_bf16 v[112:115], v[182:185], v[196:199], v[112:115]
	v_mfma_f32_16x16x32_bf16 v[100:103], v[174:177], v[204:207], v[100:103]
	v_mfma_f32_16x16x32_bf16 v[96:99], v[182:185], v[204:207], v[96:99]
	v_mfma_f32_16x16x32_bf16 v[84:87], v[174:177], v[212:215], v[84:87]
	v_mfma_f32_16x16x32_bf16 v[80:83], v[182:185], v[212:215], v[80:83]
	v_mfma_f32_16x16x32_bf16 v[68:71], v[174:177], v[220:223], v[68:71]
	v_mfma_f32_16x16x32_bf16 v[64:67], v[182:185], v[220:223], v[64:67]
	s_setprio 0
	s_barrier
; #define PG8_STAGE(bufoff, gbase, voff) do { _Pragma("unroll") for (int _i = 0; _i < 2; ++_i) \
;         __builtin_amdgcn_global_load_lds((const unsigned*)((const char*)(gbase) + (voff)[_i]), (PG8_LAS unsigned*)(lds + (bufoff) + ldsw + _i * 8192), 16, 0, 0); } while (0)
; #define PG8_LDA(dst, b, h) do { _Pragma("unroll") for (int m = 0; m < 4; ++m) _Pragma("unroll") for (int k = 0; k < 2; ++k) dst[m][k] = *(const PG8_LAS bf16x8*)(lds + PG8_SA(b, h) + aoff + m * 2048 + k * 1024); } while (0)
; #define PG8_LDB(dst, b, h) do { _Pragma("unroll") for (int n = 0; n < 2; ++n) _Pragma("unroll") for (int k = 0; k < 2; ++k) dst[n][k] = *(const PG8_LAS bf16x8*)(lds + PG8_SB(b, h) + boff + n * 2048 + k * 1024); } while (0)
; #define PG8_MMA(ai, bj, At, Bt) do { __builtin_amdgcn_s_setprio(1); _Pragma("unroll") for (int m = 0; m < 4; ++m) _Pragma("unroll") for (int n = 0; n < 2; ++n) _Pragma("unroll") for (int k = 0; k < 2; ++k) \
;         acc[ai][bj][m][n] = __builtin_amdgcn_mfma_f32_16x16x32_bf16(Bt[n][k], At[m][k], acc[ai][bj][m][n], 0, 0, 0); __builtin_amdgcn_s_setprio(0); } while (0)
; #define PG8_WAIT_V(n) asm volatile("s_waitcnt vmcnt(" #n ")" ::: "memory")
; #define PG8_WAIT_L(n) asm volatile("s_waitcnt lgkmcnt(" #n ")" ::: "memory")
; #define PG8_BAR __builtin_amdgcn_s_barrier()
; #define PG8_SCHED __builtin_amdgcn_sched_barrier(0)
; template <class Epi, class Sched, bool ALIGN_EPI = false, bool SP2 = false>
; __device__ __forceinline__ void gemm_phase(PG8_LAS unsigned char* lds, const Gemm g, const Sched& S, const Epi& E) {
;     ...
;         for (int t = 0; t < nt; t += 2) {
;             const bool last = (t == nt - 2);
;             const char* a1 = cA + (size_t)(t + 1) * kstep;
;             const char* a2 = last ? nA : cA + (size_t)(t + 2) * kstep; const char* b2 = last ? nB : cB + (size_t)(t + 2) * kstep;
;     ...
;             PG8_LDB(B0, 1, 0); PG8_LDB(B1, 1, 1); PG8_SCHED; PG8_LDA(At, 1, 0); PG8_STAGE(PG8_SA(0, 1), a2 + hstep, voffA);
;             PG8_WAIT_V(8); PG8_WAIT_L(0); PG8_BAR; PG8_MMA(0, 0, At, B0); PG8_MMA(0, 1, At, B1); PG8_BAR; PG8_SCHED;
;             PG8_LDA(At, 1, 1); PG8_STAGE(PG8_SB(1, 0), b3, voffB); PG8_STAGE(PG8_SB(1, 1), b3 + hstep, voffB); PG8_STAGE(PG8_SA(1, 0), a3, voffA);
;             PG8_WAIT_V(8); PG8_WAIT_L(0); PG8_BAR; PG8_MMA(1, 0, At, B0); PG8_MMA(1, 1, At, B1); PG8_BAR; PG8_SCHED;
	s_add_i32 s8, s61, s41
	v_lshl_add_u64 v[156:157], v[156:157], 0, s[14:15]
	s_mov_b32 m0, s8
	ds_read_b128 v[192:195], v163 offset:49152
	ds_read_b128 v[196:199], v163 offset:50176
	ds_read_b128 v[200:203], v163 offset:51200
	ds_read_b128 v[204:207], v163 offset:52224
	ds_read_b128 v[208:211], v163 offset:53248
	ds_read_b128 v[212:215], v163 offset:54272
	ds_read_b128 v[216:219], v163 offset:55296
	ds_read_b128 v[220:223], v163 offset:56320
	global_load_lds_dwordx4 v[156:157], off
	s_add_i32 m0, s8, 0x2000
	s_add_u32 s8, s36, 0xb0080
	v_lshl_add_u64 v[156:157], v[186:187], 0, s[14:15]
	s_addc_u32 s9, s37, 0
	s_add_i32 s36, s62, s41
	global_load_lds_dwordx4 v[156:157], off
	v_lshl_add_u64 v[156:157], s[8:9], 0, v[138:139]
	s_mov_b32 m0, s36
	s_nop 0
	global_load_lds_dwordx4 v[156:157], off
	v_lshl_add_u64 v[156:157], s[8:9], 0, v[142:143]
	s_add_i32 m0, s36, 0x2000
	s_nop 0
	global_load_lds_dwordx4 v[156:157], off
	v_lshl_add_u64 v[156:157], v[224:225], 0, s[14:15]
	s_mov_b32 m0, s47
	s_nop 0
	global_load_lds_dwordx4 v[156:157], off
	v_lshl_add_u64 v[156:157], v[226:227], 0, s[14:15]
	s_mov_b32 m0, s48
	s_nop 0
	global_load_lds_dwordx4 v[156:157], off
	s_waitcnt vmcnt(8)
	s_waitcnt lgkmcnt(0)
	s_barrier
	s_setprio 1
	v_mfma_f32_16x16x32_bf16 v[60:63], v[128:131], v[192:195], v[60:63]
	v_mfma_f32_16x16x32_bf16 v[56:59], v[152:155], v[192:195], v[56:59]
	v_mfma_f32_16x16x32_bf16 v[44:47], v[128:131], v[200:203], v[44:47]
	v_mfma_f32_16x16x32_bf16 v[40:43], v[152:155], v[200:203], v[40:43]
	v_mfma_f32_16x16x32_bf16 v[28:31], v[128:131], v[208:211], v[28:31]
	v_mfma_f32_16x16x32_bf16 v[24:27], v[152:155], v[208:211], v[24:27]
	v_mfma_f32_16x16x32_bf16 v[12:15], v[128:131], v[216:219], v[12:15]
	v_mfma_f32_16x16x32_bf16 v[8:11], v[152:155], v[216:219], v[8:11]
	v_mfma_f32_16x16x32_bf16 v[60:63], v[132:135], v[196:199], v[60:63]
	v_mfma_f32_16x16x32_bf16 v[56:59], v[166:169], v[196:199], v[56:59]
	v_mfma_f32_16x16x32_bf16 v[44:47], v[132:135], v[204:207], v[44:47]
	v_mfma_f32_16x16x32_bf16 v[40:43], v[166:169], v[204:207], v[40:43]
	v_mfma_f32_16x16x32_bf16 v[28:31], v[132:135], v[212:215], v[28:31]
	v_mfma_f32_16x16x32_bf16 v[24:27], v[166:169], v[212:215], v[24:27]
	v_mfma_f32_16x16x32_bf16 v[12:15], v[132:135], v[220:223], v[12:15]
	v_mfma_f32_16x16x32_bf16 v[8:11], v[166:169], v[220:223], v[8:11]
	v_mfma_f32_16x16x32_bf16 v[52:55], v[170:173], v[192:195], v[52:55]
	v_mfma_f32_16x16x32_bf16 v[48:51], v[178:181], v[192:195], v[48:51]
	v_mfma_f32_16x16x32_bf16 v[36:39], v[170:173], v[200:203], v[36:39]
	v_mfma_f32_16x16x32_bf16 v[32:35], v[178:181], v[200:203], v[32:35]
	v_mfma_f32_16x16x32_bf16 v[20:23], v[170:173], v[208:211], v[20:23]
	v_mfma_f32_16x16x32_bf16 v[16:19], v[178:181], v[208:211], v[16:19]
	v_mfma_f32_16x16x32_bf16 v[4:7], v[170:173], v[216:219], v[4:7]
	v_mfma_f32_16x16x32_bf16 v[0:3], v[178:181], v[216:219], v[0:3]
	v_mfma_f32_16x16x32_bf16 v[52:55], v[174:177], v[196:199], v[52:55]
	v_mfma_f32_16x16x32_bf16 v[48:51], v[182:185], v[196:199], v[48:51]
	v_mfma_f32_16x16x32_bf16 v[36:39], v[174:177], v[204:207], v[36:39]
	v_mfma_f32_16x16x32_bf16 v[32:35], v[182:185], v[204:207], v[32:35]
	v_mfma_f32_16x16x32_bf16 v[20:23], v[174:177], v[212:215], v[20:23]
	v_mfma_f32_16x16x32_bf16 v[16:19], v[182:185], v[212:215], v[16:19]
	v_mfma_f32_16x16x32_bf16 v[4:7], v[174:177], v[220:223], v[4:7]
	v_mfma_f32_16x16x32_bf16 v[0:3], v[182:185], v[220:223], v[0:3]
	s_setprio 0
	s_barrier
	s_add_i32 s60, s60, 2
	s_add_u32 s58, s58, 0x100
	s_addc_u32 s59, s59, 0
	s_cmp_gt_u32 s60, 41
	s_mov_b64 s[8:9], s[34:35]
	s_cbranch_scc0 .LBB0_274
	s_and_b64 vcc, exec, s[16:17]
	s_cbranch_vccz .LBB0_277
	s_barrier

; #define PG8_STAGE(bufoff, gbase, voff) do { _Pragma("unroll") for (int _i = 0; _i < 2; ++_i) \
;         __builtin_amdgcn_global_load_lds((const unsigned*)((const char*)(gbase) + (voff)[_i]), (PG8_LAS unsigned*)(lds + (bufoff) + ldsw + _i * 8192), 16, 0, 0); } while (0)
; #define PG8_LDA(dst, b, h) do { _Pragma("unroll") for (int m = 0; m < 4; ++m) _Pragma("unroll") for (int k = 0; k < 2; ++k) dst[m][k] = *(const PG8_LAS bf16x8*)(lds + PG8_SA(b, h) + aoff + m * 2048 + k * 1024); } while (0)
; #define PG8_LDB(dst, b, h) do { _Pragma("unroll") for (int n = 0; n < 2; ++n) _Pragma("unroll") for (int k = 0; k < 2; ++k) dst[n][k] = *(const PG8_LAS bf16x8*)(lds + PG8_SB(b, h) + boff + n * 2048 + k * 1024); } while (0)
; #define PG8_MMA(ai, bj, At, Bt) do { __builtin_amdgcn_s_setprio(1); _Pragma("unroll") for (int m = 0; m < 4; ++m) _Pragma("unroll") for (int n = 0; n < 2; ++n) _Pragma("unroll") for (int k = 0; k < 2; ++k) \
;         acc[ai][bj][m][n] = __builtin_amdgcn_mfma_f32_16x16x32_bf16(Bt[n][k], At[m][k], acc[ai][bj][m][n], 0, 0, 0); __builtin_amdgcn_s_setprio(0); } while (0)
; #define PG8_WAIT_V(n) asm volatile("s_waitcnt vmcnt(" #n ")" ::: "memory")
; #define PG8_WAIT_L(n) asm volatile("s_waitcnt lgkmcnt(" #n ")" ::: "memory")
; #define PG8_BAR __builtin_amdgcn_s_barrier()
; #define PG8_SCHED __builtin_amdgcn_sched_barrier(0)
; template <class Epi, class Sched, bool ALIGN_EPI = false, bool SP2 = false>
; __device__ __forceinline__ void gemm_phase(PG8_LAS unsigned char* lds, const Gemm g, const Sched& S, const Epi& E) {
;     ...
;             PG8_LDB(B0, 0, 0); PG8_LDB(B1, 0, 1); PG8_SCHED; PG8_LDA(At, 0, 0); PG8_STAGE(PG8_SA(1, 1), a1 + hstep, voffA);
;             PG8_WAIT_V(8); PG8_WAIT_L(0); PG8_BAR; PG8_MMA(0, 0, At, B0); PG8_MMA(0, 1, At, B1); PG8_BAR; PG8_SCHED;
;             PG8_LDA(At, 0, 1); PG8_STAGE(PG8_SB(0, 0), b2, voffB); PG8_STAGE(PG8_SB(0, 1), b2 + hstep, voffB); PG8_STAGE(PG8_SA(0, 0), a2, voffA);
;             PG8_WAIT_V(8); PG8_WAIT_L(0); PG8_BAR; PG8_MMA(1, 0, At, B0); PG8_MMA(1, 1, At, B1); PG8_BAR; PG8_SCHED;
.LBB0_374:
	ds_read_b128 v[128:131], v171
	ds_read_b128 v[132:135], v171 offset:1024
	ds_read_b128 v[136:139], v171 offset:2048
	ds_read_b128 v[140:143], v171 offset:3072
	ds_read_b128 v[164:167], v172
	ds_read_b128 v[178:181], v172 offset:1024
	ds_read_b128 v[182:185], v172 offset:2048
	ds_read_b128 v[192:195], v172 offset:3072
	s_add_u32 s38, s2, 0xfffc0080
	s_addc_u32 s39, s3, -1
	s_cmp_eq_u32 s60, 12
	s_cselect_b32 s41, s1, s39
	s_cselect_b32 s40, s25, s38
	s_cselect_b32 s39, s29, s59
	s_cselect_b32 s38, s31, s58
	v_lshl_add_u64 v[168:169], s[2:3], 0, v[156:157]
	s_add_i32 m0, s44, 0xc000
	ds_read_b128 v[196:199], v173
	ds_read_b128 v[200:203], v173 offset:1024
	ds_read_b128 v[204:207], v173 offset:2048
	ds_read_b128 v[208:211], v173 offset:3072
	ds_read_b128 v[212:215], v173 offset:4096
	ds_read_b128 v[216:219], v173 offset:5120
	ds_read_b128 v[220:223], v173 offset:6144
	ds_read_b128 v[224:227], v173 offset:7168
	global_load_lds_dwordx4 v[168:169], off
	v_lshl_add_u64 v[168:169], s[2:3], 0, v[158:159]
	s_add_i32 m0, s44, 0xe000
	s_nop 0
	global_load_lds_dwordx4 v[168:169], off
	s_waitcnt vmcnt(8)
	s_waitcnt lgkmcnt(0)
	s_barrier
	s_setprio 1
	v_mfma_f32_16x16x32_bf16 v[124:127], v[128:131], v[196:199], v[124:127]
	v_mfma_f32_16x16x32_bf16 v[120:123], v[136:139], v[196:199], v[120:123]
	v_mfma_f32_16x16x32_bf16 v[108:111], v[128:131], v[204:207], v[108:111]
	v_mfma_f32_16x16x32_bf16 v[104:107], v[136:139], v[204:207], v[104:107]
	v_mfma_f32_16x16x32_bf16 v[92:95], v[128:131], v[212:215], v[92:95]
	v_mfma_f32_16x16x32_bf16 v[88:91], v[136:139], v[212:215], v[88:91]
	v_mfma_f32_16x16x32_bf16 v[76:79], v[128:131], v[220:223], v[76:79]
	v_mfma_f32_16x16x32_bf16 v[72:75], v[136:139], v[220:223], v[72:75]
	v_mfma_f32_16x16x32_bf16 v[124:127], v[132:135], v[200:203], v[124:127]
	v_mfma_f32_16x16x32_bf16 v[120:123], v[140:143], v[200:203], v[120:123]
	v_mfma_f32_16x16x32_bf16 v[108:111], v[132:135], v[208:211], v[108:111]
	v_mfma_f32_16x16x32_bf16 v[104:107], v[140:143], v[208:211], v[104:107]
	v_mfma_f32_16x16x32_bf16 v[92:95], v[132:135], v[216:219], v[92:95]
	v_mfma_f32_16x16x32_bf16 v[88:91], v[140:143], v[216:219], v[88:91]
	v_mfma_f32_16x16x32_bf16 v[76:79], v[132:135], v[224:227], v[76:79]
	v_mfma_f32_16x16x32_bf16 v[72:75], v[140:143], v[224:227], v[72:75]
	v_mfma_f32_16x16x32_bf16 v[116:119], v[164:167], v[196:199], v[116:119]
	v_mfma_f32_16x16x32_bf16 v[112:115], v[182:185], v[196:199], v[112:115]
	v_mfma_f32_16x16x32_bf16 v[100:103], v[164:167], v[204:207], v[100:103]
	v_mfma_f32_16x16x32_bf16 v[96:99], v[182:185], v[204:207], v[96:99]
	v_mfma_f32_16x16x32_bf16 v[84:87], v[164:167], v[212:215], v[84:87]
	v_mfma_f32_16x16x32_bf16 v[80:83], v[182:185], v[212:215], v[80:83]
	v_mfma_f32_16x16x32_bf16 v[68:71], v[164:167], v[220:223], v[68:71]
	v_mfma_f32_16x16x32_bf16 v[64:67], v[182:185], v[220:223], v[64:67]
	v_mfma_f32_16x16x32_bf16 v[116:119], v[178:181], v[200:203], v[116:119]
	v_mfma_f32_16x16x32_bf16 v[112:115], v[192:195], v[200:203], v[112:115]
	v_mfma_f32_16x16x32_bf16 v[100:103], v[178:181], v[208:211], v[100:103]
	v_mfma_f32_16x16x32_bf16 v[96:99], v[192:195], v[208:211], v[96:99]
	v_mfma_f32_16x16x32_bf16 v[84:87], v[178:181], v[216:219], v[84:87]
	v_mfma_f32_16x16x32_bf16 v[80:83], v[192:195], v[216:219], v[80:83]
	v_mfma_f32_16x16x32_bf16 v[68:71], v[178:181], v[224:227], v[68:71]
	v_mfma_f32_16x16x32_bf16 v[64:67], v[192:195], v[224:227], v[64:67]
	s_setprio 0
	s_barrier
	s_add_i32 s61, s52, s33
	v_lshl_add_u64 v[168:169], s[38:39], 0, v[148:149]
	s_mov_b32 m0, s61
	ds_read_b128 v[196:199], v173 offset:16384
	ds_read_b128 v[200:203], v173 offset:17408
	ds_read_b128 v[204:207], v173 offset:18432
	ds_read_b128 v[208:211], v173 offset:19456
	ds_read_b128 v[212:215], v173 offset:20480
	ds_read_b128 v[216:219], v173 offset:21504
	ds_read_b128 v[220:223], v173 offset:22528
	ds_read_b128 v[224:227], v173 offset:23552
	global_load_lds_dwordx4 v[168:169], off
	s_add_i32 m0, s61, 0x2000
	s_add_u32 s62, s38, 0x40000
	v_lshl_add_u64 v[186:187], s[38:39], 0, v[144:145]
	s_addc_u32 s63, s39, 0
	s_add_i32 s61, s53, s33
	global_load_lds_dwordx4 v[186:187], off
	v_lshl_add_u64 v[228:229], s[62:63], 0, v[148:149]
	s_mov_b32 m0, s61
	v_lshl_add_u64 v[230:231], s[40:41], 0, v[146:147]
	global_load_lds_dwordx4 v[228:229], off
	v_lshl_add_u64 v[228:229], s[62:63], 0, v[144:145]
	s_add_i32 m0, s61, 0x2000
	s_nop 0
	global_load_lds_dwordx4 v[228:229], off
	v_lshl_add_u64 v[228:229], s[40:41], 0, v[150:151]
	s_mov_b32 m0, s44
	s_nop 0
	global_load_lds_dwordx4 v[228:229], off
	s_mov_b32 m0, s45
	s_nop 0
	global_load_lds_dwordx4 v[230:231], off
	s_waitcnt vmcnt(8)
	s_waitcnt lgkmcnt(0)
	s_barrier
; #define PG8_STAGE(bufoff, gbase, voff) do { _Pragma("unroll") for (int _i = 0; _i < 2; ++_i) \
;         __builtin_amdgcn_global_load_lds((const unsigned*)((const char*)(gbase) + (voff)[_i]), (PG8_LAS unsigned*)(lds + (bufoff) + ldsw + _i * 8192), 16, 0, 0); } while (0)
; #define PG8_LDA(dst, b, h) do { _Pragma("unroll") for (int m = 0; m < 4; ++m) _Pragma("unroll") for (int k = 0; k < 2; ++k) dst[m][k] = *(const PG8_LAS bf16x8*)(lds + PG8_SA(b, h) + aoff + m * 2048 + k * 1024); } while (0)
; #define PG8_LDB(dst, b, h) do { _Pragma("unroll") for (int n = 0; n < 2; ++n) _Pragma("unroll") for (int k = 0; k < 2; ++k) dst[n][k] = *(const PG8_LAS bf16x8*)(lds + PG8_SB(b, h) + boff + n * 2048 + k * 1024); } while (0)
; #define PG8_MMA(ai, bj, At, Bt) do { __builtin_amdgcn_s_setprio(1); _Pragma("unroll") for (int m = 0; m < 4; ++m) _Pragma("unroll") for (int n = 0; n < 2; ++n) _Pragma("unroll") for (int k = 0; k < 2; ++k) \
;         acc[ai][bj][m][n] = __builtin_amdgcn_mfma_f32_16x16x32_bf16(Bt[n][k], At[m][k], acc[ai][bj][m][n], 0, 0, 0); __builtin_amdgcn_s_setprio(0); } while (0)
; #define PG8_WAIT_V(n) asm volatile("s_waitcnt vmcnt(" #n ")" ::: "memory")
; #define PG8_WAIT_L(n) asm volatile("s_waitcnt lgkmcnt(" #n ")" ::: "memory")
; #define PG8_BAR __builtin_amdgcn_s_barrier()
; #define PG8_SCHED __builtin_amdgcn_sched_barrier(0)
; template <class Epi, class Sched, bool ALIGN_EPI = false, bool SP2 = false>
; __device__ __forceinline__ void gemm_phase(PG8_LAS unsigned char* lds, const Gemm g, const Sched& S, const Epi& E) {
;     ...
;             PG8_WAIT_V(8); PG8_WAIT_L(0); PG8_BAR; PG8_MMA(1, 0, At, B0); PG8_MMA(1, 1, At, B1); PG8_BAR; PG8_SCHED;
;             PG8_LDB(B0, 1, 0); PG8_LDB(B1, 1, 1); PG8_SCHED; PG8_LDA(At, 1, 0); PG8_STAGE(PG8_SA(0, 1), a2 + hstep, voffA);
;             PG8_WAIT_V(8); PG8_WAIT_L(0); PG8_BAR; PG8_MMA(0, 0, At, B0); PG8_MMA(0, 1, At, B1); PG8_BAR; PG8_SCHED;
;             PG8_LDA(At, 1, 1); PG8_STAGE(PG8_SB(1, 0), b3, voffB); PG8_STAGE(PG8_SB(1, 1), b3 + hstep, voffB); PG8_STAGE(PG8_SA(1, 0), a3, voffA);
	s_setprio 1
	v_mfma_f32_16x16x32_bf16 v[60:63], v[128:131], v[196:199], v[60:63]
	v_mfma_f32_16x16x32_bf16 v[56:59], v[136:139], v[196:199], v[56:59]
	v_mfma_f32_16x16x32_bf16 v[44:47], v[128:131], v[204:207], v[44:47]
	v_mfma_f32_16x16x32_bf16 v[40:43], v[136:139], v[204:207], v[40:43]
	v_mfma_f32_16x16x32_bf16 v[28:31], v[128:131], v[212:215], v[28:31]
	v_mfma_f32_16x16x32_bf16 v[24:27], v[136:139], v[212:215], v[24:27]
	v_mfma_f32_16x16x32_bf16 v[12:15], v[128:131], v[220:223], v[12:15]
	v_mfma_f32_16x16x32_bf16 v[8:11], v[136:139], v[220:223], v[8:11]
	v_mfma_f32_16x16x32_bf16 v[60:63], v[132:135], v[200:203], v[60:63]
	v_mfma_f32_16x16x32_bf16 v[56:59], v[140:143], v[200:203], v[56:59]
	v_mfma_f32_16x16x32_bf16 v[44:47], v[132:135], v[208:211], v[44:47]
	v_mfma_f32_16x16x32_bf16 v[40:43], v[140:143], v[208:211], v[40:43]
	v_mfma_f32_16x16x32_bf16 v[28:31], v[132:135], v[216:219], v[28:31]
	v_mfma_f32_16x16x32_bf16 v[24:27], v[140:143], v[216:219], v[24:27]
	v_mfma_f32_16x16x32_bf16 v[12:15], v[132:135], v[224:227], v[12:15]
	v_mfma_f32_16x16x32_bf16 v[8:11], v[140:143], v[224:227], v[8:11]
	v_mfma_f32_16x16x32_bf16 v[52:55], v[164:167], v[196:199], v[52:55]
	v_mfma_f32_16x16x32_bf16 v[48:51], v[182:185], v[196:199], v[48:51]
	v_mfma_f32_16x16x32_bf16 v[36:39], v[164:167], v[204:207], v[36:39]
	v_mfma_f32_16x16x32_bf16 v[32:35], v[182:185], v[204:207], v[32:35]
	v_mfma_f32_16x16x32_bf16 v[20:23], v[164:167], v[212:215], v[20:23]
	v_mfma_f32_16x16x32_bf16 v[16:19], v[182:185], v[212:215], v[16:19]
	v_mfma_f32_16x16x32_bf16 v[4:7], v[164:167], v[220:223], v[4:7]
	v_mfma_f32_16x16x32_bf16 v[0:3], v[182:185], v[220:223], v[0:3]
	v_mfma_f32_16x16x32_bf16 v[52:55], v[178:181], v[200:203], v[52:55]
	v_mfma_f32_16x16x32_bf16 v[48:51], v[192:195], v[200:203], v[48:51]
	v_mfma_f32_16x16x32_bf16 v[36:39], v[178:181], v[208:211], v[36:39]
	v_mfma_f32_16x16x32_bf16 v[32:35], v[192:195], v[208:211], v[32:35]
	v_mfma_f32_16x16x32_bf16 v[20:23], v[178:181], v[216:219], v[20:23]
	v_mfma_f32_16x16x32_bf16 v[16:19], v[192:195], v[216:219], v[16:19]
	v_mfma_f32_16x16x32_bf16 v[4:7], v[178:181], v[224:227], v[4:7]
	v_mfma_f32_16x16x32_bf16 v[0:3], v[192:195], v[224:227], v[0:3]
	s_setprio 0
	s_barrier
	s_add_i32 s61, 0, 0x18000
	s_add_i32 s62, 0, 0x1c000
	v_add_u32_e32 v140, s61, v170
	v_add_u32_e32 v152, s62, v170
	ds_read_b128 v[128:131], v140
	ds_read_b128 v[132:135], v140 offset:1024
	ds_read_b128 v[136:139], v140 offset:2048
	ds_read_b128 v[140:143], v140 offset:3072
	ds_read_b128 v[164:167], v152
	ds_read_b128 v[178:181], v152 offset:1024
	ds_read_b128 v[182:185], v152 offset:2048
	ds_read_b128 v[192:195], v152 offset:3072
	s_add_u32 s40, s40, 0x40000
	s_addc_u32 s41, s41, 0
	s_mov_b32 m0, s46
	v_lshl_add_u64 v[232:233], s[40:41], 0, v[150:151]
	ds_read_b128 v[196:199], v173 offset:32768
	ds_read_b128 v[200:203], v173 offset:33792
	ds_read_b128 v[204:207], v173 offset:34816
	ds_read_b128 v[208:211], v173 offset:35840
	ds_read_b128 v[212:215], v173 offset:36864
	ds_read_b128 v[216:219], v173 offset:37888
	ds_read_b128 v[220:223], v173 offset:38912
	ds_read_b128 v[224:227], v173 offset:39936
	global_load_lds_dwordx4 v[232:233], off
	v_lshl_add_u64 v[232:233], s[40:41], 0, v[146:147]
	s_mov_b32 m0, s47
	s_nop 0
	global_load_lds_dwordx4 v[232:233], off
	s_waitcnt vmcnt(8)
	s_waitcnt lgkmcnt(0)
	s_barrier
	s_setprio 1
	v_mfma_f32_16x16x32_bf16 v[124:127], v[128:131], v[196:199], v[124:127]
	v_mfma_f32_16x16x32_bf16 v[120:123], v[136:139], v[196:199], v[120:123]
	v_mfma_f32_16x16x32_bf16 v[108:111], v[128:131], v[204:207], v[108:111]
	v_mfma_f32_16x16x32_bf16 v[104:107], v[136:139], v[204:207], v[104:107]
	v_mfma_f32_16x16x32_bf16 v[92:95], v[128:131], v[212:215], v[92:95]
	v_mfma_f32_16x16x32_bf16 v[88:91], v[136:139], v[212:215], v[88:91]
	v_mfma_f32_16x16x32_bf16 v[76:79], v[128:131], v[220:223], v[76:79]
	v_mfma_f32_16x16x32_bf16 v[72:75], v[136:139], v[220:223], v[72:75]
	v_mfma_f32_16x16x32_bf16 v[124:127], v[132:135], v[200:203], v[124:127]
	v_mfma_f32_16x16x32_bf16 v[120:123], v[140:143], v[200:203], v[120:123]
	v_mfma_f32_16x16x32_bf16 v[108:111], v[132:135], v[208:211], v[108:111]
	v_mfma_f32_16x16x32_bf16 v[104:107], v[140:143], v[208:211], v[104:107]
	v_mfma_f32_16x16x32_bf16 v[92:95], v[132:135], v[216:219], v[92:95]
	v_mfma_f32_16x16x32_bf16 v[88:91], v[140:143], v[216:219], v[88:91]
	v_mfma_f32_16x16x32_bf16 v[76:79], v[132:135], v[224:227], v[76:79]
	v_mfma_f32_16x16x32_bf16 v[72:75], v[140:143], v[224:227], v[72:75]
	v_mfma_f32_16x16x32_bf16 v[116:119], v[164:167], v[196:199], v[116:119]
	v_mfma_f32_16x16x32_bf16 v[112:115], v[182:185], v[196:199], v[112:115]
	v_mfma_f32_16x16x32_bf16 v[100:103], v[164:167], v[204:207], v[100:103]
	v_mfma_f32_16x16x32_bf16 v[96:99], v[182:185], v[204:207], v[96:99]
	v_mfma_f32_16x16x32_bf16 v[84:87], v[164:167], v[212:215], v[84:87]
	v_mfma_f32_16x16x32_bf16 v[80:83], v[182:185], v[212:215], v[80:83]
	v_mfma_f32_16x16x32_bf16 v[68:71], v[164:167], v[220:223], v[68:71]
	v_mfma_f32_16x16x32_bf16 v[64:67], v[182:185], v[220:223], v[64:67]
	v_mfma_f32_16x16x32_bf16 v[116:119], v[178:181], v[200:203], v[116:119]
	v_mfma_f32_16x16x32_bf16 v[112:115], v[192:195], v[200:203], v[112:115]
	v_mfma_f32_16x16x32_bf16 v[100:103], v[178:181], v[208:211], v[100:103]
	v_mfma_f32_16x16x32_bf16 v[96:99], v[192:195], v[208:211], v[96:99]
	v_mfma_f32_16x16x32_bf16 v[84:87], v[178:181], v[216:219], v[84:87]
	v_mfma_f32_16x16x32_bf16 v[80:83], v[192:195], v[216:219], v[80:83]
	v_mfma_f32_16x16x32_bf16 v[68:71], v[178:181], v[224:227], v[68:71]
	v_mfma_f32_16x16x32_bf16 v[64:67], v[192:195], v[224:227], v[64:67]
	s_setprio 0
	s_barrier
; #define PG8_STAGE(bufoff, gbase, voff) do { _Pragma("unroll") for (int _i = 0; _i < 2; ++_i) \
;         __builtin_amdgcn_global_load_lds((const unsigned*)((const char*)(gbase) + (voff)[_i]), (PG8_LAS unsigned*)(lds + (bufoff) + ldsw + _i * 8192), 16, 0, 0); } while (0)
; #define PG8_LDA(dst, b, h) do { _Pragma("unroll") for (int m = 0; m < 4; ++m) _Pragma("unroll") for (int k = 0; k < 2; ++k) dst[m][k] = *(const PG8_LAS bf16x8*)(lds + PG8_SA(b, h) + aoff + m * 2048 + k * 1024); } while (0)
; #define PG8_MMA(ai, bj, At, Bt) do { __builtin_amdgcn_s_setprio(1); _Pragma("unroll") for (int m = 0; m < 4; ++m) _Pragma("unroll") for (int n = 0; n < 2; ++n) _Pragma("unroll") for (int k = 0; k < 2; ++k) \
;         acc[ai][bj][m][n] = __builtin_amdgcn_mfma_f32_16x16x32_bf16(Bt[n][k], At[m][k], acc[ai][bj][m][n], 0, 0, 0); __builtin_amdgcn_s_setprio(0); } while (0)
; #define PG8_WAIT_V(n) asm volatile("s_waitcnt vmcnt(" #n ")" ::: "memory")
; #define PG8_WAIT_L(n) asm volatile("s_waitcnt lgkmcnt(" #n ")" ::: "memory")
; #define PG8_BAR __builtin_amdgcn_s_barrier()
; #define PG8_SCHED __builtin_amdgcn_sched_barrier(0)
; template <class Epi, class Sched, bool ALIGN_EPI = false, bool SP2 = false>
; __device__ __forceinline__ void gemm_phase(PG8_LAS unsigned char* lds, const Gemm g, const Sched& S, const Epi& E) {
;     ...
;         for (int t = 0; t < nt; t += 2) {
;             const bool last = (t == nt - 2);
;             const char* a1 = cA + (size_t)(t + 1) * kstep;
;             const char* a2 = last ? nA : cA + (size_t)(t + 2) * kstep; const char* b2 = last ? nB : cB + (size_t)(t + 2) * kstep;
;     ...
;             PG8_LDA(At, 1, 1); PG8_STAGE(PG8_SB(1, 0), b3, voffB); PG8_STAGE(PG8_SB(1, 1), b3 + hstep, voffB); PG8_STAGE(PG8_SA(1, 0), a3, voffA);
;             PG8_WAIT_V(8); PG8_WAIT_L(0); PG8_BAR; PG8_MMA(1, 0, At, B0); PG8_MMA(1, 1, At, B1); PG8_BAR; PG8_SCHED;
	s_add_i32 s40, s61, s33
	v_lshl_add_u64 v[168:169], v[168:169], 0, s[16:17]
	s_mov_b32 m0, s40
	ds_read_b128 v[196:199], v173 offset:49152
	ds_read_b128 v[200:203], v173 offset:50176
	ds_read_b128 v[204:207], v173 offset:51200
	ds_read_b128 v[208:211], v173 offset:52224
	ds_read_b128 v[212:215], v173 offset:53248
	ds_read_b128 v[216:219], v173 offset:54272
	ds_read_b128 v[220:223], v173 offset:55296
	ds_read_b128 v[224:227], v173 offset:56320
	global_load_lds_dwordx4 v[168:169], off
	s_add_i32 m0, s40, 0x2000
	s_add_u32 s38, s38, 0x40080
	v_lshl_add_u64 v[168:169], v[186:187], 0, s[16:17]
	s_addc_u32 s39, s39, 0
	s_add_i32 s40, s62, s33
	global_load_lds_dwordx4 v[168:169], off
	v_lshl_add_u64 v[168:169], s[38:39], 0, v[148:149]
	s_mov_b32 m0, s40
	s_nop 0
	global_load_lds_dwordx4 v[168:169], off
	v_lshl_add_u64 v[168:169], s[38:39], 0, v[144:145]
	s_add_i32 m0, s40, 0x2000
	s_nop 0
	global_load_lds_dwordx4 v[168:169], off
	v_lshl_add_u64 v[168:169], v[228:229], 0, s[16:17]
	s_mov_b32 m0, s48
	s_nop 0
	global_load_lds_dwordx4 v[168:169], off
	v_lshl_add_u64 v[168:169], v[230:231], 0, s[16:17]
	s_mov_b32 m0, s49
	s_nop 0
	global_load_lds_dwordx4 v[168:169], off
	s_waitcnt vmcnt(8)
	s_waitcnt lgkmcnt(0)
	s_barrier
	s_setprio 1
	v_mfma_f32_16x16x32_bf16 v[60:63], v[128:131], v[196:199], v[60:63]
	v_mfma_f32_16x16x32_bf16 v[56:59], v[136:139], v[196:199], v[56:59]
	v_mfma_f32_16x16x32_bf16 v[44:47], v[128:131], v[204:207], v[44:47]
	v_mfma_f32_16x16x32_bf16 v[40:43], v[136:139], v[204:207], v[40:43]
	v_mfma_f32_16x16x32_bf16 v[28:31], v[128:131], v[212:215], v[28:31]
	v_mfma_f32_16x16x32_bf16 v[24:27], v[136:139], v[212:215], v[24:27]
	v_mfma_f32_16x16x32_bf16 v[12:15], v[128:131], v[220:223], v[12:15]
	v_mfma_f32_16x16x32_bf16 v[8:11], v[136:139], v[220:223], v[8:11]
	v_mfma_f32_16x16x32_bf16 v[60:63], v[132:135], v[200:203], v[60:63]
	v_mfma_f32_16x16x32_bf16 v[56:59], v[140:143], v[200:203], v[56:59]
	v_mfma_f32_16x16x32_bf16 v[44:47], v[132:135], v[208:211], v[44:47]
	v_mfma_f32_16x16x32_bf16 v[40:43], v[140:143], v[208:211], v[40:43]
	v_mfma_f32_16x16x32_bf16 v[28:31], v[132:135], v[216:219], v[28:31]
	v_mfma_f32_16x16x32_bf16 v[24:27], v[140:143], v[216:219], v[24:27]
	v_mfma_f32_16x16x32_bf16 v[12:15], v[132:135], v[224:227], v[12:15]
	v_mfma_f32_16x16x32_bf16 v[8:11], v[140:143], v[224:227], v[8:11]
	v_mfma_f32_16x16x32_bf16 v[52:55], v[164:167], v[196:199], v[52:55]
	v_mfma_f32_16x16x32_bf16 v[48:51], v[182:185], v[196:199], v[48:51]
	v_mfma_f32_16x16x32_bf16 v[36:39], v[164:167], v[204:207], v[36:39]
	v_mfma_f32_16x16x32_bf16 v[32:35], v[182:185], v[204:207], v[32:35]
	v_mfma_f32_16x16x32_bf16 v[20:23], v[164:167], v[212:215], v[20:23]
	v_mfma_f32_16x16x32_bf16 v[16:19], v[182:185], v[212:215], v[16:19]
	v_mfma_f32_16x16x32_bf16 v[4:7], v[164:167], v[220:223], v[4:7]
	v_mfma_f32_16x16x32_bf16 v[0:3], v[182:185], v[220:223], v[0:3]
	v_mfma_f32_16x16x32_bf16 v[52:55], v[178:181], v[200:203], v[52:55]
	v_mfma_f32_16x16x32_bf16 v[48:51], v[192:195], v[200:203], v[48:51]
	v_mfma_f32_16x16x32_bf16 v[36:39], v[178:181], v[208:211], v[36:39]
	v_mfma_f32_16x16x32_bf16 v[32:35], v[192:195], v[208:211], v[32:35]
	v_mfma_f32_16x16x32_bf16 v[20:23], v[178:181], v[216:219], v[20:23]
	v_mfma_f32_16x16x32_bf16 v[16:19], v[192:195], v[216:219], v[16:19]
	v_mfma_f32_16x16x32_bf16 v[4:7], v[178:181], v[224:227], v[4:7]
	v_mfma_f32_16x16x32_bf16 v[0:3], v[192:195], v[224:227], v[0:3]
	s_setprio 0
	s_barrier
	s_add_i32 s60, s60, 2
	s_add_u32 s2, s2, 0x100
	s_addc_u32 s3, s3, 0
	s_add_u32 s58, s58, 0x100
	s_addc_u32 s59, s59, 0
	s_cmp_gt_u32 s60, 13
	s_cbranch_scc0 .LBB0_374
	s_and_b64 vcc, exec, s[18:19]
	s_cbranch_vccnz .LBB0_379
	v_lshl_add_u32 v164, s0, 8, v155
	s_cmp_gt_i32 s57, 3
	s_mov_b64 s[0:1], -1
	s_cbranch_scc1 .LBB0_380

;     __device__ __forceinline__ void operator()(const f32x4 (&acc)[2][2][4][2], const pg8::Unit& u, int wr, int wc, int fr, int fq) const {
;     ...
;         } else {
;             if (wc == 0 && fq == 0) {
;                 const f32x4 bi = *(const f32x4*)ib, bf = *(const f32x4*)fb;
; #pragma unroll
;                 for (int ai = 0; ai < 2; ++ai)
; #pragma unroll
;                     for (int m = 0; m < 4; ++m) {
;                         const int row = row0 + ai * 128 + m * 16;
;                         const float rs = rsqrtf(sumsq[row] * (1.f / 1024.f) + EPS);
;                         *(f32x4*)(G + (size_t)row * 8) = acc[ai][0][m][0] * rs + bi;
;                         *(f32x4*)(G + (size_t)row * 8 + 4) = acc[ai][0][m][1] * rs + bf;
.LBB0_380:
	s_cmp_gt_u32 s57, 13
	s_cbranch_scc0 .LBB0_384
	s_and_saveexec_b64 s[2:3], s[4:5]
	s_cbranch_execz .LBB0_383
	v_readlane_b32 s60, v235, 2
	v_ashrrev_i32_e32 v165, 31, v164
	v_readlane_b32 s62, v235, 4
	v_readlane_b32 s63, v235, 5
	v_readlane_b32 s61, v235, 3
	s_mov_b64 s[0:1], 0x1000
	v_lshl_add_u64 v[136:137], v[164:165], 2, s[62:63]
	global_load_dword v138, v[136:137], off
	global_load_dword v236, v[136:137], off offset:64
	global_load_dword v237, v[136:137], off offset:128
	global_load_dword v238, v[136:137], off offset:192
	global_load_dword v239, v[136:137], off offset:512
	global_load_dword v240, v[136:137], off offset:576
	global_load_dword v241, v[136:137], off offset:640
	global_load_dword v242, v[136:137], off offset:704
	v_readlane_b32 s60, v235, 14
	v_readlane_b32 s66, v235, 20
	v_readlane_b32 s67, v235, 21
	v_readlane_b32 s68, v235, 22
	v_readlane_b32 s69, v235, 23
	s_nop 2
	global_load_dwordx4 v[132:135], v153, s[66:67]
	s_nop 0
	global_load_dwordx4 v[128:131], v153, s[68:69]
	s_movk_i32 s25, 0x1000
	v_readlane_b32 s61, v235, 15
	v_readlane_b32 s62, v235, 16
	v_readlane_b32 s63, v235, 17
	v_readlane_b32 s64, v235, 18
	v_readlane_b32 s65, v235, 19
	v_readlane_b32 s70, v235, 24
	v_readlane_b32 s71, v235, 25
	v_readlane_b32 s72, v235, 26
	v_readlane_b32 s73, v235, 27
	v_readlane_b32 s74, v235, 28
	v_readlane_b32 s75, v235, 29
	s_waitcnt vmcnt(0)
;     __device__ __forceinline__ void operator()(const f32x4 (&acc)[2][2][4][2], const pg8::Unit& u, int wr, int wc, int fr, int fq) const {
;     ...
;                 for (int ai = 0; ai < 2; ++ai)
; #pragma unroll
;                     for (int m = 0; m < 4; ++m) {
;                         const int row = row0 + ai * 128 + m * 16;
;                         const float rs = rsqrtf(sumsq[row] * (1.f / 1024.f) + EPS);
;                         *(f32x4*)(G + (size_t)row * 8) = acc[ai][0][m][0] * rs + bi;
;                         *(f32x4*)(G + (size_t)row * 8 + 4) = acc[ai][0][m][1] * rs + bf;
	v_fmamk_f32 v138, v138, 0x3a800000, v174
	v_mul_f32_e32 v139, 0x4b800000, v138
	v_cmp_gt_f32_e32 vcc, s54, v138
	s_nop 1
	v_cndmask_b32_e32 v138, v138, v139, vcc
	v_rsq_f32_e32 v140, v138
	v_lshlrev_b64 v[138:139], 5, v[164:165]
	v_lshl_add_u64 v[138:139], s[8:9], 0, v[138:139]
	v_mul_f32_e32 v141, 0x45800000, v140
	v_cndmask_b32_e32 v152, v140, v141, vcc
	v_pk_fma_f32 v[142:143], v[126:127], v[152:153], v[134:135] op_sel_hi:[1,0,1]
	v_pk_fma_f32 v[140:141], v[124:125], v[152:153], v[132:133] op_sel_hi:[1,0,1]
	v_pk_fma_f32 v[168:169], v[122:123], v[152:153], v[130:131] op_sel_hi:[1,0,1]
	v_pk_fma_f32 v[166:167], v[120:121], v[152:153], v[128:129] op_sel_hi:[1,0,1]
	global_store_dwordx4 v[138:139], v[140:143], off
	global_store_dwordx4 v[138:139], v[166:169], off offset:16
	s_nop 0
	v_or_b32_e32 v140, 16, v164
	s_nop 0
	v_fmamk_f32 v141, v236, 0x3a800000, v174
	v_mul_f32_e32 v142, 0x4b800000, v141
	v_cmp_gt_f32_e32 vcc, s54, v141
	s_nop 1
	v_cndmask_b32_e32 v141, v141, v142, vcc
	v_rsq_f32_e32 v142, v141
	v_ashrrev_i32_e32 v141, 31, v140
	v_lshlrev_b64 v[140:141], 5, v[140:141]
	v_lshl_add_u64 v[178:179], s[8:9], 0, v[140:141]
	v_mul_f32_e32 v140, 0x45800000, v142
	v_cndmask_b32_e32 v152, v142, v140, vcc
	v_pk_fma_f32 v[142:143], v[110:111], v[152:153], v[134:135] op_sel_hi:[1,0,1]
	v_pk_fma_f32 v[140:141], v[108:109], v[152:153], v[132:133] op_sel_hi:[1,0,1]
	v_pk_fma_f32 v[168:169], v[106:107], v[152:153], v[130:131] op_sel_hi:[1,0,1]
	v_pk_fma_f32 v[166:167], v[104:105], v[152:153], v[128:129] op_sel_hi:[1,0,1]
	global_store_dwordx4 v[178:179], v[140:143], off
	global_store_dwordx4 v[178:179], v[166:169], off offset:16
	s_nop 0
	v_or_b32_e32 v140, 32, v164
	s_nop 0
	v_fmamk_f32 v141, v237, 0x3a800000, v174
	v_mul_f32_e32 v142, 0x4b800000, v141
	v_cmp_gt_f32_e32 vcc, s54, v141
	s_nop 1
	v_cndmask_b32_e32 v141, v141, v142, vcc
	v_rsq_f32_e32 v142, v141
	v_ashrrev_i32_e32 v141, 31, v140
	v_lshlrev_b64 v[140:141], 5, v[140:141]
	v_lshl_add_u64 v[178:179], s[8:9], 0, v[140:141]
	v_mul_f32_e32 v140, 0x45800000, v142
	v_cndmask_b32_e32 v152, v142, v140, vcc
	v_pk_fma_f32 v[142:143], v[94:95], v[152:153], v[134:135] op_sel_hi:[1,0,1]
	v_pk_fma_f32 v[140:141], v[92:93], v[152:153], v[132:133] op_sel_hi:[1,0,1]
	v_pk_fma_f32 v[168:169], v[90:91], v[152:153], v[130:131] op_sel_hi:[1,0,1]
	v_pk_fma_f32 v[166:167], v[88:89], v[152:153], v[128:129] op_sel_hi:[1,0,1]
	global_store_dwordx4 v[178:179], v[140:143], off
	global_store_dwordx4 v[178:179], v[166:169], off offset:16
	s_nop 0
	v_or_b32_e32 v140, 48, v164
	s_nop 0
	v_fmamk_f32 v141, v238, 0x3a800000, v174
	v_mul_f32_e32 v142, 0x4b800000, v141
	v_cmp_gt_f32_e32 vcc, s54, v141
	s_nop 1
	v_cndmask_b32_e32 v141, v141, v142, vcc
	v_rsq_f32_e32 v142, v141
	v_ashrrev_i32_e32 v141, 31, v140
	v_lshlrev_b64 v[140:141], 5, v[140:141]
	v_lshl_add_u64 v[178:179], s[8:9], 0, v[140:141]
	v_mul_f32_e32 v140, 0x45800000, v142
	v_cndmask_b32_e32 v152, v142, v140, vcc
	v_pk_fma_f32 v[142:143], v[78:79], v[152:153], v[134:135] op_sel_hi:[1,0,1]
	v_pk_fma_f32 v[140:141], v[76:77], v[152:153], v[132:133] op_sel_hi:[1,0,1]
	v_pk_fma_f32 v[168:169], v[74:75], v[152:153], v[130:131] op_sel_hi:[1,0,1]
	v_pk_fma_f32 v[166:167], v[72:73], v[152:153], v[128:129] op_sel_hi:[1,0,1]
	global_store_dwordx4 v[178:179], v[140:143], off
	global_store_dwordx4 v[178:179], v[166:169], off offset:16
	s_nop 0
	v_lshl_add_u64 v[178:179], v[138:139], 0, s[0:1]
	v_add_co_u32_e64 v180, s[0:1], s25, v138
	s_nop 0
	v_fmamk_f32 v140, v239, 0x3a800000, v174
	v_mul_f32_e32 v141, 0x4b800000, v140
	v_cmp_gt_f32_e32 vcc, s54, v140
	v_addc_co_u32_e64 v181, s[0:1], 0, v139, s[0:1]
	s_nop 0
	v_cndmask_b32_e32 v140, v140, v141, vcc
	v_rsq_f32_e32 v140, v140
	s_mov_b64 s[0:1], 0x1200
	v_mul_f32_e32 v141, 0x45800000, v140
	v_cndmask_b32_e32 v152, v140, v141, vcc
	v_pk_fma_f32 v[142:143], v[62:63], v[152:153], v[134:135] op_sel_hi:[1,0,1]
	v_pk_fma_f32 v[140:141], v[60:61], v[152:153], v[132:133] op_sel_hi:[1,0,1]
	v_pk_fma_f32 v[168:169], v[58:59], v[152:153], v[130:131] op_sel_hi:[1,0,1]
	v_pk_fma_f32 v[166:167], v[56:57], v[152:153], v[128:129] op_sel_hi:[1,0,1]
	global_store_dwordx4 v[180:181], v[140:143], off
	global_store_dwordx4 v[178:179], v[166:169], off offset:16
	s_nop 0
	v_lshl_add_u64 v[178:179], v[138:139], 0, s[0:1]
	s_nop 0
	v_fmamk_f32 v140, v240, 0x3a800000, v174
	v_mul_f32_e32 v141, 0x4b800000, v140
	v_cmp_gt_f32_e32 vcc, s54, v140
	s_nop 1
	v_cndmask_b32_e32 v140, v140, v141, vcc
	v_rsq_f32_e32 v140, v140
	s_nop 0
	v_mul_f32_e32 v141, 0x45800000, v140
	v_cndmask_b32_e32 v152, v140, v141, vcc
	v_pk_fma_f32 v[142:143], v[46:47], v[152:153], v[134:135] op_sel_hi:[1,0,1]
	v_pk_fma_f32 v[140:141], v[44:45], v[152:153], v[132:133] op_sel_hi:[1,0,1]
	v_pk_fma_f32 v[168:169], v[42:43], v[152:153], v[130:131] op_sel_hi:[1,0,1]
	v_pk_fma_f32 v[166:167], v[40:41], v[152:153], v[128:129] op_sel_hi:[1,0,1]
	global_store_dwordx4 v[180:181], v[140:143], off offset:512
	global_store_dwordx4 v[178:179], v[166:169], off offset:16
	s_nop 0
	v_lshl_add_u64 v[178:179], v[138:139], 0, s[20:21]
	s_nop 0
	v_fmamk_f32 v140, v241, 0x3a800000, v174
	v_mul_f32_e32 v141, 0x4b800000, v140
	v_cmp_gt_f32_e32 vcc, s54, v140
	s_nop 1
	v_cndmask_b32_e32 v140, v140, v141, vcc
	v_rsq_f32_e32 v140, v140
	s_nop 0
	v_mul_f32_e32 v141, 0x45800000, v140
	v_cndmask_b32_e32 v152, v140, v141, vcc
	v_pk_fma_f32 v[142:143], v[30:31], v[152:153], v[134:135] op_sel_hi:[1,0,1]
	v_pk_fma_f32 v[140:141], v[28:29], v[152:153], v[132:133] op_sel_hi:[1,0,1]
	v_pk_fma_f32 v[168:169], v[26:27], v[152:153], v[130:131] op_sel_hi:[1,0,1]
	v_pk_fma_f32 v[166:167], v[24:25], v[152:153], v[128:129] op_sel_hi:[1,0,1]
	global_store_dwordx4 v[180:181], v[140:143], off offset:1024
	global_store_dwordx4 v[178:179], v[166:169], off offset:16
	s_nop 0
	s_nop 0
	v_fmamk_f32 v136, v242, 0x3a800000, v174
	v_mul_f32_e32 v137, 0x4b800000, v136
	v_cmp_gt_f32_e32 vcc, s54, v136
	s_nop 1
	v_cndmask_b32_e32 v136, v136, v137, vcc
	v_rsq_f32_e32 v140, v136
	v_lshl_add_u64 v[136:137], v[138:139], 0, s[22:23]
	v_mul_f32_e32 v138, 0x45800000, v140
	v_cndmask_b32_e32 v138, v140, v138, vcc
	v_pk_fma_f32 v[134:135], v[14:15], v[138:139], v[134:135] op_sel_hi:[1,0,1]
	v_pk_fma_f32 v[132:133], v[12:13], v[138:139], v[132:133] op_sel_hi:[1,0,1]
	v_pk_fma_f32 v[130:131], v[10:11], v[138:139], v[130:131] op_sel_hi:[1,0,1]
	v_pk_fma_f32 v[128:129], v[8:9], v[138:139], v[128:129] op_sel_hi:[1,0,1]
	global_store_dwordx4 v[180:181], v[132:135], off offset:1536
	global_store_dwordx4 v[136:137], v[128:131], off offset:16

; __device__ __forceinline__ unsigned pk2(float lo, float hi) { return pg8::cvt_pk_bf16(lo, hi); }
;     __device__ __forceinline__ void operator()(const f32x4 (&acc)[2][2][4][2], const pg8::Unit& u, int wr, int wc, int fr, int fq) const {
;     ...
;         } else if (u.pn < 14) {
; #pragma unroll
;             for (int ai = 0; ai < 2; ++ai)
; #pragma unroll
;                 for (int m = 0; m < 4; ++m) {
;                     const int row = row0 + ai * 128 + m * 16;
;                     const float rs = rsqrtf(sumsq[row] * (1.f / 1024.f) + EPS);
; #pragma unroll
;                     for (int bj = 0; bj < 2; ++bj) {
;                         const f32x4 a = acc[ai][bj][m][0] * rs, b = acc[ai][bj][m][1] * rs;
;                         u32x4 o; o.x = pk2(a[0], a[1]); o.y = pk2(a[2], a[3]); o.z = pk2(b[0], b[1]); o.w = pk2(b[2], b[3]);
;                         *(u32x4*)(P + (size_t)row * PW + u.pn * 256 + 128 * bj + 32 * wc + 8 * fq) = o;
;                     }
.LBB0_384:
	s_andn2_b64 vcc, exec, s[0:1]
	s_cbranch_vccnz .LBB0_386
	v_readlane_b32 s0, v235, 2
	v_ashrrev_i32_e32 v165, 31, v164
	v_readlane_b32 s2, v235, 4
	v_readlane_b32 s3, v235, 5
	v_readlane_b32 s1, v235, 3
	v_readlane_b32 s0, v235, 33
	v_lshl_add_u64 v[128:129], v[164:165], 2, s[2:3]
	global_load_dword v134, v[128:129], off
	global_load_dword v236, v[128:129], off offset:64
	global_load_dword v237, v[128:129], off offset:128
	global_load_dword v238, v[128:129], off offset:192
	global_load_dword v239, v[128:129], off offset:512
	global_load_dword v240, v[128:129], off offset:576
	global_load_dword v241, v[128:129], off offset:640
	global_load_dword v242, v[128:129], off offset:704
	v_readlane_b32 s1, v235, 34
	s_mov_b32 s25, s13
	v_lshlrev_b32_e32 v152, 1, v154
	v_mov_b64_e32 v[130:131], s[0:1]
	s_lshl_b32 s0, s57, 9
	s_mov_b32 s1, s13
	v_mad_i64_i32 v[132:133], s[2:3], v164, s55, v[130:131]
	v_lshl_add_u64 v[132:133], v[132:133], 0, s[0:1]
	v_lshl_add_u64 v[132:133], v[132:133], 0, s[24:25]
	v_lshl_add_u64 v[136:137], v[132:133], 0, v[152:153]
	s_waitcnt vmcnt(0)
	v_fmamk_f32 v134, v134, 0x3a800000, v174
	v_mul_f32_e32 v135, 0x4b800000, v134
	v_cmp_gt_f32_e32 vcc, s54, v134
	s_nop 1
	v_cndmask_b32_e32 v134, v134, v135, vcc
	v_rsq_f32_e32 v134, v134
	s_nop 0
	v_mul_f32_e32 v132, 0x45800000, v134
	v_cndmask_b32_e32 v132, v134, v132, vcc
	v_pk_mul_f32 v[134:135], v[126:127], v[132:133] op_sel_hi:[1,0]
	v_pk_mul_f32 v[138:139], v[124:125], v[132:133] op_sel_hi:[1,0]
	v_pk_mul_f32 v[140:141], v[122:123], v[132:133] op_sel_hi:[1,0]
	v_pk_mul_f32 v[142:143], v[120:121], v[132:133] op_sel_hi:[1,0]
	v_pk_mul_f32 v[166:167], v[118:119], v[132:133] op_sel_hi:[1,0]
	v_pk_mul_f32 v[168:169], v[116:117], v[132:133] op_sel_hi:[1,0]
	v_pk_mul_f32 v[178:179], v[114:115], v[132:133] op_sel_hi:[1,0]
	v_pk_mul_f32 v[180:181], v[112:113], v[132:133] op_sel_hi:[1,0]
	v_cvt_pk_bf16_f32 v132, v138, v139
	v_cvt_pk_bf16_f32 v133, v134, v135
	v_cvt_pk_bf16_f32 v134, v142, v143
	v_cvt_pk_bf16_f32 v135, v140, v141
	global_store_dwordx4 v[136:137], v[132:135], off
	s_nop 1
	v_cvt_pk_bf16_f32 v132, v168, v169
	v_cvt_pk_bf16_f32 v133, v166, v167
	v_cvt_pk_bf16_f32 v134, v180, v181
	v_cvt_pk_bf16_f32 v135, v178, v179
	global_store_dwordx4 v[136:137], v[132:135], off offset:256
	s_nop 0
	s_nop 0
	v_or_b32_e32 v132, 16, v164
	v_mad_i64_i32 v[132:133], s[2:3], v132, s55, v[130:131]
	v_lshl_add_u64 v[132:133], v[132:133], 0, s[0:1]
	v_lshl_add_u64 v[132:133], v[132:133], 0, s[24:25]
	v_lshl_add_u64 v[136:137], v[132:133], 0, v[152:153]
	s_nop 0
	v_fmamk_f32 v134, v236, 0x3a800000, v174
	v_mul_f32_e32 v135, 0x4b800000, v134
	v_cmp_gt_f32_e32 vcc, s54, v134
	s_nop 1
	v_cndmask_b32_e32 v134, v134, v135, vcc
	v_rsq_f32_e32 v134, v134
	s_nop 0
	v_mul_f32_e32 v132, 0x45800000, v134
	v_cndmask_b32_e32 v132, v134, v132, vcc
	v_pk_mul_f32 v[134:135], v[110:111], v[132:133] op_sel_hi:[1,0]
	v_pk_mul_f32 v[138:139], v[108:109], v[132:133] op_sel_hi:[1,0]
	v_pk_mul_f32 v[140:141], v[106:107], v[132:133] op_sel_hi:[1,0]
	v_pk_mul_f32 v[142:143], v[104:105], v[132:133] op_sel_hi:[1,0]
	v_pk_mul_f32 v[166:167], v[102:103], v[132:133] op_sel_hi:[1,0]
	v_pk_mul_f32 v[168:169], v[100:101], v[132:133] op_sel_hi:[1,0]
	v_pk_mul_f32 v[178:179], v[98:99], v[132:133] op_sel_hi:[1,0]
	v_pk_mul_f32 v[180:181], v[96:97], v[132:133] op_sel_hi:[1,0]
	v_cvt_pk_bf16_f32 v132, v138, v139
	v_cvt_pk_bf16_f32 v133, v134, v135
	v_cvt_pk_bf16_f32 v134, v142, v143
	v_cvt_pk_bf16_f32 v135, v140, v141
	global_store_dwordx4 v[136:137], v[132:135], off
	s_nop 1
	v_cvt_pk_bf16_f32 v132, v168, v169
	v_cvt_pk_bf16_f32 v133, v166, v167
	v_cvt_pk_bf16_f32 v134, v180, v181
	v_cvt_pk_bf16_f32 v135, v178, v179
	global_store_dwordx4 v[136:137], v[132:135], off offset:256
	s_nop 0
	s_nop 0
	v_or_b32_e32 v132, 32, v164
	v_mad_i64_i32 v[132:133], s[2:3], v132, s55, v[130:131]
	v_lshl_add_u64 v[132:133], v[132:133], 0, s[0:1]
	v_lshl_add_u64 v[132:133], v[132:133], 0, s[24:25]
	v_lshl_add_u64 v[136:137], v[132:133], 0, v[152:153]
	s_nop 0
	v_fmamk_f32 v134, v237, 0x3a800000, v174
	v_mul_f32_e32 v135, 0x4b800000, v134
	v_cmp_gt_f32_e32 vcc, s54, v134
	s_nop 1
	v_cndmask_b32_e32 v134, v134, v135, vcc
	v_rsq_f32_e32 v134, v134
	s_nop 0
	v_mul_f32_e32 v132, 0x45800000, v134
	v_cndmask_b32_e32 v132, v134, v132, vcc
	v_pk_mul_f32 v[134:135], v[94:95], v[132:133] op_sel_hi:[1,0]
	v_pk_mul_f32 v[138:139], v[92:93], v[132:133] op_sel_hi:[1,0]
	v_pk_mul_f32 v[140:141], v[90:91], v[132:133] op_sel_hi:[1,0]
	v_pk_mul_f32 v[142:143], v[88:89], v[132:133] op_sel_hi:[1,0]
	v_pk_mul_f32 v[166:167], v[86:87], v[132:133] op_sel_hi:[1,0]
	v_pk_mul_f32 v[168:169], v[84:85], v[132:133] op_sel_hi:[1,0]
	v_pk_mul_f32 v[178:179], v[82:83], v[132:133] op_sel_hi:[1,0]
	v_pk_mul_f32 v[180:181], v[80:81], v[132:133] op_sel_hi:[1,0]
	v_cvt_pk_bf16_f32 v132, v138, v139
	v_cvt_pk_bf16_f32 v133, v134, v135
	v_cvt_pk_bf16_f32 v134, v142, v143
	v_cvt_pk_bf16_f32 v135, v140, v141
	global_store_dwordx4 v[136:137], v[132:135], off
	s_nop 1
	v_cvt_pk_bf16_f32 v132, v168, v169
	v_cvt_pk_bf16_f32 v133, v166, v167
	v_cvt_pk_bf16_f32 v134, v180, v181
	v_cvt_pk_bf16_f32 v135, v178, v179
	global_store_dwordx4 v[136:137], v[132:135], off offset:256
	s_nop 0
	s_nop 0
	v_or_b32_e32 v132, 48, v164
	v_mad_i64_i32 v[132:133], s[2:3], v132, s55, v[130:131]
	v_lshl_add_u64 v[132:133], v[132:133], 0, s[0:1]
	v_lshl_add_u64 v[132:133], v[132:133], 0, s[24:25]
	v_lshl_add_u64 v[136:137], v[132:133], 0, v[152:153]
	s_nop 0
	v_fmamk_f32 v134, v238, 0x3a800000, v174
	v_mul_f32_e32 v135, 0x4b800000, v134
	v_cmp_gt_f32_e32 vcc, s54, v134
	s_nop 1
	v_cndmask_b32_e32 v134, v134, v135, vcc
; __device__ __forceinline__ unsigned pk2(float lo, float hi) { return pg8::cvt_pk_bf16(lo, hi); }
;     __device__ __forceinline__ void operator()(const f32x4 (&acc)[2][2][4][2], const pg8::Unit& u, int wr, int wc, int fr, int fq) const {
;     ...
;                 for (int m = 0; m < 4; ++m) {
;                     const int row = row0 + ai * 128 + m * 16;
;                     const float rs = rsqrtf(sumsq[row] * (1.f / 1024.f) + EPS);
; #pragma unroll
;                     for (int bj = 0; bj < 2; ++bj) {
;                         const f32x4 a = acc[ai][bj][m][0] * rs, b = acc[ai][bj][m][1] * rs;
;                         u32x4 o; o.x = pk2(a[0], a[1]); o.y = pk2(a[2], a[3]); o.z = pk2(b[0], b[1]); o.w = pk2(b[2], b[3]);
;                         *(u32x4*)(P + (size_t)row * PW + u.pn * 256 + 128 * bj + 32 * wc + 8 * fq) = o;
;                     }
	v_rsq_f32_e32 v134, v134
	s_nop 0
	v_mul_f32_e32 v132, 0x45800000, v134
	v_cndmask_b32_e32 v132, v134, v132, vcc
	v_pk_mul_f32 v[134:135], v[78:79], v[132:133] op_sel_hi:[1,0]
	v_pk_mul_f32 v[138:139], v[76:77], v[132:133] op_sel_hi:[1,0]
	v_pk_mul_f32 v[140:141], v[74:75], v[132:133] op_sel_hi:[1,0]
	v_pk_mul_f32 v[142:143], v[72:73], v[132:133] op_sel_hi:[1,0]
	v_pk_mul_f32 v[166:167], v[70:71], v[132:133] op_sel_hi:[1,0]
	v_pk_mul_f32 v[168:169], v[68:69], v[132:133] op_sel_hi:[1,0]
	v_pk_mul_f32 v[178:179], v[66:67], v[132:133] op_sel_hi:[1,0]
	v_pk_mul_f32 v[180:181], v[64:65], v[132:133] op_sel_hi:[1,0]
	v_cvt_pk_bf16_f32 v132, v138, v139
	v_cvt_pk_bf16_f32 v133, v134, v135
	v_cvt_pk_bf16_f32 v134, v142, v143
	v_cvt_pk_bf16_f32 v135, v140, v141
	global_store_dwordx4 v[136:137], v[132:135], off
	s_nop 1
	v_cvt_pk_bf16_f32 v132, v168, v169
	v_cvt_pk_bf16_f32 v133, v166, v167
	v_cvt_pk_bf16_f32 v134, v180, v181
	v_cvt_pk_bf16_f32 v135, v178, v179
	global_store_dwordx4 v[136:137], v[132:135], off offset:256
	s_nop 0
	s_nop 0
	v_add_u32_e32 v132, 0x80, v164
	v_mad_i64_i32 v[132:133], s[2:3], v132, s55, v[130:131]
	v_lshl_add_u64 v[132:133], v[132:133], 0, s[0:1]
	v_lshl_add_u64 v[132:133], v[132:133], 0, s[24:25]
	v_lshl_add_u64 v[136:137], v[132:133], 0, v[152:153]
	s_nop 0
	v_fmamk_f32 v134, v239, 0x3a800000, v174
	v_mul_f32_e32 v135, 0x4b800000, v134
	v_cmp_gt_f32_e32 vcc, s54, v134
	s_nop 1
	v_cndmask_b32_e32 v134, v134, v135, vcc
	v_rsq_f32_e32 v134, v134
	s_nop 0
	v_mul_f32_e32 v132, 0x45800000, v134
	v_cndmask_b32_e32 v132, v134, v132, vcc
	v_pk_mul_f32 v[134:135], v[62:63], v[132:133] op_sel_hi:[1,0]
	v_pk_mul_f32 v[138:139], v[60:61], v[132:133] op_sel_hi:[1,0]
	v_pk_mul_f32 v[140:141], v[58:59], v[132:133] op_sel_hi:[1,0]
	v_pk_mul_f32 v[142:143], v[56:57], v[132:133] op_sel_hi:[1,0]
	v_pk_mul_f32 v[166:167], v[54:55], v[132:133] op_sel_hi:[1,0]
	v_pk_mul_f32 v[168:169], v[52:53], v[132:133] op_sel_hi:[1,0]
	v_pk_mul_f32 v[178:179], v[50:51], v[132:133] op_sel_hi:[1,0]
	v_pk_mul_f32 v[180:181], v[48:49], v[132:133] op_sel_hi:[1,0]
	v_cvt_pk_bf16_f32 v132, v138, v139
	v_cvt_pk_bf16_f32 v133, v134, v135
	v_cvt_pk_bf16_f32 v134, v142, v143
	v_cvt_pk_bf16_f32 v135, v140, v141
	global_store_dwordx4 v[136:137], v[132:135], off
	s_nop 1
	v_cvt_pk_bf16_f32 v132, v168, v169
	v_cvt_pk_bf16_f32 v133, v166, v167
	v_cvt_pk_bf16_f32 v134, v180, v181
	v_cvt_pk_bf16_f32 v135, v178, v179
	global_store_dwordx4 v[136:137], v[132:135], off offset:256
	s_nop 0
	s_nop 0
	v_add_u32_e32 v132, 0x90, v164
	v_mad_i64_i32 v[132:133], s[2:3], v132, s55, v[130:131]
	v_lshl_add_u64 v[132:133], v[132:133], 0, s[0:1]
	v_lshl_add_u64 v[132:133], v[132:133], 0, s[24:25]
	v_lshl_add_u64 v[136:137], v[132:133], 0, v[152:153]
	s_nop 0
	v_fmamk_f32 v134, v240, 0x3a800000, v174
	v_mul_f32_e32 v135, 0x4b800000, v134
	v_cmp_gt_f32_e32 vcc, s54, v134
	s_nop 1
	v_cndmask_b32_e32 v134, v134, v135, vcc
	v_rsq_f32_e32 v134, v134
	s_nop 0
	v_mul_f32_e32 v132, 0x45800000, v134
	v_cndmask_b32_e32 v132, v134, v132, vcc
	v_pk_mul_f32 v[134:135], v[46:47], v[132:133] op_sel_hi:[1,0]
	v_pk_mul_f32 v[138:139], v[44:45], v[132:133] op_sel_hi:[1,0]
	v_pk_mul_f32 v[140:141], v[42:43], v[132:133] op_sel_hi:[1,0]
	v_pk_mul_f32 v[142:143], v[40:41], v[132:133] op_sel_hi:[1,0]
	v_pk_mul_f32 v[166:167], v[38:39], v[132:133] op_sel_hi:[1,0]
	v_pk_mul_f32 v[168:169], v[36:37], v[132:133] op_sel_hi:[1,0]
	v_pk_mul_f32 v[178:179], v[34:35], v[132:133] op_sel_hi:[1,0]
	v_pk_mul_f32 v[180:181], v[32:33], v[132:133] op_sel_hi:[1,0]
	v_cvt_pk_bf16_f32 v132, v138, v139
	v_cvt_pk_bf16_f32 v133, v134, v135
	v_cvt_pk_bf16_f32 v134, v142, v143
	v_cvt_pk_bf16_f32 v135, v140, v141
	global_store_dwordx4 v[136:137], v[132:135], off
	s_nop 1
	v_cvt_pk_bf16_f32 v132, v168, v169
	v_cvt_pk_bf16_f32 v133, v166, v167
	v_cvt_pk_bf16_f32 v134, v180, v181
	v_cvt_pk_bf16_f32 v135, v178, v179
	global_store_dwordx4 v[136:137], v[132:135], off offset:256
	s_nop 0
	s_nop 0
	v_add_u32_e32 v132, 0xa0, v164
	v_mad_i64_i32 v[132:133], s[2:3], v132, s55, v[130:131]
	v_lshl_add_u64 v[132:133], v[132:133], 0, s[0:1]
	v_lshl_add_u64 v[132:133], v[132:133], 0, s[24:25]
	v_lshl_add_u64 v[136:137], v[132:133], 0, v[152:153]
	s_nop 0
	v_fmamk_f32 v134, v241, 0x3a800000, v174
	v_mul_f32_e32 v135, 0x4b800000, v134
	v_cmp_gt_f32_e32 vcc, s54, v134
	s_nop 1
	v_cndmask_b32_e32 v134, v134, v135, vcc
	v_rsq_f32_e32 v134, v134
	s_nop 0
	v_mul_f32_e32 v132, 0x45800000, v134
	v_cndmask_b32_e32 v132, v134, v132, vcc
	v_pk_mul_f32 v[134:135], v[30:31], v[132:133] op_sel_hi:[1,0]
	v_pk_mul_f32 v[138:139], v[28:29], v[132:133] op_sel_hi:[1,0]
	v_pk_mul_f32 v[140:141], v[26:27], v[132:133] op_sel_hi:[1,0]
	v_pk_mul_f32 v[142:143], v[24:25], v[132:133] op_sel_hi:[1,0]
	v_pk_mul_f32 v[166:167], v[22:23], v[132:133] op_sel_hi:[1,0]
	v_pk_mul_f32 v[168:169], v[20:21], v[132:133] op_sel_hi:[1,0]
	v_pk_mul_f32 v[178:179], v[18:19], v[132:133] op_sel_hi:[1,0]
	v_pk_mul_f32 v[180:181], v[16:17], v[132:133] op_sel_hi:[1,0]
	v_cvt_pk_bf16_f32 v132, v138, v139
	v_cvt_pk_bf16_f32 v133, v134, v135
	v_cvt_pk_bf16_f32 v134, v142, v143
	v_cvt_pk_bf16_f32 v135, v140, v141
	global_store_dwordx4 v[136:137], v[132:135], off
	s_nop 1
	v_cvt_pk_bf16_f32 v132, v168, v169
	v_cvt_pk_bf16_f32 v133, v166, v167
	v_cvt_pk_bf16_f32 v134, v180, v181
	v_cvt_pk_bf16_f32 v135, v178, v179
	global_store_dwordx4 v[136:137], v[132:135], off offset:256
	s_nop 0
	v_add_u32_e32 v128, 0xb0, v164
	v_mad_i64_i32 v[128:129], s[2:3], v128, s55, v[130:131]
	v_lshl_add_u64 v[128:129], v[128:129], 0, s[0:1]
	v_lshl_add_u64 v[128:129], v[128:129], 0, s[24:25]
	s_nop 0
	v_fmamk_f32 v130, v242, 0x3a800000, v174
	v_mul_f32_e32 v131, 0x4b800000, v130
	v_cmp_gt_f32_e32 vcc, s54, v130
	v_lshl_add_u64 v[132:133], v[128:129], 0, v[152:153]
	s_nop 0
	v_cndmask_b32_e32 v130, v130, v131, vcc
	v_rsq_f32_e32 v130, v130
	s_nop 0
	v_mul_f32_e32 v128, 0x45800000, v130
	v_cndmask_b32_e32 v128, v130, v128, vcc
	v_pk_mul_f32 v[130:131], v[14:15], v[128:129] op_sel_hi:[1,0]
	v_pk_mul_f32 v[134:135], v[12:13], v[128:129] op_sel_hi:[1,0]
	v_pk_mul_f32 v[136:137], v[10:11], v[128:129] op_sel_hi:[1,0]
	v_pk_mul_f32 v[138:139], v[8:9], v[128:129] op_sel_hi:[1,0]
	v_pk_mul_f32 v[140:141], v[6:7], v[128:129] op_sel_hi:[1,0]
	v_pk_mul_f32 v[142:143], v[4:5], v[128:129] op_sel_hi:[1,0]
	v_pk_mul_f32 v[166:167], v[2:3], v[128:129] op_sel_hi:[1,0]
	v_pk_mul_f32 v[168:169], v[0:1], v[128:129] op_sel_hi:[1,0]
	v_cvt_pk_bf16_f32 v128, v134, v135
	v_cvt_pk_bf16_f32 v129, v130, v131
	v_cvt_pk_bf16_f32 v130, v138, v139
	v_cvt_pk_bf16_f32 v131, v136, v137
	global_store_dwordx4 v[132:133], v[128:131], off
	s_nop 1
	v_cvt_pk_bf16_f32 v128, v142, v143
	v_cvt_pk_bf16_f32 v129, v140, v141
	v_cvt_pk_bf16_f32 v130, v168, v169
	v_cvt_pk_bf16_f32 v131, v166, v167
	global_store_dwordx4 v[132:133], v[128:131], off offset:256

;     __device__ __forceinline__ void operator()(const f32x4 (&acc)[2][2][4][2], const pg8::Unit& u, int wr, int wc, int fr, int fq) const {
;     ...
;             const float* w = (u.pn < 2) ? qw : kw; const float sc = (u.pn < 2) ? 0.125f * LOG2E : 1.f;
;             f32x4 wv[2][2];
; #pragma unroll
;             for (int bj = 0; bj < 2; ++bj)
; #pragma unroll
;                 for (int n = 0; n < 2; ++n) wv[bj][n] = *(const f32x4*)(w + 32 * bj + 8 * fq + 4 * n);
; #pragma unroll
;             for (int ai = 0; ai < 2; ++ai)
; #pragma unroll
;                 for (int m = 0; m < 4; ++m) {
;                     const int row = row0 + ai * 128 + m * 16;
;                     const float rs = rsqrtf(sumsq[row] * (1.f / 1024.f) + EPS);
;                     f32x4 v[2][2]; float ss = 0.f;
; #pragma unroll
;                     for (int bj = 0; bj < 2; ++bj)
; #pragma unroll
;                         for (int n = 0; n < 2; ++n) { v[bj][n] = acc[ai][bj][m][n] * rs; ss += (v[bj][n][0] * v[bj][n][0] + v[bj][n][1] * v[bj][n][1]) + (v[bj][n][2] * v[bj][n][2] + v[bj][n][3] * v[bj][n][3]); }
;                     ss += __shfl_xor(ss, 16); ss += __shfl_xor(ss, 32);
;                     const float r = rsqrtf(ss * (1.f / 64.f) + EPS) * sc;
.LBB0_387:
	v_readlane_b32 s0, v235, 2
	v_ashrrev_i32_e32 v165, 31, v164
	v_readlane_b32 s2, v235, 4
	v_readlane_b32 s3, v235, 5
	s_cmp_lt_i32 s57, 2
	v_readlane_b32 s1, v235, 3
	v_lshl_add_u64 v[166:167], v[164:165], 2, s[2:3]
	global_load_dword v179, v[166:167], off
	global_load_dword v236, v[166:167], off offset:64
	global_load_dword v237, v[166:167], off offset:128
	global_load_dword v238, v[166:167], off offset:192
	global_load_dword v239, v[166:167], off offset:512
	global_load_dword v240, v[166:167], off offset:576
	global_load_dword v241, v[166:167], off offset:640
	global_load_dword v242, v[166:167], off offset:704
	s_cselect_b64 vcc, -1, 0
	v_readlane_b32 s60, v235, 14
	s_and_b64 s[0:1], vcc, exec
	v_readlane_b32 s61, v235, 15
	v_lshlrev_b32_e32 v128, 2, v154
	s_cselect_b32 s1, s27, s61
	s_cselect_b32 s0, s26, s60
	global_load_dwordx4 v[140:143], v128, s[0:1]
	global_load_dwordx4 v[136:139], v128, s[0:1] offset:16
	global_load_dwordx4 v[132:135], v128, s[0:1] offset:128
	s_nop 0
	global_load_dwordx4 v[128:131], v128, s[0:1] offset:144
	v_and_b32_e32 v178, 64, v176
	v_xor_b32_e32 v177, 16, v176
	v_add_u32_e32 v178, 64, v178
	v_cndmask_b32_e32 v165, 1.0, v175, vcc
	v_xor_b32_e32 v182, 32, v176
	v_cmp_lt_i32_e32 vcc, v177, v178
	v_readlane_b32 s0, v235, 33
	v_readlane_b32 s1, v235, 34
	v_cndmask_b32_e32 v177, v176, v177, vcc
	v_cmp_lt_i32_e32 vcc, v182, v178
	v_lshlrev_b32_e32 v178, 2, v177
	v_mov_b64_e32 v[168:169], s[0:1]
	v_cndmask_b32_e32 v182, v176, v182, vcc
	v_lshlrev_b32_e32 v177, 2, v182
	v_mad_i64_i32 v[180:181], s[0:1], v164, s55, v[168:169]
	s_lshl_b32 s0, s57, 8
	s_ashr_i32 s1, s0, 31
	s_lshl_b64 s[0:1], s[0:1], 1
	v_lshl_add_u64 v[180:181], v[180:181], 0, s[0:1]
	v_lshlrev_b32_e32 v152, 1, v154
	v_lshl_add_u64 v[180:181], v[180:181], 0, s[12:13]
	v_lshl_add_u64 v[180:181], v[180:181], 0, v[152:153]
	v_readlane_b32 s62, v235, 16
	v_readlane_b32 s63, v235, 17
	v_readlane_b32 s64, v235, 18
	v_readlane_b32 s65, v235, 19
	v_readlane_b32 s66, v235, 20
	v_readlane_b32 s67, v235, 21
	v_readlane_b32 s68, v235, 22
	v_readlane_b32 s69, v235, 23
	v_readlane_b32 s70, v235, 24
	v_readlane_b32 s71, v235, 25
	v_readlane_b32 s72, v235, 26
	v_readlane_b32 s73, v235, 27
	v_readlane_b32 s74, v235, 28
	v_readlane_b32 s75, v235, 29
	s_waitcnt vmcnt(0)
	v_fmamk_f32 v179, v179, 0x3a800000, v174
	v_mul_f32_e32 v182, 0x4b800000, v179
	v_cmp_gt_f32_e32 vcc, s54, v179
	s_nop 1
	v_cndmask_b32_e32 v179, v179, v182, vcc
	v_rsq_f32_e32 v179, v179
	s_nop 0
	v_mul_f32_e32 v182, 0x45800000, v179
	v_cndmask_b32_e32 v182, v179, v182, vcc
	v_pk_mul_f32 v[124:125], v[124:125], v[182:183] op_sel_hi:[1,0]
	v_pk_mul_f32 v[126:127], v[126:127], v[182:183] op_sel_hi:[1,0]
	v_pk_mul_f32 v[120:121], v[120:121], v[182:183] op_sel_hi:[1,0]
	v_pk_mul_f32 v[122:123], v[122:123], v[182:183] op_sel_hi:[1,0]
	v_pk_mul_f32 v[118:119], v[118:119], v[182:183] op_sel_hi:[1,0]
	v_pk_mul_f32 v[116:117], v[116:117], v[182:183] op_sel_hi:[1,0]
	v_pk_mul_f32 v[114:115], v[114:115], v[182:183] op_sel_hi:[1,0]
	v_pk_mul_f32 v[112:113], v[112:113], v[182:183] op_sel_hi:[1,0]
	v_pk_mul_f32 v[182:183], v[126:127], v[126:127]
	v_pk_mul_f32 v[184:185], v[124:125], v[124:125]
	v_pk_mul_f32 v[186:187], v[122:123], v[122:123]
	v_pk_mul_f32 v[192:193], v[120:121], v[120:121]
	v_pk_mov_b32 v[196:197], v[184:185], v[182:183] op_sel:[1,0]
	v_mov_b32_e32 v185, v183
	v_pk_mov_b32 v[182:183], v[192:193], v[186:187] op_sel:[1,0]
	v_mov_b32_e32 v193, v187
	v_mul_f32_e32 v188, v116, v116
	v_mul_f32_e32 v194, v118, v118
	v_pk_add_f32 v[184:185], v[196:197], v[184:185]
	v_pk_add_f32 v[182:183], v[182:183], v[192:193]
	v_pk_fma_f32 v[186:187], v[116:117], v[116:117], v[188:189] op_sel_hi:[1,1,0]
	v_pk_fma_f32 v[194:195], v[118:119], v[118:119], v[194:195] op_sel_hi:[1,1,0]
	v_pk_add_f32 v[184:185], v[184:185], v[184:185] op_sel_hi:[0,1]
	v_pk_add_f32 v[182:183], v[182:183], v[182:183] op_sel_hi:[0,1]
	v_mul_f32_e32 v186, v112, v112
	v_mul_f32_e32 v194, v113, v113
	v_mul_f32_e32 v184, v114, v114
	v_mul_f32_e32 v182, v115, v115
	v_pk_add_f32 v[186:187], v[186:187], v[194:195]
	v_pk_add_f32 v[182:183], v[184:185], v[182:183]
	v_pk_mul_f32 v[124:125], v[140:141], v[124:125]
	v_pk_add_f32 v[182:183], v[186:187], v[182:183]
	v_pk_mul_f32 v[126:127], v[142:143], v[126:127]
	v_add_f32_e32 v179, v182, v183
	ds_bpermute_b32 v182, v178, v179
	v_pk_mul_f32 v[120:121], v[136:137], v[120:121]
	v_pk_mul_f32 v[122:123], v[138:139], v[122:123]
	v_pk_mul_f32 v[116:117], v[132:133], v[116:117]
	v_pk_mul_f32 v[118:119], v[134:135], v[118:119]
	s_waitcnt lgkmcnt(0)
	v_add_f32_e32 v179, v179, v182
	ds_bpermute_b32 v182, v177, v179
	v_pk_mul_f32 v[112:113], v[128:129], v[112:113]
	v_pk_mul_f32 v[114:115], v[130:131], v[114:115]
	s_waitcnt lgkmcnt(0)
; __device__ __forceinline__ unsigned pk2(float lo, float hi) { return pg8::cvt_pk_bf16(lo, hi); }
;     __device__ __forceinline__ void operator()(const f32x4 (&acc)[2][2][4][2], const pg8::Unit& u, int wr, int wc, int fr, int fq) const {
;     ...
;                 for (int m = 0; m < 4; ++m) {
;                     const int row = row0 + ai * 128 + m * 16;
;                     const float rs = rsqrtf(sumsq[row] * (1.f / 1024.f) + EPS);
;                     f32x4 v[2][2]; float ss = 0.f;
; #pragma unroll
;                     for (int bj = 0; bj < 2; ++bj)
; #pragma unroll
;                         for (int n = 0; n < 2; ++n) { v[bj][n] = acc[ai][bj][m][n] * rs; ss += (v[bj][n][0] * v[bj][n][0] + v[bj][n][1] * v[bj][n][1]) + (v[bj][n][2] * v[bj][n][2] + v[bj][n][3] * v[bj][n][3]); }
;                     ss += __shfl_xor(ss, 16); ss += __shfl_xor(ss, 32);
;                     const float r = rsqrtf(ss * (1.f / 64.f) + EPS) * sc;
; #pragma unroll
;                     for (int bj = 0; bj < 2; ++bj) {
;                         const f32x4 a = v[bj][0] * wv[bj][0] * r, b = v[bj][1] * wv[bj][1] * r;
;                         u32x4 o; o.x = pk2(a[0], a[1]); o.y = pk2(a[2], a[3]); o.z = pk2(b[0], b[1]); o.w = pk2(b[2], b[3]);
;                         *(u32x4*)(P + (size_t)row * PW + u.pn * 256 + 64 * wc + 32 * bj + 8 * fq) = o;
;                     }
	v_add_f32_e32 v179, v179, v182
	v_fmamk_f32 v179, v179, 0x3c800000, v174
	v_mul_f32_e32 v182, 0x4b800000, v179
	v_cmp_gt_f32_e32 vcc, s54, v179
	s_nop 1
	v_cndmask_b32_e32 v179, v179, v182, vcc
	v_rsq_f32_e32 v179, v179
	s_nop 0
	v_mul_f32_e32 v182, 0x45800000, v179
	v_cndmask_b32_e32 v179, v179, v182, vcc
	v_mul_f32_e32 v182, v165, v179
	v_pk_mul_f32 v[126:127], v[126:127], v[182:183] op_sel_hi:[1,0]
	v_pk_mul_f32 v[124:125], v[124:125], v[182:183] op_sel_hi:[1,0]
	v_pk_mul_f32 v[122:123], v[122:123], v[182:183] op_sel_hi:[1,0]
	v_pk_mul_f32 v[120:121], v[120:121], v[182:183] op_sel_hi:[1,0]
	v_pk_mul_f32 v[118:119], v[118:119], v[182:183] op_sel_hi:[1,0]
	v_pk_mul_f32 v[116:117], v[116:117], v[182:183] op_sel_hi:[1,0]
	v_pk_mul_f32 v[184:185], v[114:115], v[182:183] op_sel_hi:[1,0]
	v_pk_mul_f32 v[182:183], v[112:113], v[182:183] op_sel_hi:[1,0]
	v_cvt_pk_bf16_f32 v112, v124, v125
	v_cvt_pk_bf16_f32 v113, v126, v127
	v_cvt_pk_bf16_f32 v114, v120, v121
	v_cvt_pk_bf16_f32 v115, v122, v123
	global_store_dwordx4 v[180:181], v[112:115], off
	s_nop 1
	v_cvt_pk_bf16_f32 v112, v116, v117
	v_cvt_pk_bf16_f32 v113, v118, v119
	v_cvt_pk_bf16_f32 v114, v182, v183
	v_cvt_pk_bf16_f32 v115, v184, v185
	global_store_dwordx4 v[180:181], v[112:115], off offset:64
	s_nop 0
	s_nop 0
	v_fmamk_f32 v112, v236, 0x3a800000, v174
	v_mul_f32_e32 v113, 0x4b800000, v112
	v_cmp_gt_f32_e32 vcc, s54, v112
	s_nop 1
	v_cndmask_b32_e32 v112, v112, v113, vcc
	v_rsq_f32_e32 v114, v112
	v_or_b32_e32 v112, 16, v164
	v_mad_i64_i32 v[112:113], s[2:3], v112, s55, v[168:169]
	v_mul_f32_e32 v115, 0x45800000, v114
	v_cndmask_b32_e32 v114, v114, v115, vcc
	v_pk_mul_f32 v[108:109], v[108:109], v[114:115] op_sel_hi:[1,0]
	v_pk_mul_f32 v[110:111], v[110:111], v[114:115] op_sel_hi:[1,0]
	v_pk_mul_f32 v[104:105], v[104:105], v[114:115] op_sel_hi:[1,0]
	v_pk_mul_f32 v[106:107], v[106:107], v[114:115] op_sel_hi:[1,0]
	v_pk_mul_f32 v[102:103], v[102:103], v[114:115] op_sel_hi:[1,0]
	v_pk_mul_f32 v[100:101], v[100:101], v[114:115] op_sel_hi:[1,0]
	v_pk_mul_f32 v[98:99], v[98:99], v[114:115] op_sel_hi:[1,0]
	v_pk_mul_f32 v[96:97], v[96:97], v[114:115] op_sel_hi:[1,0]
	v_pk_mul_f32 v[114:115], v[110:111], v[110:111]
	v_pk_mul_f32 v[116:117], v[108:109], v[108:109]
	v_pk_mul_f32 v[118:119], v[106:107], v[106:107]
	v_pk_mul_f32 v[120:121], v[104:105], v[104:105]
	v_pk_mov_b32 v[126:127], v[116:117], v[114:115] op_sel:[1,0]
	v_mov_b32_e32 v117, v115
	v_pk_mov_b32 v[114:115], v[120:121], v[118:119] op_sel:[1,0]
	v_mov_b32_e32 v121, v119
	v_mul_f32_e32 v122, v100, v100
	v_mul_f32_e32 v124, v102, v102
	v_pk_add_f32 v[116:117], v[126:127], v[116:117]
	v_pk_add_f32 v[114:115], v[114:115], v[120:121]
	v_pk_fma_f32 v[118:119], v[100:101], v[100:101], v[122:123] op_sel_hi:[1,1,0]
	v_pk_fma_f32 v[122:123], v[102:103], v[102:103], v[124:125] op_sel_hi:[1,1,0]
	v_pk_add_f32 v[116:117], v[116:117], v[116:117] op_sel_hi:[0,1]
	v_pk_add_f32 v[114:115], v[114:115], v[114:115] op_sel_hi:[0,1]
	v_mul_f32_e32 v118, v96, v96
	v_mul_f32_e32 v122, v97, v97
	v_mul_f32_e32 v116, v98, v98
	v_mul_f32_e32 v114, v99, v99
	v_pk_add_f32 v[118:119], v[118:119], v[122:123]
	v_pk_add_f32 v[114:115], v[116:117], v[114:115]
	v_lshl_add_u64 v[112:113], v[112:113], 0, s[0:1]
	v_pk_add_f32 v[114:115], v[118:119], v[114:115]
	v_lshl_add_u64 v[112:113], v[112:113], 0, s[12:13]
	v_add_f32_e32 v114, v114, v115
	ds_bpermute_b32 v115, v178, v114
	v_pk_mul_f32 v[108:109], v[140:141], v[108:109]
	v_pk_mul_f32 v[110:111], v[142:143], v[110:111]
	v_pk_mul_f32 v[104:105], v[136:137], v[104:105]
	v_pk_mul_f32 v[106:107], v[138:139], v[106:107]
	s_waitcnt lgkmcnt(0)
	v_add_f32_e32 v114, v114, v115
	ds_bpermute_b32 v115, v177, v114
	v_pk_mul_f32 v[100:101], v[132:133], v[100:101]
	v_pk_mul_f32 v[102:103], v[134:135], v[102:103]
	v_pk_mul_f32 v[96:97], v[128:129], v[96:97]
	v_pk_mul_f32 v[98:99], v[130:131], v[98:99]
	s_waitcnt lgkmcnt(0)
	v_add_f32_e32 v114, v114, v115
	v_fmamk_f32 v114, v114, 0x3c800000, v174
	v_mul_f32_e32 v115, 0x4b800000, v114
	v_cmp_gt_f32_e32 vcc, s54, v114
	v_lshl_add_u64 v[112:113], v[112:113], 0, v[152:153]
	s_nop 0
	v_cndmask_b32_e32 v114, v114, v115, vcc
	v_rsq_f32_e32 v114, v114
	s_nop 0
	v_mul_f32_e32 v115, 0x45800000, v114
	v_cndmask_b32_e32 v114, v114, v115, vcc
	v_mul_f32_e32 v114, v165, v114
	v_pk_mul_f32 v[110:111], v[110:111], v[114:115] op_sel_hi:[1,0]
	v_pk_mul_f32 v[108:109], v[108:109], v[114:115] op_sel_hi:[1,0]
	v_pk_mul_f32 v[106:107], v[106:107], v[114:115] op_sel_hi:[1,0]
	v_pk_mul_f32 v[104:105], v[104:105], v[114:115] op_sel_hi:[1,0]
	v_pk_mul_f32 v[102:103], v[102:103], v[114:115] op_sel_hi:[1,0]
	v_pk_mul_f32 v[100:101], v[100:101], v[114:115] op_sel_hi:[1,0]
	v_pk_mul_f32 v[116:117], v[98:99], v[114:115] op_sel_hi:[1,0]
	v_pk_mul_f32 v[114:115], v[96:97], v[114:115] op_sel_hi:[1,0]
	v_cvt_pk_bf16_f32 v96, v108, v109
	v_cvt_pk_bf16_f32 v97, v110, v111
	v_cvt_pk_bf16_f32 v98, v104, v105
	v_cvt_pk_bf16_f32 v99, v106, v107
	global_store_dwordx4 v[112:113], v[96:99], off
	s_nop 1
	v_cvt_pk_bf16_f32 v96, v100, v101
	v_cvt_pk_bf16_f32 v97, v102, v103
	v_cvt_pk_bf16_f32 v98, v114, v115
	v_cvt_pk_bf16_f32 v99, v116, v117
	global_store_dwordx4 v[112:113], v[96:99], off offset:64
	s_nop 0
	s_nop 0
	v_fmamk_f32 v96, v237, 0x3a800000, v174
	v_mul_f32_e32 v97, 0x4b800000, v96
	v_cmp_gt_f32_e32 vcc, s54, v96
	s_nop 1
	v_cndmask_b32_e32 v96, v96, v97, vcc
	v_rsq_f32_e32 v98, v96
	v_or_b32_e32 v96, 32, v164
	v_mad_i64_i32 v[96:97], s[2:3], v96, s55, v[168:169]
	v_mul_f32_e32 v99, 0x45800000, v98
	v_cndmask_b32_e32 v98, v98, v99, vcc
	v_pk_mul_f32 v[92:93], v[92:93], v[98:99] op_sel_hi:[1,0]
; __device__ __forceinline__ unsigned pk2(float lo, float hi) { return pg8::cvt_pk_bf16(lo, hi); }
;     __device__ __forceinline__ void operator()(const f32x4 (&acc)[2][2][4][2], const pg8::Unit& u, int wr, int wc, int fr, int fq) const {
;     ...
;                 for (int m = 0; m < 4; ++m) {
;                     const int row = row0 + ai * 128 + m * 16;
;                     const float rs = rsqrtf(sumsq[row] * (1.f / 1024.f) + EPS);
;                     f32x4 v[2][2]; float ss = 0.f;
; #pragma unroll
;                     for (int bj = 0; bj < 2; ++bj)
; #pragma unroll
;                         for (int n = 0; n < 2; ++n) { v[bj][n] = acc[ai][bj][m][n] * rs; ss += (v[bj][n][0] * v[bj][n][0] + v[bj][n][1] * v[bj][n][1]) + (v[bj][n][2] * v[bj][n][2] + v[bj][n][3] * v[bj][n][3]); }
;                     ss += __shfl_xor(ss, 16); ss += __shfl_xor(ss, 32);
;                     const float r = rsqrtf(ss * (1.f / 64.f) + EPS) * sc;
; #pragma unroll
;                     for (int bj = 0; bj < 2; ++bj) {
;                         const f32x4 a = v[bj][0] * wv[bj][0] * r, b = v[bj][1] * wv[bj][1] * r;
;                         u32x4 o; o.x = pk2(a[0], a[1]); o.y = pk2(a[2], a[3]); o.z = pk2(b[0], b[1]); o.w = pk2(b[2], b[3]);
;                         *(u32x4*)(P + (size_t)row * PW + u.pn * 256 + 64 * wc + 32 * bj + 8 * fq) = o;
;                     }
	v_pk_mul_f32 v[94:95], v[94:95], v[98:99] op_sel_hi:[1,0]
	v_pk_mul_f32 v[88:89], v[88:89], v[98:99] op_sel_hi:[1,0]
	v_pk_mul_f32 v[90:91], v[90:91], v[98:99] op_sel_hi:[1,0]
	v_pk_mul_f32 v[86:87], v[86:87], v[98:99] op_sel_hi:[1,0]
	v_pk_mul_f32 v[84:85], v[84:85], v[98:99] op_sel_hi:[1,0]
	v_pk_mul_f32 v[82:83], v[82:83], v[98:99] op_sel_hi:[1,0]
	v_pk_mul_f32 v[80:81], v[80:81], v[98:99] op_sel_hi:[1,0]
	v_pk_mul_f32 v[98:99], v[94:95], v[94:95]
	v_pk_mul_f32 v[100:101], v[92:93], v[92:93]
	v_pk_mul_f32 v[102:103], v[90:91], v[90:91]
	v_pk_mul_f32 v[104:105], v[88:89], v[88:89]
	v_pk_mov_b32 v[110:111], v[100:101], v[98:99] op_sel:[1,0]
	v_mov_b32_e32 v101, v99
	v_pk_mov_b32 v[98:99], v[104:105], v[102:103] op_sel:[1,0]
	v_mov_b32_e32 v105, v103
	v_mul_f32_e32 v106, v84, v84
	v_mul_f32_e32 v108, v86, v86
	v_pk_add_f32 v[100:101], v[110:111], v[100:101]
	v_pk_add_f32 v[98:99], v[98:99], v[104:105]
	v_pk_fma_f32 v[102:103], v[84:85], v[84:85], v[106:107] op_sel_hi:[1,1,0]
	v_pk_fma_f32 v[106:107], v[86:87], v[86:87], v[108:109] op_sel_hi:[1,1,0]
	v_pk_add_f32 v[100:101], v[100:101], v[100:101] op_sel_hi:[0,1]
	v_pk_add_f32 v[98:99], v[98:99], v[98:99] op_sel_hi:[0,1]
	v_mul_f32_e32 v102, v80, v80
	v_mul_f32_e32 v106, v81, v81
	v_mul_f32_e32 v100, v82, v82
	v_mul_f32_e32 v98, v83, v83
	v_pk_add_f32 v[102:103], v[102:103], v[106:107]
	v_pk_add_f32 v[98:99], v[100:101], v[98:99]
	v_lshl_add_u64 v[96:97], v[96:97], 0, s[0:1]
	v_pk_add_f32 v[98:99], v[102:103], v[98:99]
	v_lshl_add_u64 v[96:97], v[96:97], 0, s[12:13]
	v_add_f32_e32 v98, v98, v99
	ds_bpermute_b32 v99, v178, v98
	v_pk_mul_f32 v[92:93], v[140:141], v[92:93]
	v_pk_mul_f32 v[94:95], v[142:143], v[94:95]
	v_pk_mul_f32 v[88:89], v[136:137], v[88:89]
	v_pk_mul_f32 v[90:91], v[138:139], v[90:91]
	s_waitcnt lgkmcnt(0)
	v_add_f32_e32 v98, v98, v99
	ds_bpermute_b32 v99, v177, v98
	v_pk_mul_f32 v[84:85], v[132:133], v[84:85]
	v_pk_mul_f32 v[86:87], v[134:135], v[86:87]
	v_pk_mul_f32 v[80:81], v[128:129], v[80:81]
	v_pk_mul_f32 v[82:83], v[130:131], v[82:83]
	s_waitcnt lgkmcnt(0)
	v_add_f32_e32 v98, v98, v99
	v_fmamk_f32 v98, v98, 0x3c800000, v174
	v_mul_f32_e32 v99, 0x4b800000, v98
	v_cmp_gt_f32_e32 vcc, s54, v98
	v_lshl_add_u64 v[96:97], v[96:97], 0, v[152:153]
	s_nop 0
	v_cndmask_b32_e32 v98, v98, v99, vcc
	v_rsq_f32_e32 v98, v98
	s_nop 0
	v_mul_f32_e32 v99, 0x45800000, v98
	v_cndmask_b32_e32 v98, v98, v99, vcc
	v_mul_f32_e32 v98, v165, v98
	v_pk_mul_f32 v[94:95], v[94:95], v[98:99] op_sel_hi:[1,0]
	v_pk_mul_f32 v[92:93], v[92:93], v[98:99] op_sel_hi:[1,0]
	v_pk_mul_f32 v[90:91], v[90:91], v[98:99] op_sel_hi:[1,0]
	v_pk_mul_f32 v[88:89], v[88:89], v[98:99] op_sel_hi:[1,0]
	v_pk_mul_f32 v[86:87], v[86:87], v[98:99] op_sel_hi:[1,0]
	v_pk_mul_f32 v[84:85], v[84:85], v[98:99] op_sel_hi:[1,0]
	v_pk_mul_f32 v[100:101], v[82:83], v[98:99] op_sel_hi:[1,0]
	v_pk_mul_f32 v[98:99], v[80:81], v[98:99] op_sel_hi:[1,0]
	v_cvt_pk_bf16_f32 v80, v92, v93
	v_cvt_pk_bf16_f32 v81, v94, v95
	v_cvt_pk_bf16_f32 v82, v88, v89
	v_cvt_pk_bf16_f32 v83, v90, v91
	global_store_dwordx4 v[96:97], v[80:83], off
	s_nop 1
	v_cvt_pk_bf16_f32 v80, v84, v85
	v_cvt_pk_bf16_f32 v81, v86, v87
	v_cvt_pk_bf16_f32 v82, v98, v99
	v_cvt_pk_bf16_f32 v83, v100, v101
	global_store_dwordx4 v[96:97], v[80:83], off offset:64
	s_nop 0
	s_nop 0
	v_fmamk_f32 v80, v238, 0x3a800000, v174
	v_mul_f32_e32 v81, 0x4b800000, v80
	v_cmp_gt_f32_e32 vcc, s54, v80
	s_nop 1
	v_cndmask_b32_e32 v80, v80, v81, vcc
	v_rsq_f32_e32 v82, v80
	v_or_b32_e32 v80, 48, v164
	v_mad_i64_i32 v[80:81], s[2:3], v80, s55, v[168:169]
	v_mul_f32_e32 v83, 0x45800000, v82
	v_cndmask_b32_e32 v82, v82, v83, vcc
	v_pk_mul_f32 v[76:77], v[76:77], v[82:83] op_sel_hi:[1,0]
	v_pk_mul_f32 v[78:79], v[78:79], v[82:83] op_sel_hi:[1,0]
	v_pk_mul_f32 v[72:73], v[72:73], v[82:83] op_sel_hi:[1,0]
	v_pk_mul_f32 v[74:75], v[74:75], v[82:83] op_sel_hi:[1,0]
	v_pk_mul_f32 v[70:71], v[70:71], v[82:83] op_sel_hi:[1,0]
	v_pk_mul_f32 v[68:69], v[68:69], v[82:83] op_sel_hi:[1,0]
	v_pk_mul_f32 v[66:67], v[66:67], v[82:83] op_sel_hi:[1,0]
	v_pk_mul_f32 v[64:65], v[64:65], v[82:83] op_sel_hi:[1,0]
	v_pk_mul_f32 v[82:83], v[78:79], v[78:79]
	v_pk_mul_f32 v[84:85], v[76:77], v[76:77]
	v_pk_mul_f32 v[86:87], v[74:75], v[74:75]
	v_pk_mul_f32 v[88:89], v[72:73], v[72:73]
	v_pk_mov_b32 v[94:95], v[84:85], v[82:83] op_sel:[1,0]
	v_mov_b32_e32 v85, v83
	v_pk_mov_b32 v[82:83], v[88:89], v[86:87] op_sel:[1,0]
	v_mov_b32_e32 v89, v87
	v_mul_f32_e32 v90, v68, v68
	v_mul_f32_e32 v92, v70, v70
	v_pk_add_f32 v[84:85], v[94:95], v[84:85]
	v_pk_add_f32 v[82:83], v[82:83], v[88:89]
	v_pk_fma_f32 v[86:87], v[68:69], v[68:69], v[90:91] op_sel_hi:[1,1,0]
	v_pk_fma_f32 v[90:91], v[70:71], v[70:71], v[92:93] op_sel_hi:[1,1,0]
	v_pk_add_f32 v[84:85], v[84:85], v[84:85] op_sel_hi:[0,1]
	v_pk_add_f32 v[82:83], v[82:83], v[82:83] op_sel_hi:[0,1]
	v_mul_f32_e32 v86, v64, v64
	v_mul_f32_e32 v90, v65, v65
	v_mul_f32_e32 v84, v66, v66
	v_mul_f32_e32 v82, v67, v67
	v_pk_add_f32 v[86:87], v[86:87], v[90:91]
	v_pk_add_f32 v[82:83], v[84:85], v[82:83]
	v_lshl_add_u64 v[80:81], v[80:81], 0, s[0:1]
	v_pk_add_f32 v[82:83], v[86:87], v[82:83]
	v_lshl_add_u64 v[80:81], v[80:81], 0, s[12:13]
	v_add_f32_e32 v82, v82, v83
	ds_bpermute_b32 v83, v178, v82
	v_pk_mul_f32 v[76:77], v[140:141], v[76:77]
	v_pk_mul_f32 v[78:79], v[142:143], v[78:79]
	v_pk_mul_f32 v[72:73], v[136:137], v[72:73]
	v_pk_mul_f32 v[74:75], v[138:139], v[74:75]
	s_waitcnt lgkmcnt(0)
	v_add_f32_e32 v82, v82, v83
	ds_bpermute_b32 v83, v177, v82
	v_pk_mul_f32 v[68:69], v[132:133], v[68:69]
	v_pk_mul_f32 v[70:71], v[134:135], v[70:71]
	v_pk_mul_f32 v[64:65], v[128:129], v[64:65]
	v_pk_mul_f32 v[66:67], v[130:131], v[66:67]
	s_waitcnt lgkmcnt(0)
; __device__ __forceinline__ unsigned pk2(float lo, float hi) { return pg8::cvt_pk_bf16(lo, hi); }
;     __device__ __forceinline__ void operator()(const f32x4 (&acc)[2][2][4][2], const pg8::Unit& u, int wr, int wc, int fr, int fq) const {
;     ...
;                 for (int m = 0; m < 4; ++m) {
;                     const int row = row0 + ai * 128 + m * 16;
;                     const float rs = rsqrtf(sumsq[row] * (1.f / 1024.f) + EPS);
;                     f32x4 v[2][2]; float ss = 0.f;
; #pragma unroll
;                     for (int bj = 0; bj < 2; ++bj)
; #pragma unroll
;                         for (int n = 0; n < 2; ++n) { v[bj][n] = acc[ai][bj][m][n] * rs; ss += (v[bj][n][0] * v[bj][n][0] + v[bj][n][1] * v[bj][n][1]) + (v[bj][n][2] * v[bj][n][2] + v[bj][n][3] * v[bj][n][3]); }
;                     ss += __shfl_xor(ss, 16); ss += __shfl_xor(ss, 32);
;                     const float r = rsqrtf(ss * (1.f / 64.f) + EPS) * sc;
; #pragma unroll
;                     for (int bj = 0; bj < 2; ++bj) {
;                         const f32x4 a = v[bj][0] * wv[bj][0] * r, b = v[bj][1] * wv[bj][1] * r;
;                         u32x4 o; o.x = pk2(a[0], a[1]); o.y = pk2(a[2], a[3]); o.z = pk2(b[0], b[1]); o.w = pk2(b[2], b[3]);
;                         *(u32x4*)(P + (size_t)row * PW + u.pn * 256 + 64 * wc + 32 * bj + 8 * fq) = o;
;                     }
	v_add_f32_e32 v82, v82, v83
	v_fmamk_f32 v82, v82, 0x3c800000, v174
	v_mul_f32_e32 v83, 0x4b800000, v82
	v_cmp_gt_f32_e32 vcc, s54, v82
	v_lshl_add_u64 v[80:81], v[80:81], 0, v[152:153]
	s_nop 0
	v_cndmask_b32_e32 v82, v82, v83, vcc
	v_rsq_f32_e32 v82, v82
	s_nop 0
	v_mul_f32_e32 v83, 0x45800000, v82
	v_cndmask_b32_e32 v82, v82, v83, vcc
	v_mul_f32_e32 v82, v165, v82
	v_pk_mul_f32 v[78:79], v[78:79], v[82:83] op_sel_hi:[1,0]
	v_pk_mul_f32 v[76:77], v[76:77], v[82:83] op_sel_hi:[1,0]
	v_pk_mul_f32 v[74:75], v[74:75], v[82:83] op_sel_hi:[1,0]
	v_pk_mul_f32 v[72:73], v[72:73], v[82:83] op_sel_hi:[1,0]
	v_pk_mul_f32 v[70:71], v[70:71], v[82:83] op_sel_hi:[1,0]
	v_pk_mul_f32 v[68:69], v[68:69], v[82:83] op_sel_hi:[1,0]
	v_pk_mul_f32 v[84:85], v[66:67], v[82:83] op_sel_hi:[1,0]
	v_pk_mul_f32 v[82:83], v[64:65], v[82:83] op_sel_hi:[1,0]
	v_cvt_pk_bf16_f32 v64, v76, v77
	v_cvt_pk_bf16_f32 v65, v78, v79
	v_cvt_pk_bf16_f32 v66, v72, v73
	v_cvt_pk_bf16_f32 v67, v74, v75
	global_store_dwordx4 v[80:81], v[64:67], off
	s_nop 1
	v_cvt_pk_bf16_f32 v64, v68, v69
	v_cvt_pk_bf16_f32 v65, v70, v71
	v_cvt_pk_bf16_f32 v66, v82, v83
	v_cvt_pk_bf16_f32 v67, v84, v85
	global_store_dwordx4 v[80:81], v[64:67], off offset:64
	s_nop 0
	s_nop 0
	v_fmamk_f32 v64, v239, 0x3a800000, v174
	v_mul_f32_e32 v65, 0x4b800000, v64
	v_cmp_gt_f32_e32 vcc, s54, v64
	s_nop 1
	v_cndmask_b32_e32 v64, v64, v65, vcc
	v_rsq_f32_e32 v66, v64
	v_add_u32_e32 v64, 0x80, v164
	v_mad_i64_i32 v[64:65], s[2:3], v64, s55, v[168:169]
	v_mul_f32_e32 v67, 0x45800000, v66
	v_cndmask_b32_e32 v66, v66, v67, vcc
	v_pk_mul_f32 v[60:61], v[60:61], v[66:67] op_sel_hi:[1,0]
	v_pk_mul_f32 v[62:63], v[62:63], v[66:67] op_sel_hi:[1,0]
	v_pk_mul_f32 v[56:57], v[56:57], v[66:67] op_sel_hi:[1,0]
	v_pk_mul_f32 v[58:59], v[58:59], v[66:67] op_sel_hi:[1,0]
	v_pk_mul_f32 v[54:55], v[54:55], v[66:67] op_sel_hi:[1,0]
	v_pk_mul_f32 v[52:53], v[52:53], v[66:67] op_sel_hi:[1,0]
	v_pk_mul_f32 v[50:51], v[50:51], v[66:67] op_sel_hi:[1,0]
	v_pk_mul_f32 v[48:49], v[48:49], v[66:67] op_sel_hi:[1,0]
	v_pk_mul_f32 v[66:67], v[62:63], v[62:63]
	v_pk_mul_f32 v[68:69], v[60:61], v[60:61]
	v_pk_mul_f32 v[70:71], v[58:59], v[58:59]
	v_pk_mul_f32 v[72:73], v[56:57], v[56:57]
	v_pk_mov_b32 v[78:79], v[68:69], v[66:67] op_sel:[1,0]
	v_mov_b32_e32 v69, v67
	v_pk_mov_b32 v[66:67], v[72:73], v[70:71] op_sel:[1,0]
	v_mov_b32_e32 v73, v71
	v_mul_f32_e32 v74, v52, v52
	v_mul_f32_e32 v76, v54, v54
	v_pk_add_f32 v[68:69], v[78:79], v[68:69]
	v_pk_add_f32 v[66:67], v[66:67], v[72:73]
	v_pk_fma_f32 v[70:71], v[52:53], v[52:53], v[74:75] op_sel_hi:[1,1,0]
	v_pk_fma_f32 v[74:75], v[54:55], v[54:55], v[76:77] op_sel_hi:[1,1,0]
	v_pk_add_f32 v[68:69], v[68:69], v[68:69] op_sel_hi:[0,1]
	v_pk_add_f32 v[66:67], v[66:67], v[66:67] op_sel_hi:[0,1]
	v_mul_f32_e32 v70, v48, v48
	v_mul_f32_e32 v74, v49, v49
	v_mul_f32_e32 v68, v50, v50
	v_mul_f32_e32 v66, v51, v51
	v_pk_add_f32 v[70:71], v[70:71], v[74:75]
	v_pk_add_f32 v[66:67], v[68:69], v[66:67]
	v_lshl_add_u64 v[64:65], v[64:65], 0, s[0:1]
	v_pk_add_f32 v[66:67], v[70:71], v[66:67]
	v_lshl_add_u64 v[64:65], v[64:65], 0, s[12:13]
	v_add_f32_e32 v66, v66, v67
	ds_bpermute_b32 v67, v178, v66
	v_pk_mul_f32 v[60:61], v[140:141], v[60:61]
	v_pk_mul_f32 v[62:63], v[142:143], v[62:63]
	v_pk_mul_f32 v[56:57], v[136:137], v[56:57]
	v_pk_mul_f32 v[58:59], v[138:139], v[58:59]
	s_waitcnt lgkmcnt(0)
	v_add_f32_e32 v66, v66, v67
	ds_bpermute_b32 v67, v177, v66
	v_pk_mul_f32 v[52:53], v[132:133], v[52:53]
	v_pk_mul_f32 v[54:55], v[134:135], v[54:55]
	v_pk_mul_f32 v[48:49], v[128:129], v[48:49]
	v_pk_mul_f32 v[50:51], v[130:131], v[50:51]
	s_waitcnt lgkmcnt(0)
	v_add_f32_e32 v66, v66, v67
	v_fmamk_f32 v66, v66, 0x3c800000, v174
	v_mul_f32_e32 v67, 0x4b800000, v66
	v_cmp_gt_f32_e32 vcc, s54, v66
	v_lshl_add_u64 v[64:65], v[64:65], 0, v[152:153]
	s_nop 0
	v_cndmask_b32_e32 v66, v66, v67, vcc
	v_rsq_f32_e32 v66, v66
	s_nop 0
	v_mul_f32_e32 v67, 0x45800000, v66
	v_cndmask_b32_e32 v66, v66, v67, vcc
	v_mul_f32_e32 v66, v165, v66
	v_pk_mul_f32 v[62:63], v[62:63], v[66:67] op_sel_hi:[1,0]
	v_pk_mul_f32 v[60:61], v[60:61], v[66:67] op_sel_hi:[1,0]
	v_pk_mul_f32 v[58:59], v[58:59], v[66:67] op_sel_hi:[1,0]
	v_pk_mul_f32 v[56:57], v[56:57], v[66:67] op_sel_hi:[1,0]
	v_pk_mul_f32 v[54:55], v[54:55], v[66:67] op_sel_hi:[1,0]
	v_pk_mul_f32 v[52:53], v[52:53], v[66:67] op_sel_hi:[1,0]
	v_pk_mul_f32 v[68:69], v[50:51], v[66:67] op_sel_hi:[1,0]
	v_pk_mul_f32 v[66:67], v[48:49], v[66:67] op_sel_hi:[1,0]
	v_cvt_pk_bf16_f32 v48, v60, v61
	v_cvt_pk_bf16_f32 v49, v62, v63
	v_cvt_pk_bf16_f32 v50, v56, v57
	v_cvt_pk_bf16_f32 v51, v58, v59
	global_store_dwordx4 v[64:65], v[48:51], off
	s_nop 1
	v_cvt_pk_bf16_f32 v48, v52, v53
	v_cvt_pk_bf16_f32 v49, v54, v55
	v_cvt_pk_bf16_f32 v50, v66, v67
	v_cvt_pk_bf16_f32 v51, v68, v69
	global_store_dwordx4 v[64:65], v[48:51], off offset:64
	s_nop 0
	s_nop 0
	v_fmamk_f32 v48, v240, 0x3a800000, v174
	v_mul_f32_e32 v49, 0x4b800000, v48
	v_cmp_gt_f32_e32 vcc, s54, v48
	s_nop 1
	v_cndmask_b32_e32 v48, v48, v49, vcc
	v_rsq_f32_e32 v50, v48
	v_add_u32_e32 v48, 0x90, v164
	v_mad_i64_i32 v[48:49], s[2:3], v48, s55, v[168:169]
	v_mul_f32_e32 v51, 0x45800000, v50
	v_cndmask_b32_e32 v50, v50, v51, vcc
	v_pk_mul_f32 v[44:45], v[44:45], v[50:51] op_sel_hi:[1,0]
	v_pk_mul_f32 v[46:47], v[46:47], v[50:51] op_sel_hi:[1,0]
	v_pk_mul_f32 v[40:41], v[40:41], v[50:51] op_sel_hi:[1,0]
	v_pk_mul_f32 v[42:43], v[42:43], v[50:51] op_sel_hi:[1,0]
	v_pk_mul_f32 v[38:39], v[38:39], v[50:51] op_sel_hi:[1,0]
	v_pk_mul_f32 v[36:37], v[36:37], v[50:51] op_sel_hi:[1,0]
	v_pk_mul_f32 v[34:35], v[34:35], v[50:51] op_sel_hi:[1,0]
	v_pk_mul_f32 v[32:33], v[32:33], v[50:51] op_sel_hi:[1,0]
	v_pk_mul_f32 v[50:51], v[46:47], v[46:47]
	v_pk_mul_f32 v[52:53], v[44:45], v[44:45]
	v_pk_mul_f32 v[54:55], v[42:43], v[42:43]
	v_pk_mul_f32 v[56:57], v[40:41], v[40:41]
	v_pk_mov_b32 v[62:63], v[52:53], v[50:51] op_sel:[1,0]
	v_mov_b32_e32 v53, v51
	v_pk_mov_b32 v[50:51], v[56:57], v[54:55] op_sel:[1,0]
	v_mov_b32_e32 v57, v55
	v_mul_f32_e32 v58, v36, v36
	v_mul_f32_e32 v60, v38, v38
	v_pk_add_f32 v[52:53], v[62:63], v[52:53]
	v_pk_add_f32 v[50:51], v[50:51], v[56:57]
	v_pk_fma_f32 v[54:55], v[36:37], v[36:37], v[58:59] op_sel_hi:[1,1,0]
	v_pk_fma_f32 v[58:59], v[38:39], v[38:39], v[60:61] op_sel_hi:[1,1,0]
	v_pk_add_f32 v[52:53], v[52:53], v[52:53] op_sel_hi:[0,1]
	v_pk_add_f32 v[50:51], v[50:51], v[50:51] op_sel_hi:[0,1]
	v_mul_f32_e32 v54, v32, v32
	v_mul_f32_e32 v58, v33, v33
	v_mul_f32_e32 v52, v34, v34
	v_mul_f32_e32 v50, v35, v35
	v_pk_add_f32 v[54:55], v[54:55], v[58:59]
	v_pk_add_f32 v[50:51], v[52:53], v[50:51]
	v_lshl_add_u64 v[48:49], v[48:49], 0, s[0:1]
	v_pk_add_f32 v[50:51], v[54:55], v[50:51]
	v_lshl_add_u64 v[48:49], v[48:49], 0, s[12:13]
	v_add_f32_e32 v50, v50, v51
	ds_bpermute_b32 v51, v178, v50
	v_pk_mul_f32 v[44:45], v[140:141], v[44:45]
	v_pk_mul_f32 v[46:47], v[142:143], v[46:47]
	v_pk_mul_f32 v[40:41], v[136:137], v[40:41]
	v_pk_mul_f32 v[42:43], v[138:139], v[42:43]
	s_waitcnt lgkmcnt(0)
; __device__ __forceinline__ unsigned pk2(float lo, float hi) { return pg8::cvt_pk_bf16(lo, hi); }
;     __device__ __forceinline__ void operator()(const f32x4 (&acc)[2][2][4][2], const pg8::Unit& u, int wr, int wc, int fr, int fq) const {
;     ...
;                 for (int m = 0; m < 4; ++m) {
;                     const int row = row0 + ai * 128 + m * 16;
;                     const float rs = rsqrtf(sumsq[row] * (1.f / 1024.f) + EPS);
;                     f32x4 v[2][2]; float ss = 0.f;
; #pragma unroll
;                     for (int bj = 0; bj < 2; ++bj)
; #pragma unroll
;                         for (int n = 0; n < 2; ++n) { v[bj][n] = acc[ai][bj][m][n] * rs; ss += (v[bj][n][0] * v[bj][n][0] + v[bj][n][1] * v[bj][n][1]) + (v[bj][n][2] * v[bj][n][2] + v[bj][n][3] * v[bj][n][3]); }
;                     ss += __shfl_xor(ss, 16); ss += __shfl_xor(ss, 32);
;                     const float r = rsqrtf(ss * (1.f / 64.f) + EPS) * sc;
; #pragma unroll
;                     for (int bj = 0; bj < 2; ++bj) {
;                         const f32x4 a = v[bj][0] * wv[bj][0] * r, b = v[bj][1] * wv[bj][1] * r;
;                         u32x4 o; o.x = pk2(a[0], a[1]); o.y = pk2(a[2], a[3]); o.z = pk2(b[0], b[1]); o.w = pk2(b[2], b[3]);
;                         *(u32x4*)(P + (size_t)row * PW + u.pn * 256 + 64 * wc + 32 * bj + 8 * fq) = o;
;                     }
	v_add_f32_e32 v50, v50, v51
	ds_bpermute_b32 v51, v177, v50
	v_pk_mul_f32 v[36:37], v[132:133], v[36:37]
	v_pk_mul_f32 v[38:39], v[134:135], v[38:39]
	v_pk_mul_f32 v[32:33], v[128:129], v[32:33]
	v_pk_mul_f32 v[34:35], v[130:131], v[34:35]
	s_waitcnt lgkmcnt(0)
	v_add_f32_e32 v50, v50, v51
	v_fmamk_f32 v50, v50, 0x3c800000, v174
	v_mul_f32_e32 v51, 0x4b800000, v50
	v_cmp_gt_f32_e32 vcc, s54, v50
	v_lshl_add_u64 v[48:49], v[48:49], 0, v[152:153]
	s_nop 0
	v_cndmask_b32_e32 v50, v50, v51, vcc
	v_rsq_f32_e32 v50, v50
	s_nop 0
	v_mul_f32_e32 v51, 0x45800000, v50
	v_cndmask_b32_e32 v50, v50, v51, vcc
	v_mul_f32_e32 v50, v165, v50
	v_pk_mul_f32 v[46:47], v[46:47], v[50:51] op_sel_hi:[1,0]
	v_pk_mul_f32 v[44:45], v[44:45], v[50:51] op_sel_hi:[1,0]
	v_pk_mul_f32 v[42:43], v[42:43], v[50:51] op_sel_hi:[1,0]
	v_pk_mul_f32 v[40:41], v[40:41], v[50:51] op_sel_hi:[1,0]
	v_pk_mul_f32 v[38:39], v[38:39], v[50:51] op_sel_hi:[1,0]
	v_pk_mul_f32 v[36:37], v[36:37], v[50:51] op_sel_hi:[1,0]
	v_pk_mul_f32 v[52:53], v[34:35], v[50:51] op_sel_hi:[1,0]
	v_pk_mul_f32 v[50:51], v[32:33], v[50:51] op_sel_hi:[1,0]
	v_cvt_pk_bf16_f32 v32, v44, v45
	v_cvt_pk_bf16_f32 v33, v46, v47
	v_cvt_pk_bf16_f32 v34, v40, v41
	v_cvt_pk_bf16_f32 v35, v42, v43
	global_store_dwordx4 v[48:49], v[32:35], off
	s_nop 1
	v_cvt_pk_bf16_f32 v32, v36, v37
	v_cvt_pk_bf16_f32 v33, v38, v39
	v_cvt_pk_bf16_f32 v34, v50, v51
	v_cvt_pk_bf16_f32 v35, v52, v53
	global_store_dwordx4 v[48:49], v[32:35], off offset:64
	s_nop 0
	s_nop 0
	v_fmamk_f32 v32, v241, 0x3a800000, v174
	v_mul_f32_e32 v33, 0x4b800000, v32
	v_cmp_gt_f32_e32 vcc, s54, v32
	s_nop 1
	v_cndmask_b32_e32 v32, v32, v33, vcc
	v_rsq_f32_e32 v34, v32
	v_add_u32_e32 v32, 0xa0, v164
	v_mad_i64_i32 v[32:33], s[2:3], v32, s55, v[168:169]
	v_mul_f32_e32 v35, 0x45800000, v34
	v_cndmask_b32_e32 v34, v34, v35, vcc
	v_pk_mul_f32 v[28:29], v[28:29], v[34:35] op_sel_hi:[1,0]
	v_pk_mul_f32 v[30:31], v[30:31], v[34:35] op_sel_hi:[1,0]
	v_pk_mul_f32 v[24:25], v[24:25], v[34:35] op_sel_hi:[1,0]
	v_pk_mul_f32 v[26:27], v[26:27], v[34:35] op_sel_hi:[1,0]
	v_pk_mul_f32 v[22:23], v[22:23], v[34:35] op_sel_hi:[1,0]
	v_pk_mul_f32 v[20:21], v[20:21], v[34:35] op_sel_hi:[1,0]
	v_pk_mul_f32 v[18:19], v[18:19], v[34:35] op_sel_hi:[1,0]
	v_pk_mul_f32 v[16:17], v[16:17], v[34:35] op_sel_hi:[1,0]
	v_pk_mul_f32 v[34:35], v[30:31], v[30:31]
	v_pk_mul_f32 v[36:37], v[28:29], v[28:29]
	v_pk_mul_f32 v[38:39], v[26:27], v[26:27]
	v_pk_mul_f32 v[40:41], v[24:25], v[24:25]
	v_pk_mov_b32 v[46:47], v[36:37], v[34:35] op_sel:[1,0]
	v_mov_b32_e32 v37, v35
	v_pk_mov_b32 v[34:35], v[40:41], v[38:39] op_sel:[1,0]
	v_mov_b32_e32 v41, v39
	v_mul_f32_e32 v42, v20, v20
	v_mul_f32_e32 v44, v22, v22
	v_pk_add_f32 v[36:37], v[46:47], v[36:37]
	v_pk_add_f32 v[34:35], v[34:35], v[40:41]
	v_pk_fma_f32 v[38:39], v[20:21], v[20:21], v[42:43] op_sel_hi:[1,1,0]
	v_pk_fma_f32 v[42:43], v[22:23], v[22:23], v[44:45] op_sel_hi:[1,1,0]
	v_pk_add_f32 v[36:37], v[36:37], v[36:37] op_sel_hi:[0,1]
	v_pk_add_f32 v[34:35], v[34:35], v[34:35] op_sel_hi:[0,1]
	v_mul_f32_e32 v38, v16, v16
	v_mul_f32_e32 v42, v17, v17
	v_mul_f32_e32 v36, v18, v18
	v_mul_f32_e32 v34, v19, v19
	v_pk_add_f32 v[38:39], v[38:39], v[42:43]
	v_pk_add_f32 v[34:35], v[36:37], v[34:35]
	v_lshl_add_u64 v[32:33], v[32:33], 0, s[0:1]
	v_pk_add_f32 v[34:35], v[38:39], v[34:35]
	v_lshl_add_u64 v[32:33], v[32:33], 0, s[12:13]
	v_add_f32_e32 v34, v34, v35
	ds_bpermute_b32 v35, v178, v34
	v_pk_mul_f32 v[28:29], v[140:141], v[28:29]
	v_pk_mul_f32 v[30:31], v[142:143], v[30:31]
	v_pk_mul_f32 v[24:25], v[136:137], v[24:25]
	v_pk_mul_f32 v[26:27], v[138:139], v[26:27]
	s_waitcnt lgkmcnt(0)
	v_add_f32_e32 v34, v34, v35
	ds_bpermute_b32 v35, v177, v34
	v_pk_mul_f32 v[20:21], v[132:133], v[20:21]
	v_pk_mul_f32 v[22:23], v[134:135], v[22:23]
	v_pk_mul_f32 v[16:17], v[128:129], v[16:17]
	v_pk_mul_f32 v[18:19], v[130:131], v[18:19]
	s_waitcnt lgkmcnt(0)
; __device__ __forceinline__ unsigned pk2(float lo, float hi) { return pg8::cvt_pk_bf16(lo, hi); }
;     __device__ __forceinline__ void operator()(const f32x4 (&acc)[2][2][4][2], const pg8::Unit& u, int wr, int wc, int fr, int fq) const {
;     ...
;                 for (int m = 0; m < 4; ++m) {
;                     const int row = row0 + ai * 128 + m * 16;
;                     const float rs = rsqrtf(sumsq[row] * (1.f / 1024.f) + EPS);
;                     f32x4 v[2][2]; float ss = 0.f;
; #pragma unroll
;                     for (int bj = 0; bj < 2; ++bj)
; #pragma unroll
;                         for (int n = 0; n < 2; ++n) { v[bj][n] = acc[ai][bj][m][n] * rs; ss += (v[bj][n][0] * v[bj][n][0] + v[bj][n][1] * v[bj][n][1]) + (v[bj][n][2] * v[bj][n][2] + v[bj][n][3] * v[bj][n][3]); }
;                     ss += __shfl_xor(ss, 16); ss += __shfl_xor(ss, 32);
;                     const float r = rsqrtf(ss * (1.f / 64.f) + EPS) * sc;
; #pragma unroll
;                     for (int bj = 0; bj < 2; ++bj) {
;                         const f32x4 a = v[bj][0] * wv[bj][0] * r, b = v[bj][1] * wv[bj][1] * r;
;                         u32x4 o; o.x = pk2(a[0], a[1]); o.y = pk2(a[2], a[3]); o.z = pk2(b[0], b[1]); o.w = pk2(b[2], b[3]);
;                         *(u32x4*)(P + (size_t)row * PW + u.pn * 256 + 64 * wc + 32 * bj + 8 * fq) = o;
;                     }
	v_add_f32_e32 v34, v34, v35
	v_fmamk_f32 v34, v34, 0x3c800000, v174
	v_mul_f32_e32 v35, 0x4b800000, v34
	v_cmp_gt_f32_e32 vcc, s54, v34
	v_lshl_add_u64 v[32:33], v[32:33], 0, v[152:153]
	s_nop 0
	v_cndmask_b32_e32 v34, v34, v35, vcc
	v_rsq_f32_e32 v34, v34
	s_nop 0
	v_mul_f32_e32 v35, 0x45800000, v34
	v_cndmask_b32_e32 v34, v34, v35, vcc
	v_mul_f32_e32 v34, v165, v34
	v_pk_mul_f32 v[30:31], v[30:31], v[34:35] op_sel_hi:[1,0]
	v_pk_mul_f32 v[28:29], v[28:29], v[34:35] op_sel_hi:[1,0]
	v_pk_mul_f32 v[26:27], v[26:27], v[34:35] op_sel_hi:[1,0]
	v_pk_mul_f32 v[24:25], v[24:25], v[34:35] op_sel_hi:[1,0]
	v_pk_mul_f32 v[22:23], v[22:23], v[34:35] op_sel_hi:[1,0]
	v_pk_mul_f32 v[20:21], v[20:21], v[34:35] op_sel_hi:[1,0]
	v_pk_mul_f32 v[36:37], v[18:19], v[34:35] op_sel_hi:[1,0]
	v_pk_mul_f32 v[34:35], v[16:17], v[34:35] op_sel_hi:[1,0]
	v_cvt_pk_bf16_f32 v16, v28, v29
	v_cvt_pk_bf16_f32 v17, v30, v31
	v_cvt_pk_bf16_f32 v18, v24, v25
	v_cvt_pk_bf16_f32 v19, v26, v27
	global_store_dwordx4 v[32:33], v[16:19], off
	s_nop 1
	v_cvt_pk_bf16_f32 v16, v20, v21
	v_cvt_pk_bf16_f32 v17, v22, v23
	v_cvt_pk_bf16_f32 v18, v34, v35
	v_cvt_pk_bf16_f32 v19, v36, v37
	global_store_dwordx4 v[32:33], v[16:19], off offset:64
	s_nop 0
	s_nop 0
	v_fmamk_f32 v16, v242, 0x3a800000, v174
	v_mul_f32_e32 v17, 0x4b800000, v16
	v_cmp_gt_f32_e32 vcc, s54, v16
	s_nop 1
	v_cndmask_b32_e32 v16, v16, v17, vcc
	v_rsq_f32_e32 v18, v16
	v_add_u32_e32 v16, 0xb0, v164
	v_mad_i64_i32 v[16:17], s[2:3], v16, s55, v[168:169]
	v_mul_f32_e32 v19, 0x45800000, v18
	v_cndmask_b32_e32 v18, v18, v19, vcc
	v_pk_mul_f32 v[12:13], v[12:13], v[18:19] op_sel_hi:[1,0]
	v_pk_mul_f32 v[14:15], v[14:15], v[18:19] op_sel_hi:[1,0]
	v_pk_mul_f32 v[8:9], v[8:9], v[18:19] op_sel_hi:[1,0]
	v_pk_mul_f32 v[10:11], v[10:11], v[18:19] op_sel_hi:[1,0]
	v_pk_mul_f32 v[6:7], v[6:7], v[18:19] op_sel_hi:[1,0]
	v_pk_mul_f32 v[4:5], v[4:5], v[18:19] op_sel_hi:[1,0]
	v_pk_mul_f32 v[2:3], v[2:3], v[18:19] op_sel_hi:[1,0]
	v_pk_mul_f32 v[0:1], v[0:1], v[18:19] op_sel_hi:[1,0]
	v_pk_mul_f32 v[18:19], v[14:15], v[14:15]
	v_pk_mul_f32 v[20:21], v[12:13], v[12:13]
	v_pk_mul_f32 v[22:23], v[10:11], v[10:11]
	v_pk_mul_f32 v[24:25], v[8:9], v[8:9]
	v_pk_mov_b32 v[30:31], v[20:21], v[18:19] op_sel:[1,0]
	v_mov_b32_e32 v21, v19
	v_pk_mov_b32 v[18:19], v[24:25], v[22:23] op_sel:[1,0]
	v_mov_b32_e32 v25, v23
	v_mul_f32_e32 v26, v4, v4
	v_mul_f32_e32 v28, v6, v6
	v_pk_add_f32 v[20:21], v[30:31], v[20:21]
	v_pk_add_f32 v[18:19], v[18:19], v[24:25]
	v_pk_fma_f32 v[22:23], v[4:5], v[4:5], v[26:27] op_sel_hi:[1,1,0]
	v_pk_fma_f32 v[26:27], v[6:7], v[6:7], v[28:29] op_sel_hi:[1,1,0]
	v_pk_add_f32 v[20:21], v[20:21], v[20:21] op_sel_hi:[0,1]
	v_pk_add_f32 v[18:19], v[18:19], v[18:19] op_sel_hi:[0,1]
	v_mul_f32_e32 v22, v0, v0
	v_mul_f32_e32 v26, v1, v1
	v_mul_f32_e32 v20, v2, v2
	v_mul_f32_e32 v18, v3, v3
	v_pk_add_f32 v[22:23], v[22:23], v[26:27]
	v_pk_add_f32 v[18:19], v[20:21], v[18:19]
	v_lshl_add_u64 v[16:17], v[16:17], 0, s[0:1]
	v_pk_add_f32 v[18:19], v[22:23], v[18:19]
	v_lshl_add_u64 v[16:17], v[16:17], 0, s[12:13]
	v_add_f32_e32 v18, v18, v19
	ds_bpermute_b32 v19, v178, v18
	v_pk_mul_f32 v[12:13], v[140:141], v[12:13]
	v_pk_mul_f32 v[14:15], v[142:143], v[14:15]
	v_pk_mul_f32 v[8:9], v[136:137], v[8:9]
	v_pk_mul_f32 v[10:11], v[138:139], v[10:11]
	s_waitcnt lgkmcnt(0)
	v_add_f32_e32 v18, v18, v19
	ds_bpermute_b32 v19, v177, v18
	v_pk_mul_f32 v[4:5], v[132:133], v[4:5]
	v_pk_mul_f32 v[6:7], v[134:135], v[6:7]
	v_pk_mul_f32 v[0:1], v[128:129], v[0:1]
	v_pk_mul_f32 v[2:3], v[130:131], v[2:3]
	s_waitcnt lgkmcnt(0)
	v_add_f32_e32 v18, v18, v19
	v_fmamk_f32 v18, v18, 0x3c800000, v174
	v_mul_f32_e32 v19, 0x4b800000, v18
	v_cmp_gt_f32_e32 vcc, s54, v18
	v_lshl_add_u64 v[16:17], v[16:17], 0, v[152:153]
	s_nop 0
	v_cndmask_b32_e32 v18, v18, v19, vcc
	v_rsq_f32_e32 v18, v18
	s_nop 0
	v_mul_f32_e32 v19, 0x45800000, v18
	v_cndmask_b32_e32 v18, v18, v19, vcc
	v_mul_f32_e32 v18, v165, v18
	v_pk_mul_f32 v[14:15], v[14:15], v[18:19] op_sel_hi:[1,0]
	v_pk_mul_f32 v[12:13], v[12:13], v[18:19] op_sel_hi:[1,0]
	v_pk_mul_f32 v[10:11], v[10:11], v[18:19] op_sel_hi:[1,0]
	v_pk_mul_f32 v[8:9], v[8:9], v[18:19] op_sel_hi:[1,0]
	v_pk_mul_f32 v[6:7], v[6:7], v[18:19] op_sel_hi:[1,0]
	v_pk_mul_f32 v[4:5], v[4:5], v[18:19] op_sel_hi:[1,0]
	v_pk_mul_f32 v[20:21], v[2:3], v[18:19] op_sel_hi:[1,0]
	v_pk_mul_f32 v[18:19], v[0:1], v[18:19] op_sel_hi:[1,0]
	v_cvt_pk_bf16_f32 v0, v12, v13
	v_cvt_pk_bf16_f32 v1, v14, v15
	v_cvt_pk_bf16_f32 v2, v8, v9
	v_cvt_pk_bf16_f32 v3, v10, v11
	global_store_dwordx4 v[16:17], v[0:3], off
	s_nop 1
	v_cvt_pk_bf16_f32 v0, v4, v5
	v_cvt_pk_bf16_f32 v1, v6, v7
	v_cvt_pk_bf16_f32 v2, v18, v19
	v_cvt_pk_bf16_f32 v3, v20, v21
	global_store_dwordx4 v[16:17], v[0:3], off offset:64
	s_andn2_b64 vcc, exec, s[6:7]
	s_mov_b64 s[0:1], -1
	s_cbranch_vccnz .LBB0_370

; #define LAS __attribute__((address_space(3)))
; #define MFMA32(a, b, c) __builtin_amdgcn_mfma_f32_32x32x16_bf16((a), (b), (c), 0, 0, 0)
; #define PACK8(v, base) __builtin_bit_cast(bf16x8, (u32x4){pk2((v)[(base)], (v)[(base) + 1]), pk2((v)[(base) + 2], (v)[(base) + 3]), pk2((v)[(base) + 4], (v)[(base) + 5]), pk2((v)[(base) + 6], (v)[(base) + 7])})
; #define LFENCE() asm volatile("" ::: "memory")
; __device__ __forceinline__ void mlstm_pass1(const bf16_t* PR, const bf16_t* QC, const bf16_t* KC, const float* Gt, const float* gain, bf16_t* Y, LAS unsigned char* lds, ...
;     ...
;                     const LAS unsigned char* kb0 = lds + ML_KT + r * KROW + 8 * h;
; #pragma unroll
;                     for (int i = 0; i < 4; ++i)
; #pragma unroll
;                         for (int s = 0; s < 2; ++s) {
;                             const bf16x8 q = lds2x8(qb0 + 64 * i + 32 * s, qb0 + 64 * i + 32 * s + 16);
;                             hi_ = MFMA32(PACK8(C[i], 8 * s), q, hi_);
;                             S0 = MFMA32(lds2x8(kb0 + 64 * i + 32 * s, kb0 + 64 * i + 32 * s + 16), q, S0);
;                             S1 = MFMA32(lds2x8(kb0 + 32 * KROW + 64 * i + 32 * s, kb0 + 32 * KROW + 64 * i + 32 * s + 16), q, S1);
;                             if (s == 1) LFENCE();
;                         }
;                     const float bt = __shfl(bsum, 32 * tt + r);
;                     const LAS unsigned char* vb = vtb + (4 * h + (li >> 2)) * vstr + (16 * gg + 4 * (li & 3)) * 2;
;                     {
; #pragma unroll
;                         for (int g4 = 0; g4 < 4; ++g4) { const f32x4 cv = *(const LAS f32x4*)(cs_t + 8 * g4 + 4 * h);
; #pragma unroll
;                             for (int e = 0; e < 4; ++e) { const int sl = 8 * g4 + 4 * h + e; const bool ok = (tt == 1) || (sl <= r);
;                                 S0[4 * g4 + e] = ok ? S0[4 * g4 + e] * __builtin_amdgcn_exp2f((bt + cv[e]) * LOG2E) : 0.f; } }
;                         ha = MFMA32(tr2(vb, vb + 8 * vstr), PACK8(S0, 0), ha);
.LBB0_476:
	v_lshl_or_b32 v186, s75, 5, v142
	v_mad_u32_u24 v187, v186, s33, v165
	ds_read2_b64 v[80:83], v187 offset1:2
	v_cvt_pk_bf16_f32 v64, v32, v33
	v_cvt_pk_bf16_f32 v65, v34, v35
	v_cvt_pk_bf16_f32 v66, v36, v37
	v_cvt_pk_bf16_f32 v67, v38, v39
	ds_read2_b64 v[84:87], v180 offset1:2
	s_waitcnt lgkmcnt(0)
	v_mfma_f32_32x32x16_bf16 v[64:79], v[64:67], v[80:83], 0
	ds_read2_b64 v[192:195], v187 offset0:4 offset1:6
	v_add_u32_e32 v188, 0x2000, v180
	s_or_b64 vcc, s[94:95], s[8:9]
	v_mfma_f32_32x32x16_bf16 v[96:111], v[84:87], v[80:83], 0
	ds_read2_b64 v[84:87], v188 offset0:64 offset1:66
	ds_read2_b64 v[208:211], v180 offset0:4 offset1:6
	ds_read2_b64 v[216:219], v188 offset0:68 offset1:70
	v_cvt_pk_bf16_f32 v196, v40, v41
	v_cvt_pk_bf16_f32 v197, v42, v43
	v_cvt_pk_bf16_f32 v198, v44, v45
	v_cvt_pk_bf16_f32 v199, v46, v47
	ds_read2_b64 v[204:207], v187 offset0:8 offset1:10
	ds_read2_b64 v[212:215], v180 offset0:8 offset1:10
	ds_read2_b64 v[220:223], v188 offset0:72 offset1:74
	s_waitcnt lgkmcnt(3)
	v_mfma_f32_32x32x16_bf16 v[64:79], v[196:199], v[192:195], v[64:79]
	v_mfma_f32_32x32x16_bf16 v[96:111], v[208:211], v[192:195], v[96:111]
	v_mfma_f32_32x32x16_bf16 v[80:95], v[84:87], v[80:83], 0
	v_mfma_f32_32x32x16_bf16 v[80:95], v[216:219], v[192:195], v[80:95]
	v_cvt_pk_bf16_f32 v196, v48, v49
	v_cvt_pk_bf16_f32 v197, v50, v51
	v_cvt_pk_bf16_f32 v198, v52, v53
	v_cvt_pk_bf16_f32 v199, v54, v55
	ds_read2_b64 v[192:195], v187 offset0:12 offset1:14
	ds_read2_b64 v[208:211], v180 offset0:12 offset1:14
	ds_read2_b64 v[216:219], v188 offset0:76 offset1:78
	s_waitcnt lgkmcnt(3)
	v_mfma_f32_32x32x16_bf16 v[64:79], v[196:199], v[204:207], v[64:79]
	v_mfma_f32_32x32x16_bf16 v[96:111], v[212:215], v[204:207], v[96:111]
	v_mfma_f32_32x32x16_bf16 v[80:95], v[220:223], v[204:207], v[80:95]
	v_cvt_pk_bf16_f32 v196, v56, v57
	v_cvt_pk_bf16_f32 v197, v58, v59
	v_cvt_pk_bf16_f32 v198, v60, v61
	v_cvt_pk_bf16_f32 v199, v62, v63
	ds_read2_b64 v[204:207], v187 offset0:16 offset1:18
	ds_read2_b64 v[212:215], v180 offset0:16 offset1:18
	ds_read2_b64 v[220:223], v188 offset0:80 offset1:82
	s_waitcnt lgkmcnt(3)
	v_mfma_f32_32x32x16_bf16 v[64:79], v[196:199], v[192:195], v[64:79]
	v_mfma_f32_32x32x16_bf16 v[96:111], v[208:211], v[192:195], v[96:111]
	v_mfma_f32_32x32x16_bf16 v[80:95], v[216:219], v[192:195], v[80:95]
	v_cvt_pk_bf16_f32 v196, v16, v17
	v_cvt_pk_bf16_f32 v197, v18, v19
	v_cvt_pk_bf16_f32 v198, v20, v21
	v_cvt_pk_bf16_f32 v199, v22, v23
	ds_read2_b64 v[192:195], v187 offset0:20 offset1:22
	ds_read2_b64 v[208:211], v180 offset0:20 offset1:22
	ds_read2_b64 v[216:219], v188 offset0:84 offset1:86
	s_waitcnt lgkmcnt(3)
	v_mfma_f32_32x32x16_bf16 v[64:79], v[196:199], v[204:207], v[64:79]
	v_mfma_f32_32x32x16_bf16 v[96:111], v[212:215], v[204:207], v[96:111]
	v_mfma_f32_32x32x16_bf16 v[80:95], v[220:223], v[204:207], v[80:95]
	v_cvt_pk_bf16_f32 v196, v24, v25
	v_cvt_pk_bf16_f32 v197, v26, v27
	v_cvt_pk_bf16_f32 v198, v28, v29
	v_cvt_pk_bf16_f32 v199, v30, v31
	ds_read2_b64 v[204:207], v187 offset0:24 offset1:26
	ds_read2_b64 v[212:215], v180 offset0:24 offset1:26
	ds_read2_b64 v[220:223], v188 offset0:88 offset1:90
	s_waitcnt lgkmcnt(3)
	v_mfma_f32_32x32x16_bf16 v[64:79], v[196:199], v[192:195], v[64:79]
	v_mfma_f32_32x32x16_bf16 v[96:111], v[208:211], v[192:195], v[96:111]
	v_mfma_f32_32x32x16_bf16 v[80:95], v[216:219], v[192:195], v[80:95]
	v_cvt_pk_bf16_f32 v196, v0, v1
	v_cvt_pk_bf16_f32 v197, v2, v3
	v_cvt_pk_bf16_f32 v198, v4, v5
	v_cvt_pk_bf16_f32 v199, v6, v7
	ds_read2_b64 v[192:195], v187 offset0:28 offset1:30
	ds_read2_b64 v[208:211], v180 offset0:28 offset1:30
	ds_read2_b64 v[216:219], v188 offset0:92 offset1:94
	s_waitcnt lgkmcnt(3)
	v_mfma_f32_32x32x16_bf16 v[64:79], v[196:199], v[204:207], v[64:79]
	v_mfma_f32_32x32x16_bf16 v[96:111], v[212:215], v[204:207], v[96:111]
	v_mfma_f32_32x32x16_bf16 v[80:95], v[220:223], v[204:207], v[80:95]
	v_cvt_pk_bf16_f32 v196, v8, v9
	v_cvt_pk_bf16_f32 v197, v10, v11
	v_cvt_pk_bf16_f32 v198, v12, v13
	v_cvt_pk_bf16_f32 v199, v14, v15
	v_or_b32_e32 v187, v186, v143
	v_lshlrev_b32_e32 v187, 2, v187
	ds_bpermute_b32 v187, v187, v185
	s_waitcnt lgkmcnt(0)
	v_mfma_f32_32x32x16_bf16 v[64:79], v[196:199], v[192:195], v[64:79]
	v_mfma_f32_32x32x16_bf16 v[96:111], v[208:211], v[192:195], v[96:111]
	v_mfma_f32_32x32x16_bf16 v[80:95], v[216:219], v[192:195], v[80:95]
	ds_read_b128 v[192:195], v167 offset:62464
	ds_read_b128 v[196:199], v167 offset:62496
	s_waitcnt lgkmcnt(0)
	v_add_f32_e32 v188, v192, v187
	v_mul_f32_e32 v188, 0x3fb8aa3b, v188
	v_exp_f32_e32 v188, v188
	s_nop 2
	v_mul_f32_e32 v96, v96, v188
	v_add_f32_e32 v188, v193, v187
	v_mul_f32_e32 v188, 0x3fb8aa3b, v188
	v_exp_f32_e32 v188, v188
	v_cndmask_b32_e32 v96, 0, v96, vcc
	s_or_b64 vcc, s[94:95], s[10:11]
	v_mul_f32_e32 v97, v97, v188
	v_add_f32_e32 v188, v194, v187
	v_mul_f32_e32 v188, 0x3fb8aa3b, v188
	v_exp_f32_e32 v188, v188
	v_cndmask_b32_e32 v97, 0, v97, vcc
	s_or_b64 vcc, s[94:95], s[12:13]
	v_mul_f32_e32 v98, v98, v188
	v_cndmask_b32_e32 v188, 0, v98, vcc
	v_add_f32_e32 v98, v195, v187
	v_mul_f32_e32 v98, 0x3fb8aa3b, v98
	v_exp_f32_e32 v98, v98
	s_or_b64 vcc, s[94:95], s[14:15]
	v_mul_f32_e32 v98, v99, v98
	v_cndmask_b32_e32 v191, 0, v98, vcc
	v_add_f32_e32 v98, v196, v187
	v_mul_f32_e32 v98, 0x3fb8aa3b, v98
	v_exp_f32_e32 v98, v98
	s_or_b64 vcc, s[94:95], s[16:17]
	v_mul_f32_e32 v98, v100, v98
	v_cndmask_b32_e32 v192, 0, v98, vcc
	v_add_f32_e32 v98, v197, v187
	v_mul_f32_e32 v98, 0x3fb8aa3b, v98
	v_exp_f32_e32 v98, v98
	s_or_b64 vcc, s[94:95], s[18:19]
	v_mul_f32_e32 v98, v101, v98
	v_cndmask_b32_e32 v193, 0, v98, vcc
	v_add_f32_e32 v98, v198, v187
	v_mul_f32_e32 v98, 0x3fb8aa3b, v98
	v_exp_f32_e32 v98, v98
	s_or_b64 vcc, s[94:95], s[20:21]
	v_mul_f32_e32 v98, v102, v98
	v_cndmask_b32_e32 v194, 0, v98, vcc
	v_add_f32_e32 v98, v199, v187
	v_mul_f32_e32 v98, 0x3fb8aa3b, v98
	v_exp_f32_e32 v98, v98
	s_or_b64 vcc, s[94:95], s[22:23]
	v_mul_f32_e32 v98, v103, v98
	v_cndmask_b32_e32 v195, 0, v98, vcc
	ds_read_b128 v[98:101], v167 offset:62528
	s_or_b64 vcc, s[94:95], s[24:25]
	s_waitcnt lgkmcnt(0)
; #define LAS __attribute__((address_space(3)))
; #define MFMA32(a, b, c) __builtin_amdgcn_mfma_f32_32x32x16_bf16((a), (b), (c), 0, 0, 0)
; #define PACK8(v, base) __builtin_bit_cast(bf16x8, (u32x4){pk2((v)[(base)], (v)[(base) + 1]), pk2((v)[(base) + 2], (v)[(base) + 3]), pk2((v)[(base) + 4], (v)[(base) + 5]), pk2((v)[(base) + 6], (v)[(base) + 7])})
; __device__ __forceinline__ void mlstm_pass1(const bf16_t* PR, const bf16_t* QC, const bf16_t* KC, const float* Gt, const float* gain, bf16_t* Y, LAS unsigned char* lds, ...
;     ...
;                         for (int g4 = 0; g4 < 4; ++g4) { const f32x4 cv = *(const LAS f32x4*)(cs_t + 8 * g4 + 4 * h);
; #pragma unroll
;                             for (int e = 0; e < 4; ++e) { const int sl = 8 * g4 + 4 * h + e; const bool ok = (tt == 1) || (sl <= r);
;                                 S0[4 * g4 + e] = ok ? S0[4 * g4 + e] * __builtin_amdgcn_exp2f((bt + cv[e]) * LOG2E) : 0.f; } }
;                         ha = MFMA32(tr2(vb, vb + 8 * vstr), PACK8(S0, 0), ha);
;                         ha = MFMA32(tr2(vb + 16 * vstr, vb + 24 * vstr), PACK8(S0, 8), ha);
;                     }
;                     if (tt == 1) {
; #pragma unroll
;                         for (int g4 = 0; g4 < 4; ++g4) { const f32x4 cv = *(const LAS f32x4*)(cs_t + 32 + 8 * g4 + 4 * h);
; #pragma unroll
;                             for (int e = 0; e < 4; ++e) { const int sl = 8 * g4 + 4 * h + e; const bool ok = (sl <= r);
;                                 S1[4 * g4 + e] = ok ? S1[4 * g4 + e] * __builtin_amdgcn_exp2f((bt + cv[e]) * LOG2E) : 0.f; } }
;                         ha = MFMA32(tr2(vb + 32 * vstr, vb + 40 * vstr), PACK8(S1, 0), ha);
;                         ha = MFMA32(tr2(vb + 48 * vstr, vb + 56 * vstr), PACK8(S1, 8), ha);
;                     }
	v_add_f32_e32 v98, v98, v187
	v_mul_f32_e32 v98, 0x3fb8aa3b, v98
	v_exp_f32_e32 v98, v98
	s_nop 0
	v_mul_f32_e32 v98, v104, v98
	v_cndmask_b32_e32 v196, 0, v98, vcc
	v_add_f32_e32 v98, v99, v187
	v_mul_f32_e32 v98, 0x3fb8aa3b, v98
	v_exp_f32_e32 v98, v98
	s_or_b64 vcc, s[94:95], s[26:27]
	v_mul_f32_e32 v98, v105, v98
	v_cndmask_b32_e32 v197, 0, v98, vcc
	v_add_f32_e32 v98, v100, v187
	v_mul_f32_e32 v98, 0x3fb8aa3b, v98
	v_exp_f32_e32 v98, v98
	s_or_b64 vcc, s[94:95], s[28:29]
	v_mul_f32_e32 v98, v106, v98
	v_cndmask_b32_e32 v198, 0, v98, vcc
	v_add_f32_e32 v98, v101, v187
	v_mul_f32_e32 v98, 0x3fb8aa3b, v98
	v_exp_f32_e32 v98, v98
	s_or_b64 vcc, s[94:95], s[30:31]
	v_mul_f32_e32 v98, v107, v98
	v_cndmask_b32_e32 v199, 0, v98, vcc
	ds_read_b128 v[98:101], v167 offset:62560
	s_or_b64 vcc, s[94:95], s[34:35]
	s_waitcnt lgkmcnt(0)
	v_add_f32_e32 v98, v98, v187
	v_mul_f32_e32 v98, 0x3fb8aa3b, v98
	v_exp_f32_e32 v98, v98
	s_nop 0
	v_mul_f32_e32 v98, v108, v98
	v_cndmask_b32_e32 v200, 0, v98, vcc
	v_add_f32_e32 v98, v99, v187
	v_mul_f32_e32 v98, 0x3fb8aa3b, v98
	v_exp_f32_e32 v98, v98
	s_or_b64 vcc, s[94:95], s[36:37]
	v_mul_f32_e32 v98, v109, v98
	v_cndmask_b32_e32 v201, 0, v98, vcc
	v_add_f32_e32 v98, v100, v187
	v_mul_f32_e32 v98, 0x3fb8aa3b, v98
	v_exp_f32_e32 v98, v98
	s_or_b64 vcc, s[94:95], s[38:39]
	v_add_u32_e32 v100, s72, v166
	v_mul_f32_e32 v98, v110, v98
	v_cndmask_b32_e32 v202, 0, v98, vcc
	v_add_f32_e32 v98, v101, v187
	v_mul_f32_e32 v98, 0x3fb8aa3b, v98
	v_exp_f32_e32 v98, v98
	s_or_b64 vcc, s[94:95], s[40:41]
	ds_read_b64_tr_b16 v[100:101], v100
	v_mul_f32_e32 v98, v111, v98
	v_cndmask_b32_e32 v203, 0, v98, vcc
	ds_read_b64_tr_b16 v[98:99], v166
	v_cvt_pk_bf16_f32 v102, v96, v97
	v_cvt_pk_bf16_f32 v103, v188, v191
	v_add_u32_e32 v188, s73, v166
	v_cvt_pk_bf16_f32 v104, v192, v193
	v_cvt_pk_bf16_f32 v105, v194, v195
	ds_read_b64_tr_b16 v[192:193], v188
	v_add_u32_e32 v188, s4, v166
	ds_read_b64_tr_b16 v[194:195], v188
	s_waitcnt lgkmcnt(0)
	v_mfma_f32_32x32x16_bf16 v[96:111], v[98:101], v[102:105], 0
	v_cvt_pk_bf16_f32 v196, v196, v197
	v_cvt_pk_bf16_f32 v197, v198, v199
	v_cvt_pk_bf16_f32 v198, v200, v201
	v_cvt_pk_bf16_f32 v199, v202, v203
	s_andn2_b64 vcc, exec, s[94:95]
	v_mfma_f32_32x32x16_bf16 v[96:111], v[192:195], v[196:199], v[96:111]
	s_cbranch_vccnz .LBB0_478
	ds_read_b128 v[192:195], v167 offset:62592
	ds_read_b128 v[196:199], v167 offset:62624
	s_waitcnt lgkmcnt(0)
	v_add_f32_e32 v188, v192, v187
	v_mul_f32_e32 v188, 0x3fb8aa3b, v188
	v_exp_f32_e32 v188, v188
	s_nop 0
	v_mul_f32_e32 v80, v80, v188
	v_cndmask_b32_e64 v188, v80, 0, s[42:43]
	v_add_f32_e32 v80, v193, v187
	v_mul_f32_e32 v80, 0x3fb8aa3b, v80
	v_exp_f32_e32 v80, v80
	s_nop 0
	v_mul_f32_e32 v80, v81, v80
	v_cndmask_b32_e64 v191, 0, v80, s[10:11]
	v_add_f32_e32 v80, v194, v187
	v_mul_f32_e32 v80, 0x3fb8aa3b, v80
	v_exp_f32_e32 v80, v80
	s_nop 0
	v_mul_f32_e32 v80, v82, v80
	v_cndmask_b32_e64 v192, v80, 0, s[44:45]
	v_add_f32_e32 v80, v195, v187
	v_mul_f32_e32 v80, 0x3fb8aa3b, v80
	v_exp_f32_e32 v80, v80
	s_nop 0
	v_mul_f32_e32 v80, v83, v80
	v_cndmask_b32_e64 v193, v80, 0, s[46:47]
	v_add_f32_e32 v80, v196, v187
	v_mul_f32_e32 v80, 0x3fb8aa3b, v80
	v_exp_f32_e32 v80, v80
	s_nop 0
	v_mul_f32_e32 v80, v84, v80
	v_cndmask_b32_e64 v194, v80, 0, s[48:49]
	v_add_f32_e32 v80, v197, v187
	v_mul_f32_e32 v80, 0x3fb8aa3b, v80
	v_exp_f32_e32 v80, v80
	s_nop 0
	v_mul_f32_e32 v80, v85, v80
	v_cndmask_b32_e64 v195, v80, 0, s[50:51]
	v_add_f32_e32 v80, v198, v187
	v_mul_f32_e32 v80, 0x3fb8aa3b, v80
	v_exp_f32_e32 v80, v80
	s_nop 0
	v_mul_f32_e32 v80, v86, v80
	v_cndmask_b32_e64 v196, v80, 0, s[52:53]
	v_add_f32_e32 v80, v199, v187
	v_mul_f32_e32 v80, 0x3fb8aa3b, v80
	v_exp_f32_e32 v80, v80
	s_nop 0
	v_mul_f32_e32 v80, v87, v80
	v_cndmask_b32_e64 v87, v80, 0, s[54:55]
	ds_read_b128 v[80:83], v167 offset:62656
	s_waitcnt lgkmcnt(0)
	v_add_f32_e32 v80, v80, v187
	v_mul_f32_e32 v80, 0x3fb8aa3b, v80
	v_exp_f32_e32 v80, v80
	s_nop 0
	v_mul_f32_e32 v80, v88, v80
	v_cndmask_b32_e64 v88, v80, 0, s[56:57]
	v_add_f32_e32 v80, v81, v187
	v_mul_f32_e32 v80, 0x3fb8aa3b, v80
	v_exp_f32_e32 v80, v80
	s_nop 0
	v_mul_f32_e32 v80, v89, v80
	v_cndmask_b32_e64 v89, v80, 0, s[58:59]
	v_add_f32_e32 v80, v82, v187
	v_mul_f32_e32 v80, 0x3fb8aa3b, v80
	v_exp_f32_e32 v80, v80
	s_nop 0
	v_mul_f32_e32 v80, v90, v80
	v_cndmask_b32_e64 v90, v80, 0, s[60:61]
	v_add_f32_e32 v80, v83, v187
	v_mul_f32_e32 v80, 0x3fb8aa3b, v80
	v_exp_f32_e32 v80, v80
	s_nop 0
	v_mul_f32_e32 v80, v91, v80
	v_cndmask_b32_e64 v91, v80, 0, s[62:63]
	ds_read_b128 v[80:83], v167 offset:62688
	s_waitcnt lgkmcnt(0)
	v_add_f32_e32 v80, v80, v187
	v_mul_f32_e32 v80, 0x3fb8aa3b, v80
	v_exp_f32_e32 v80, v80
	s_nop 0
	v_mul_f32_e32 v80, v92, v80
	v_cndmask_b32_e64 v92, v80, 0, s[64:65]
	v_add_f32_e32 v80, v81, v187
	v_mul_f32_e32 v80, 0x3fb8aa3b, v80
	v_exp_f32_e32 v80, v80
	s_nop 0
	v_mul_f32_e32 v80, v93, v80
	v_cndmask_b32_e64 v93, v80, 0, s[66:67]
	v_add_f32_e32 v80, v82, v187
	v_mul_f32_e32 v80, 0x3fb8aa3b, v80
	v_exp_f32_e32 v80, v80
	v_add_u32_e32 v82, s6, v166
	v_mul_f32_e32 v80, v94, v80
	v_cndmask_b32_e64 v94, v80, 0, s[68:69]
	v_add_f32_e32 v80, v83, v187
	v_mul_f32_e32 v80, 0x3fb8aa3b, v80
	v_exp_f32_e32 v80, v80
	ds_read_b64_tr_b16 v[82:83], v82
	v_mul_f32_e32 v80, v95, v80
	v_cndmask_b32_e64 v95, v80, 0, s[70:71]
	v_add_u32_e32 v80, s5, v166
	ds_read_b64_tr_b16 v[80:81], v80
	v_cvt_pk_bf16_f32 v84, v188, v191
	v_cvt_pk_bf16_f32 v85, v192, v193
	v_cvt_pk_bf16_f32 v86, v194, v195
	v_cvt_pk_bf16_f32 v87, v196, v87
	s_waitcnt lgkmcnt(0)
	v_mfma_f32_32x32x16_bf16 v[96:111], v[80:83], v[84:87], v[96:111]
	v_add_u32_e32 v80, s7, v166
	v_add_u32_e32 v82, s92, v166
	ds_read_b64_tr_b16 v[80:81], v80
	ds_read_b64_tr_b16 v[82:83], v82
	v_cvt_pk_bf16_f32 v84, v88, v89
	v_cvt_pk_bf16_f32 v85, v90, v91
	v_cvt_pk_bf16_f32 v86, v92, v93
	v_cvt_pk_bf16_f32 v87, v94, v95
	s_waitcnt lgkmcnt(0)
	v_mfma_f32_32x32x16_bf16 v[96:111], v[80:83], v[84:87], v[96:111]

; #define PG8_STAGE(bufoff, gbase, voff) do { _Pragma("unroll") for (int _i = 0; _i < 2; ++_i) \
;         __builtin_amdgcn_global_load_lds((const unsigned*)((const char*)(gbase) + (voff)[_i]), (PG8_LAS unsigned*)(lds + (bufoff) + ldsw + _i * 8192), 16, 0, 0); } while (0)
; #define PG8_LDA(dst, b, h) do { _Pragma("unroll") for (int m = 0; m < 4; ++m) _Pragma("unroll") for (int k = 0; k < 2; ++k) dst[m][k] = *(const PG8_LAS bf16x8*)(lds + PG8_SA(b, h) + aoff + m * 2048 + k * 1024); } while (0)
; #define PG8_LDB(dst, b, h) do { _Pragma("unroll") for (int n = 0; n < 2; ++n) _Pragma("unroll") for (int k = 0; k < 2; ++k) dst[n][k] = *(const PG8_LAS bf16x8*)(lds + PG8_SB(b, h) + boff + n * 2048 + k * 1024); } while (0)
; #define PG8_MMA(ai, bj, At, Bt) do { __builtin_amdgcn_s_setprio(1); _Pragma("unroll") for (int m = 0; m < 4; ++m) _Pragma("unroll") for (int n = 0; n < 2; ++n) _Pragma("unroll") for (int k = 0; k < 2; ++k) \
;         acc[ai][bj][m][n] = __builtin_amdgcn_mfma_f32_16x16x32_bf16(Bt[n][k], At[m][k], acc[ai][bj][m][n], 0, 0, 0); __builtin_amdgcn_s_setprio(0); } while (0)
; #define PG8_WAIT_V(n) asm volatile("s_waitcnt vmcnt(" #n ")" ::: "memory")
; #define PG8_WAIT_L(n) asm volatile("s_waitcnt lgkmcnt(" #n ")" ::: "memory")
; #define PG8_BAR __builtin_amdgcn_s_barrier()
; #define PG8_SCHED __builtin_amdgcn_sched_barrier(0)
; template <class Epi, class Sched, bool ALIGN_EPI = false, bool SP2 = false>
; __device__ __forceinline__ void gemm_phase(PG8_LAS unsigned char* lds, const Gemm g, const Sched& S, const Epi& E) {
;     ...
;             PG8_LDB(B0, 0, 0); PG8_LDB(B1, 0, 1); PG8_SCHED; PG8_LDA(At, 0, 0); PG8_STAGE(PG8_SA(1, 1), a1 + hstep, voffA);
;             PG8_WAIT_V(8); PG8_WAIT_L(0); PG8_BAR; PG8_MMA(0, 0, At, B0); PG8_MMA(0, 1, At, B1); PG8_BAR; PG8_SCHED;
;             PG8_LDA(At, 0, 1); PG8_STAGE(PG8_SB(0, 0), b2, voffB); PG8_STAGE(PG8_SB(0, 1), b2 + hstep, voffB); PG8_STAGE(PG8_SA(0, 0), a2, voffA);
;             PG8_WAIT_V(8); PG8_WAIT_L(0); PG8_BAR; PG8_MMA(1, 0, At, B0); PG8_MMA(1, 1, At, B1); PG8_BAR; PG8_SCHED;
.LBB0_698:
	ds_read_b128 v[144:147], v151
	ds_read_b128 v[156:159], v151 offset:1024
	ds_read_b128 v[160:163], v151 offset:2048
	ds_read_b128 v[164:167], v151 offset:3072
	ds_read_b128 v[168:171], v152
	ds_read_b128 v[172:175], v152 offset:1024
	ds_read_b128 v[176:179], v152 offset:2048
	ds_read_b128 v[180:183], v152 offset:3072
	s_add_u32 s28, s26, 0xfffc0080
	s_addc_u32 s29, s27, -1
	s_cmp_eq_u32 s50, 12
	s_cselect_b32 s31, s17, s29
	s_cselect_b32 s30, s23, s28
	s_cselect_b32 s29, s15, s49
	s_cselect_b32 s28, s47, s48
	v_lshl_add_u64 v[218:219], s[26:27], 0, v[136:137]
	s_add_i32 m0, s25, 0xc000
	ds_read_b128 v[184:187], v153
	ds_read_b128 v[190:193], v153 offset:1024
	ds_read_b128 v[194:197], v153 offset:2048
	ds_read_b128 v[198:201], v153 offset:3072
	ds_read_b128 v[202:205], v153 offset:4096
	ds_read_b128 v[206:209], v153 offset:5120
	ds_read_b128 v[210:213], v153 offset:6144
	ds_read_b128 v[214:217], v153 offset:7168
	global_load_lds_dwordx4 v[218:219], off
	v_lshl_add_u64 v[218:219], s[26:27], 0, v[138:139]
	s_add_i32 m0, s25, 0xe000
	s_nop 0
	global_load_lds_dwordx4 v[218:219], off
	s_waitcnt vmcnt(8)
	s_waitcnt lgkmcnt(0)
	s_barrier
	s_setprio 1
	v_mfma_f32_16x16x32_bf16 v[124:127], v[144:147], v[184:187], v[124:127]
	v_mfma_f32_16x16x32_bf16 v[120:123], v[160:163], v[184:187], v[120:123]
	v_mfma_f32_16x16x32_bf16 v[108:111], v[144:147], v[194:197], v[108:111]
	v_mfma_f32_16x16x32_bf16 v[104:107], v[160:163], v[194:197], v[104:107]
	v_mfma_f32_16x16x32_bf16 v[92:95], v[144:147], v[202:205], v[92:95]
	v_mfma_f32_16x16x32_bf16 v[88:91], v[160:163], v[202:205], v[88:91]
	v_mfma_f32_16x16x32_bf16 v[76:79], v[144:147], v[210:213], v[76:79]
	v_mfma_f32_16x16x32_bf16 v[72:75], v[160:163], v[210:213], v[72:75]
	v_mfma_f32_16x16x32_bf16 v[124:127], v[156:159], v[190:193], v[124:127]
	v_mfma_f32_16x16x32_bf16 v[120:123], v[164:167], v[190:193], v[120:123]
	v_mfma_f32_16x16x32_bf16 v[108:111], v[156:159], v[198:201], v[108:111]
	v_mfma_f32_16x16x32_bf16 v[104:107], v[164:167], v[198:201], v[104:107]
	v_mfma_f32_16x16x32_bf16 v[92:95], v[156:159], v[206:209], v[92:95]
	v_mfma_f32_16x16x32_bf16 v[88:91], v[164:167], v[206:209], v[88:91]
	v_mfma_f32_16x16x32_bf16 v[76:79], v[156:159], v[214:217], v[76:79]
	v_mfma_f32_16x16x32_bf16 v[72:75], v[164:167], v[214:217], v[72:75]
	v_mfma_f32_16x16x32_bf16 v[116:119], v[168:171], v[184:187], v[116:119]
	v_mfma_f32_16x16x32_bf16 v[112:115], v[176:179], v[184:187], v[112:115]
	v_mfma_f32_16x16x32_bf16 v[100:103], v[168:171], v[194:197], v[100:103]
	v_mfma_f32_16x16x32_bf16 v[96:99], v[176:179], v[194:197], v[96:99]
	v_mfma_f32_16x16x32_bf16 v[84:87], v[168:171], v[202:205], v[84:87]
	v_mfma_f32_16x16x32_bf16 v[80:83], v[176:179], v[202:205], v[80:83]
	v_mfma_f32_16x16x32_bf16 v[68:71], v[168:171], v[210:213], v[68:71]
	v_mfma_f32_16x16x32_bf16 v[64:67], v[176:179], v[210:213], v[64:67]
	v_mfma_f32_16x16x32_bf16 v[116:119], v[172:175], v[190:193], v[116:119]
	v_mfma_f32_16x16x32_bf16 v[112:115], v[180:183], v[190:193], v[112:115]
	v_mfma_f32_16x16x32_bf16 v[100:103], v[172:175], v[198:201], v[100:103]
	v_mfma_f32_16x16x32_bf16 v[96:99], v[180:183], v[198:201], v[96:99]
	v_mfma_f32_16x16x32_bf16 v[84:87], v[172:175], v[206:209], v[84:87]
	v_mfma_f32_16x16x32_bf16 v[80:83], v[180:183], v[206:209], v[80:83]
	v_mfma_f32_16x16x32_bf16 v[68:71], v[172:175], v[214:217], v[68:71]
	v_mfma_f32_16x16x32_bf16 v[64:67], v[180:183], v[214:217], v[64:67]
	s_setprio 0
	s_barrier
	s_add_i32 s51, s45, s35
	v_lshl_add_u64 v[218:219], s[28:29], 0, v[130:131]
	s_mov_b32 m0, s51
	ds_read_b128 v[184:187], v153 offset:16384
	ds_read_b128 v[190:193], v153 offset:17408
	ds_read_b128 v[194:197], v153 offset:18432
	ds_read_b128 v[198:201], v153 offset:19456
	ds_read_b128 v[202:205], v153 offset:20480
	ds_read_b128 v[206:209], v153 offset:21504
	ds_read_b128 v[210:213], v153 offset:22528
	ds_read_b128 v[214:217], v153 offset:23552
	global_load_lds_dwordx4 v[218:219], off
	s_add_i32 m0, s51, 0x2000
	s_add_u32 s52, s28, 0x40000
	v_lshl_add_u64 v[220:221], s[28:29], 0, v[134:135]
	s_addc_u32 s53, s29, 0
	s_add_i32 s51, s46, s35
	global_load_lds_dwordx4 v[220:221], off
	v_lshl_add_u64 v[222:223], s[52:53], 0, v[130:131]
	s_mov_b32 m0, s51
	v_lshl_add_u64 v[224:225], s[30:31], 0, v[132:133]
	global_load_lds_dwordx4 v[222:223], off
	v_lshl_add_u64 v[222:223], s[52:53], 0, v[134:135]
	s_add_i32 m0, s51, 0x2000
	s_nop 0
	global_load_lds_dwordx4 v[222:223], off
	v_lshl_add_u64 v[222:223], s[30:31], 0, v[128:129]
	s_mov_b32 m0, s25
	s_nop 0
	global_load_lds_dwordx4 v[222:223], off
	s_mov_b32 m0, s36
	s_nop 0
	global_load_lds_dwordx4 v[224:225], off
	s_waitcnt vmcnt(8)
	s_waitcnt lgkmcnt(0)
	s_barrier
; #define PG8_STAGE(bufoff, gbase, voff) do { _Pragma("unroll") for (int _i = 0; _i < 2; ++_i) \
;         __builtin_amdgcn_global_load_lds((const unsigned*)((const char*)(gbase) + (voff)[_i]), (PG8_LAS unsigned*)(lds + (bufoff) + ldsw + _i * 8192), 16, 0, 0); } while (0)
; #define PG8_LDA(dst, b, h) do { _Pragma("unroll") for (int m = 0; m < 4; ++m) _Pragma("unroll") for (int k = 0; k < 2; ++k) dst[m][k] = *(const PG8_LAS bf16x8*)(lds + PG8_SA(b, h) + aoff + m * 2048 + k * 1024); } while (0)
; #define PG8_LDB(dst, b, h) do { _Pragma("unroll") for (int n = 0; n < 2; ++n) _Pragma("unroll") for (int k = 0; k < 2; ++k) dst[n][k] = *(const PG8_LAS bf16x8*)(lds + PG8_SB(b, h) + boff + n * 2048 + k * 1024); } while (0)
; #define PG8_MMA(ai, bj, At, Bt) do { __builtin_amdgcn_s_setprio(1); _Pragma("unroll") for (int m = 0; m < 4; ++m) _Pragma("unroll") for (int n = 0; n < 2; ++n) _Pragma("unroll") for (int k = 0; k < 2; ++k) \
;         acc[ai][bj][m][n] = __builtin_amdgcn_mfma_f32_16x16x32_bf16(Bt[n][k], At[m][k], acc[ai][bj][m][n], 0, 0, 0); __builtin_amdgcn_s_setprio(0); } while (0)
; #define PG8_WAIT_V(n) asm volatile("s_waitcnt vmcnt(" #n ")" ::: "memory")
; #define PG8_WAIT_L(n) asm volatile("s_waitcnt lgkmcnt(" #n ")" ::: "memory")
; #define PG8_BAR __builtin_amdgcn_s_barrier()
; #define PG8_SCHED __builtin_amdgcn_sched_barrier(0)
; template <class Epi, class Sched, bool ALIGN_EPI = false, bool SP2 = false>
; __device__ __forceinline__ void gemm_phase(PG8_LAS unsigned char* lds, const Gemm g, const Sched& S, const Epi& E) {
;     ...
;             PG8_WAIT_V(8); PG8_WAIT_L(0); PG8_BAR; PG8_MMA(1, 0, At, B0); PG8_MMA(1, 1, At, B1); PG8_BAR; PG8_SCHED;
;             PG8_LDB(B0, 1, 0); PG8_LDB(B1, 1, 1); PG8_SCHED; PG8_LDA(At, 1, 0); PG8_STAGE(PG8_SA(0, 1), a2 + hstep, voffA);
;             PG8_WAIT_V(8); PG8_WAIT_L(0); PG8_BAR; PG8_MMA(0, 0, At, B0); PG8_MMA(0, 1, At, B1); PG8_BAR; PG8_SCHED;
;             PG8_LDA(At, 1, 1); PG8_STAGE(PG8_SB(1, 0), b3, voffB); PG8_STAGE(PG8_SB(1, 1), b3 + hstep, voffB); PG8_STAGE(PG8_SA(1, 0), a3, voffA);
	s_setprio 1
	v_mfma_f32_16x16x32_bf16 v[60:63], v[144:147], v[184:187], v[60:63]
	v_mfma_f32_16x16x32_bf16 v[56:59], v[160:163], v[184:187], v[56:59]
	v_mfma_f32_16x16x32_bf16 v[44:47], v[144:147], v[194:197], v[44:47]
	v_mfma_f32_16x16x32_bf16 v[40:43], v[160:163], v[194:197], v[40:43]
	v_mfma_f32_16x16x32_bf16 v[28:31], v[144:147], v[202:205], v[28:31]
	v_mfma_f32_16x16x32_bf16 v[24:27], v[160:163], v[202:205], v[24:27]
	v_mfma_f32_16x16x32_bf16 v[12:15], v[144:147], v[210:213], v[12:15]
	v_mfma_f32_16x16x32_bf16 v[8:11], v[160:163], v[210:213], v[8:11]
	v_mfma_f32_16x16x32_bf16 v[60:63], v[156:159], v[190:193], v[60:63]
	v_mfma_f32_16x16x32_bf16 v[56:59], v[164:167], v[190:193], v[56:59]
	v_mfma_f32_16x16x32_bf16 v[44:47], v[156:159], v[198:201], v[44:47]
	v_mfma_f32_16x16x32_bf16 v[40:43], v[164:167], v[198:201], v[40:43]
	v_mfma_f32_16x16x32_bf16 v[28:31], v[156:159], v[206:209], v[28:31]
	v_mfma_f32_16x16x32_bf16 v[24:27], v[164:167], v[206:209], v[24:27]
	v_mfma_f32_16x16x32_bf16 v[12:15], v[156:159], v[214:217], v[12:15]
	v_mfma_f32_16x16x32_bf16 v[8:11], v[164:167], v[214:217], v[8:11]
	v_mfma_f32_16x16x32_bf16 v[52:55], v[168:171], v[184:187], v[52:55]
	v_mfma_f32_16x16x32_bf16 v[48:51], v[176:179], v[184:187], v[48:51]
	v_mfma_f32_16x16x32_bf16 v[36:39], v[168:171], v[194:197], v[36:39]
	v_mfma_f32_16x16x32_bf16 v[32:35], v[176:179], v[194:197], v[32:35]
	v_mfma_f32_16x16x32_bf16 v[20:23], v[168:171], v[202:205], v[20:23]
	v_mfma_f32_16x16x32_bf16 v[16:19], v[176:179], v[202:205], v[16:19]
	v_mfma_f32_16x16x32_bf16 v[4:7], v[168:171], v[210:213], v[4:7]
	v_mfma_f32_16x16x32_bf16 v[0:3], v[176:179], v[210:213], v[0:3]
	v_mfma_f32_16x16x32_bf16 v[52:55], v[172:175], v[190:193], v[52:55]
	v_mfma_f32_16x16x32_bf16 v[48:51], v[180:183], v[190:193], v[48:51]
	v_mfma_f32_16x16x32_bf16 v[36:39], v[172:175], v[198:201], v[36:39]
	v_mfma_f32_16x16x32_bf16 v[32:35], v[180:183], v[198:201], v[32:35]
	v_mfma_f32_16x16x32_bf16 v[20:23], v[172:175], v[206:209], v[20:23]
	v_mfma_f32_16x16x32_bf16 v[16:19], v[180:183], v[206:209], v[16:19]
	v_mfma_f32_16x16x32_bf16 v[4:7], v[172:175], v[214:217], v[4:7]
	v_mfma_f32_16x16x32_bf16 v[0:3], v[180:183], v[214:217], v[0:3]
	s_setprio 0
	s_barrier
	s_add_i32 s51, 0, 0x18000
	v_add_u32_e32 v155, s51, v149
	s_add_i32 s52, 0, 0x1c000
	ds_read_b128 v[144:147], v155
	ds_read_b128 v[156:159], v155 offset:1024
	ds_read_b128 v[160:163], v155 offset:2048
	ds_read_b128 v[164:167], v155 offset:3072
	v_add_u32_e32 v155, s52, v149
	ds_read_b128 v[168:171], v155
	ds_read_b128 v[172:175], v155 offset:1024
	ds_read_b128 v[176:179], v155 offset:2048
	ds_read_b128 v[180:183], v155 offset:3072
	s_add_u32 s30, s30, 0x40000
	s_addc_u32 s31, s31, 0
	s_mov_b32 m0, s37
	v_lshl_add_u64 v[226:227], s[30:31], 0, v[128:129]
	ds_read_b128 v[184:187], v153 offset:32768
	ds_read_b128 v[190:193], v153 offset:33792
	ds_read_b128 v[194:197], v153 offset:34816
	ds_read_b128 v[198:201], v153 offset:35840
	ds_read_b128 v[202:205], v153 offset:36864
	ds_read_b128 v[206:209], v153 offset:37888
	ds_read_b128 v[210:213], v153 offset:38912
	ds_read_b128 v[214:217], v153 offset:39936
	global_load_lds_dwordx4 v[226:227], off
	v_lshl_add_u64 v[226:227], s[30:31], 0, v[132:133]
	s_mov_b32 m0, s38
	s_nop 0
	global_load_lds_dwordx4 v[226:227], off
	s_waitcnt vmcnt(8)
	s_waitcnt lgkmcnt(0)
	s_barrier
	s_setprio 1
	v_mfma_f32_16x16x32_bf16 v[124:127], v[144:147], v[184:187], v[124:127]
	v_mfma_f32_16x16x32_bf16 v[120:123], v[160:163], v[184:187], v[120:123]
	v_mfma_f32_16x16x32_bf16 v[108:111], v[144:147], v[194:197], v[108:111]
	v_mfma_f32_16x16x32_bf16 v[104:107], v[160:163], v[194:197], v[104:107]
	v_mfma_f32_16x16x32_bf16 v[92:95], v[144:147], v[202:205], v[92:95]
	v_mfma_f32_16x16x32_bf16 v[88:91], v[160:163], v[202:205], v[88:91]
	v_mfma_f32_16x16x32_bf16 v[76:79], v[144:147], v[210:213], v[76:79]
	v_mfma_f32_16x16x32_bf16 v[72:75], v[160:163], v[210:213], v[72:75]
	v_mfma_f32_16x16x32_bf16 v[124:127], v[156:159], v[190:193], v[124:127]
	v_mfma_f32_16x16x32_bf16 v[120:123], v[164:167], v[190:193], v[120:123]
	v_mfma_f32_16x16x32_bf16 v[108:111], v[156:159], v[198:201], v[108:111]
	v_mfma_f32_16x16x32_bf16 v[104:107], v[164:167], v[198:201], v[104:107]
	v_mfma_f32_16x16x32_bf16 v[92:95], v[156:159], v[206:209], v[92:95]
	v_mfma_f32_16x16x32_bf16 v[88:91], v[164:167], v[206:209], v[88:91]
	v_mfma_f32_16x16x32_bf16 v[76:79], v[156:159], v[214:217], v[76:79]
	v_mfma_f32_16x16x32_bf16 v[72:75], v[164:167], v[214:217], v[72:75]
	v_mfma_f32_16x16x32_bf16 v[116:119], v[168:171], v[184:187], v[116:119]
	v_mfma_f32_16x16x32_bf16 v[112:115], v[176:179], v[184:187], v[112:115]
	v_mfma_f32_16x16x32_bf16 v[100:103], v[168:171], v[194:197], v[100:103]
	v_mfma_f32_16x16x32_bf16 v[96:99], v[176:179], v[194:197], v[96:99]
	v_mfma_f32_16x16x32_bf16 v[84:87], v[168:171], v[202:205], v[84:87]
	v_mfma_f32_16x16x32_bf16 v[80:83], v[176:179], v[202:205], v[80:83]
	v_mfma_f32_16x16x32_bf16 v[68:71], v[168:171], v[210:213], v[68:71]
	v_mfma_f32_16x16x32_bf16 v[64:67], v[176:179], v[210:213], v[64:67]
	v_mfma_f32_16x16x32_bf16 v[116:119], v[172:175], v[190:193], v[116:119]
	v_mfma_f32_16x16x32_bf16 v[112:115], v[180:183], v[190:193], v[112:115]
	v_mfma_f32_16x16x32_bf16 v[100:103], v[172:175], v[198:201], v[100:103]
	v_mfma_f32_16x16x32_bf16 v[96:99], v[180:183], v[198:201], v[96:99]
	v_mfma_f32_16x16x32_bf16 v[84:87], v[172:175], v[206:209], v[84:87]
	v_mfma_f32_16x16x32_bf16 v[80:83], v[180:183], v[206:209], v[80:83]
	v_mfma_f32_16x16x32_bf16 v[68:71], v[172:175], v[214:217], v[68:71]
	v_mfma_f32_16x16x32_bf16 v[64:67], v[180:183], v[214:217], v[64:67]
	s_setprio 0
	s_barrier
; #define PG8_STAGE(bufoff, gbase, voff) do { _Pragma("unroll") for (int _i = 0; _i < 2; ++_i) \
;         __builtin_amdgcn_global_load_lds((const unsigned*)((const char*)(gbase) + (voff)[_i]), (PG8_LAS unsigned*)(lds + (bufoff) + ldsw + _i * 8192), 16, 0, 0); } while (0)
; #define PG8_LDA(dst, b, h) do { _Pragma("unroll") for (int m = 0; m < 4; ++m) _Pragma("unroll") for (int k = 0; k < 2; ++k) dst[m][k] = *(const PG8_LAS bf16x8*)(lds + PG8_SA(b, h) + aoff + m * 2048 + k * 1024); } while (0)
; #define PG8_MMA(ai, bj, At, Bt) do { __builtin_amdgcn_s_setprio(1); _Pragma("unroll") for (int m = 0; m < 4; ++m) _Pragma("unroll") for (int n = 0; n < 2; ++n) _Pragma("unroll") for (int k = 0; k < 2; ++k) \
;         acc[ai][bj][m][n] = __builtin_amdgcn_mfma_f32_16x16x32_bf16(Bt[n][k], At[m][k], acc[ai][bj][m][n], 0, 0, 0); __builtin_amdgcn_s_setprio(0); } while (0)
; #define PG8_WAIT_V(n) asm volatile("s_waitcnt vmcnt(" #n ")" ::: "memory")
; #define PG8_WAIT_L(n) asm volatile("s_waitcnt lgkmcnt(" #n ")" ::: "memory")
; #define PG8_BAR __builtin_amdgcn_s_barrier()
; #define PG8_SCHED __builtin_amdgcn_sched_barrier(0)
; template <class Epi, class Sched, bool ALIGN_EPI = false, bool SP2 = false>
; __device__ __forceinline__ void gemm_phase(PG8_LAS unsigned char* lds, const Gemm g, const Sched& S, const Epi& E) {
;     ...
;         for (int t = 0; t < nt; t += 2) {
;             const bool last = (t == nt - 2);
;             const char* a1 = cA + (size_t)(t + 1) * kstep;
;             const char* a2 = last ? nA : cA + (size_t)(t + 2) * kstep; const char* b2 = last ? nB : cB + (size_t)(t + 2) * kstep;
;     ...
;             PG8_LDA(At, 1, 1); PG8_STAGE(PG8_SB(1, 0), b3, voffB); PG8_STAGE(PG8_SB(1, 1), b3 + hstep, voffB); PG8_STAGE(PG8_SA(1, 0), a3, voffA);
;             PG8_WAIT_V(8); PG8_WAIT_L(0); PG8_BAR; PG8_MMA(1, 0, At, B0); PG8_MMA(1, 1, At, B1); PG8_BAR; PG8_SCHED;
	s_add_i32 s30, s51, s35
	v_lshl_add_u64 v[218:219], v[218:219], 0, s[2:3]
	s_mov_b32 m0, s30
	ds_read_b128 v[184:187], v153 offset:49152
	ds_read_b128 v[190:193], v153 offset:50176
	ds_read_b128 v[194:197], v153 offset:51200
	ds_read_b128 v[198:201], v153 offset:52224
	ds_read_b128 v[202:205], v153 offset:53248
	ds_read_b128 v[206:209], v153 offset:54272
	ds_read_b128 v[210:213], v153 offset:55296
	ds_read_b128 v[214:217], v153 offset:56320
	global_load_lds_dwordx4 v[218:219], off
	s_add_i32 m0, s30, 0x2000
	s_add_u32 s28, s28, 0x40080
	v_lshl_add_u64 v[218:219], v[220:221], 0, s[2:3]
	s_addc_u32 s29, s29, 0
	s_add_i32 s30, s52, s35
	global_load_lds_dwordx4 v[218:219], off
	v_lshl_add_u64 v[218:219], s[28:29], 0, v[130:131]
	s_mov_b32 m0, s30
	s_nop 0
	global_load_lds_dwordx4 v[218:219], off
	v_lshl_add_u64 v[218:219], s[28:29], 0, v[134:135]
	s_add_i32 m0, s30, 0x2000
	s_nop 0
	global_load_lds_dwordx4 v[218:219], off
	v_lshl_add_u64 v[218:219], v[222:223], 0, s[2:3]
	s_mov_b32 m0, s40
	s_nop 0
	global_load_lds_dwordx4 v[218:219], off
	v_lshl_add_u64 v[218:219], v[224:225], 0, s[2:3]
	s_mov_b32 m0, s41
	s_nop 0
	global_load_lds_dwordx4 v[218:219], off
	s_waitcnt vmcnt(8)
	s_waitcnt lgkmcnt(0)
	s_barrier
	s_setprio 1
	v_mfma_f32_16x16x32_bf16 v[60:63], v[144:147], v[184:187], v[60:63]
	v_mfma_f32_16x16x32_bf16 v[56:59], v[160:163], v[184:187], v[56:59]
	v_mfma_f32_16x16x32_bf16 v[44:47], v[144:147], v[194:197], v[44:47]
	v_mfma_f32_16x16x32_bf16 v[40:43], v[160:163], v[194:197], v[40:43]
	v_mfma_f32_16x16x32_bf16 v[28:31], v[144:147], v[202:205], v[28:31]
	v_mfma_f32_16x16x32_bf16 v[24:27], v[160:163], v[202:205], v[24:27]
	v_mfma_f32_16x16x32_bf16 v[12:15], v[144:147], v[210:213], v[12:15]
	v_mfma_f32_16x16x32_bf16 v[8:11], v[160:163], v[210:213], v[8:11]
	v_mfma_f32_16x16x32_bf16 v[60:63], v[156:159], v[190:193], v[60:63]
	v_mfma_f32_16x16x32_bf16 v[56:59], v[164:167], v[190:193], v[56:59]
	v_mfma_f32_16x16x32_bf16 v[44:47], v[156:159], v[198:201], v[44:47]
	v_mfma_f32_16x16x32_bf16 v[40:43], v[164:167], v[198:201], v[40:43]
	v_mfma_f32_16x16x32_bf16 v[28:31], v[156:159], v[206:209], v[28:31]
	v_mfma_f32_16x16x32_bf16 v[24:27], v[164:167], v[206:209], v[24:27]
	v_mfma_f32_16x16x32_bf16 v[12:15], v[156:159], v[214:217], v[12:15]
	v_mfma_f32_16x16x32_bf16 v[8:11], v[164:167], v[214:217], v[8:11]
	v_mfma_f32_16x16x32_bf16 v[52:55], v[168:171], v[184:187], v[52:55]
	v_mfma_f32_16x16x32_bf16 v[48:51], v[176:179], v[184:187], v[48:51]
	v_mfma_f32_16x16x32_bf16 v[36:39], v[168:171], v[194:197], v[36:39]
	v_mfma_f32_16x16x32_bf16 v[32:35], v[176:179], v[194:197], v[32:35]
	v_mfma_f32_16x16x32_bf16 v[20:23], v[168:171], v[202:205], v[20:23]
	v_mfma_f32_16x16x32_bf16 v[16:19], v[176:179], v[202:205], v[16:19]
	v_mfma_f32_16x16x32_bf16 v[4:7], v[168:171], v[210:213], v[4:7]
	v_mfma_f32_16x16x32_bf16 v[0:3], v[176:179], v[210:213], v[0:3]
	v_mfma_f32_16x16x32_bf16 v[52:55], v[172:175], v[190:193], v[52:55]
	v_mfma_f32_16x16x32_bf16 v[48:51], v[180:183], v[190:193], v[48:51]
	v_mfma_f32_16x16x32_bf16 v[36:39], v[172:175], v[198:201], v[36:39]
	v_mfma_f32_16x16x32_bf16 v[32:35], v[180:183], v[198:201], v[32:35]
	v_mfma_f32_16x16x32_bf16 v[20:23], v[172:175], v[206:209], v[20:23]
	v_mfma_f32_16x16x32_bf16 v[16:19], v[180:183], v[206:209], v[16:19]
	v_mfma_f32_16x16x32_bf16 v[4:7], v[172:175], v[214:217], v[4:7]
	v_mfma_f32_16x16x32_bf16 v[0:3], v[180:183], v[214:217], v[0:3]
	s_setprio 0
	s_barrier
	s_add_i32 s50, s50, 2
	s_add_u32 s26, s26, 0x100
	s_addc_u32 s27, s27, 0
	s_add_u32 s48, s48, 0x100
	s_addc_u32 s49, s49, 0
	s_cmp_gt_u32 s50, 13
	s_cbranch_scc0 .LBB0_698
	s_and_b64 vcc, exec, s[12:13]
	s_cbranch_vccz .LBB0_701
	s_barrier

; #define PG8_STAGE(bufoff, gbase, voff) do { _Pragma("unroll") for (int _i = 0; _i < 2; ++_i) \
;         __builtin_amdgcn_global_load_lds((const unsigned*)((const char*)(gbase) + (voff)[_i]), (PG8_LAS unsigned*)(lds + (bufoff) + ldsw + _i * 8192), 16, 0, 0); } while (0)
; #define PG8_LDA(dst, b, h) do { _Pragma("unroll") for (int m = 0; m < 4; ++m) _Pragma("unroll") for (int k = 0; k < 2; ++k) dst[m][k] = *(const PG8_LAS bf16x8*)(lds + PG8_SA(b, h) + aoff + m * 2048 + k * 1024); } while (0)
; #define PG8_LDB(dst, b, h) do { _Pragma("unroll") for (int n = 0; n < 2; ++n) _Pragma("unroll") for (int k = 0; k < 2; ++k) dst[n][k] = *(const PG8_LAS bf16x8*)(lds + PG8_SB(b, h) + boff + n * 2048 + k * 1024); } while (0)
; #define PG8_MMA(ai, bj, At, Bt) do { __builtin_amdgcn_s_setprio(1); _Pragma("unroll") for (int m = 0; m < 4; ++m) _Pragma("unroll") for (int n = 0; n < 2; ++n) _Pragma("unroll") for (int k = 0; k < 2; ++k) \
;         acc[ai][bj][m][n] = __builtin_amdgcn_mfma_f32_16x16x32_bf16(Bt[n][k], At[m][k], acc[ai][bj][m][n], 0, 0, 0); __builtin_amdgcn_s_setprio(0); } while (0)
; #define PG8_WAIT_V(n) asm volatile("s_waitcnt vmcnt(" #n ")" ::: "memory")
; #define PG8_WAIT_L(n) asm volatile("s_waitcnt lgkmcnt(" #n ")" ::: "memory")
; #define PG8_BAR __builtin_amdgcn_s_barrier()
; #define PG8_SCHED __builtin_amdgcn_sched_barrier(0)
; template <class Epi, class Sched, bool ALIGN_EPI = false, bool SP2 = false>
; __device__ __forceinline__ void gemm_phase(PG8_LAS unsigned char* lds, const Gemm g, const Sched& S, const Epi& E) {
;     ...
;             PG8_LDB(B0, 0, 0); PG8_LDB(B1, 0, 1); PG8_SCHED; PG8_LDA(At, 0, 0); PG8_STAGE(PG8_SA(1, 1), a1 + hstep, voffA);
;             PG8_WAIT_V(8); PG8_WAIT_L(0); PG8_BAR; PG8_MMA(0, 0, At, B0); PG8_MMA(0, 1, At, B1); PG8_BAR; PG8_SCHED;
;             PG8_LDA(At, 0, 1); PG8_STAGE(PG8_SB(0, 0), b2, voffB); PG8_STAGE(PG8_SB(0, 1), b2 + hstep, voffB); PG8_STAGE(PG8_SA(0, 0), a2, voffA);
;             PG8_WAIT_V(8); PG8_WAIT_L(0); PG8_BAR; PG8_MMA(1, 0, At, B0); PG8_MMA(1, 1, At, B1); PG8_BAR; PG8_SCHED;
.LBB0_782:
	ds_read_b128 v[144:147], v151
	ds_read_b128 v[156:159], v151 offset:1024
	ds_read_b128 v[160:163], v151 offset:2048
	ds_read_b128 v[164:167], v151 offset:3072
	ds_read_b128 v[168:171], v152
	ds_read_b128 v[172:175], v152 offset:1024
	ds_read_b128 v[176:179], v152 offset:2048
	ds_read_b128 v[180:183], v152 offset:3072
	s_add_u32 s24, s22, 0xfffc0080
	s_addc_u32 s25, s23, -1
	s_cmp_eq_u32 s51, 12
	s_cselect_b32 s27, s17, s25
	s_cselect_b32 s26, s47, s24
	s_cselect_b32 s25, s15, s50
	s_cselect_b32 s24, s48, s49
	v_lshl_add_u64 v[218:219], s[22:23], 0, v[136:137]
	s_add_i32 m0, s34, 0xc000
	ds_read_b128 v[184:187], v153
	ds_read_b128 v[190:193], v153 offset:1024
	ds_read_b128 v[194:197], v153 offset:2048
	ds_read_b128 v[198:201], v153 offset:3072
	ds_read_b128 v[202:205], v153 offset:4096
	ds_read_b128 v[206:209], v153 offset:5120
	ds_read_b128 v[210:213], v153 offset:6144
	ds_read_b128 v[214:217], v153 offset:7168
	global_load_lds_dwordx4 v[218:219], off
	v_lshl_add_u64 v[218:219], s[22:23], 0, v[138:139]
	s_add_i32 m0, s34, 0xe000
	s_nop 0
	global_load_lds_dwordx4 v[218:219], off
	s_waitcnt vmcnt(8)
	s_waitcnt lgkmcnt(0)
	s_barrier
	s_setprio 1
	v_mfma_f32_16x16x32_bf16 v[116:119], v[144:147], v[184:187], v[116:119]
	v_mfma_f32_16x16x32_bf16 v[112:115], v[160:163], v[184:187], v[112:115]
	v_mfma_f32_16x16x32_bf16 v[100:103], v[144:147], v[194:197], v[100:103]
	v_mfma_f32_16x16x32_bf16 v[96:99], v[160:163], v[194:197], v[96:99]
	v_mfma_f32_16x16x32_bf16 v[84:87], v[144:147], v[202:205], v[84:87]
	v_mfma_f32_16x16x32_bf16 v[80:83], v[160:163], v[202:205], v[80:83]
	v_mfma_f32_16x16x32_bf16 v[72:75], v[144:147], v[210:213], v[72:75]
	v_mfma_f32_16x16x32_bf16 v[64:67], v[160:163], v[210:213], v[64:67]
	v_mfma_f32_16x16x32_bf16 v[116:119], v[156:159], v[190:193], v[116:119]
	v_mfma_f32_16x16x32_bf16 v[112:115], v[164:167], v[190:193], v[112:115]
	v_mfma_f32_16x16x32_bf16 v[100:103], v[156:159], v[198:201], v[100:103]
	v_mfma_f32_16x16x32_bf16 v[96:99], v[164:167], v[198:201], v[96:99]
	v_mfma_f32_16x16x32_bf16 v[84:87], v[156:159], v[206:209], v[84:87]
	v_mfma_f32_16x16x32_bf16 v[80:83], v[164:167], v[206:209], v[80:83]
	v_mfma_f32_16x16x32_bf16 v[72:75], v[156:159], v[214:217], v[72:75]
	v_mfma_f32_16x16x32_bf16 v[64:67], v[164:167], v[214:217], v[64:67]
	v_mfma_f32_16x16x32_bf16 v[124:127], v[168:171], v[184:187], v[124:127]
	v_mfma_f32_16x16x32_bf16 v[120:123], v[176:179], v[184:187], v[120:123]
	v_mfma_f32_16x16x32_bf16 v[108:111], v[168:171], v[194:197], v[108:111]
	v_mfma_f32_16x16x32_bf16 v[104:107], v[176:179], v[194:197], v[104:107]
	v_mfma_f32_16x16x32_bf16 v[92:95], v[168:171], v[202:205], v[92:95]
	v_mfma_f32_16x16x32_bf16 v[88:91], v[176:179], v[202:205], v[88:91]
	v_mfma_f32_16x16x32_bf16 v[76:79], v[168:171], v[210:213], v[76:79]
	v_mfma_f32_16x16x32_bf16 v[68:71], v[176:179], v[210:213], v[68:71]
	v_mfma_f32_16x16x32_bf16 v[124:127], v[172:175], v[190:193], v[124:127]
	v_mfma_f32_16x16x32_bf16 v[120:123], v[180:183], v[190:193], v[120:123]
	v_mfma_f32_16x16x32_bf16 v[108:111], v[172:175], v[198:201], v[108:111]
	v_mfma_f32_16x16x32_bf16 v[104:107], v[180:183], v[198:201], v[104:107]
	v_mfma_f32_16x16x32_bf16 v[92:95], v[172:175], v[206:209], v[92:95]
	v_mfma_f32_16x16x32_bf16 v[88:91], v[180:183], v[206:209], v[88:91]
	v_mfma_f32_16x16x32_bf16 v[76:79], v[172:175], v[214:217], v[76:79]
	v_mfma_f32_16x16x32_bf16 v[68:71], v[180:183], v[214:217], v[68:71]
	s_setprio 0
	s_barrier
	s_add_i32 s52, s43, s30
	v_lshl_add_u64 v[218:219], s[24:25], 0, v[132:133]
	s_mov_b32 m0, s52
	ds_read_b128 v[184:187], v153 offset:16384
	ds_read_b128 v[190:193], v153 offset:17408
	ds_read_b128 v[194:197], v153 offset:18432
	ds_read_b128 v[198:201], v153 offset:19456
	ds_read_b128 v[202:205], v153 offset:20480
	ds_read_b128 v[206:209], v153 offset:21504
	ds_read_b128 v[210:213], v153 offset:22528
	ds_read_b128 v[214:217], v153 offset:23552
	global_load_lds_dwordx4 v[218:219], off
	s_add_i32 m0, s52, 0x2000
	s_add_u32 s52, s24, 0x40000
	v_lshl_add_u64 v[220:221], s[24:25], 0, v[128:129]
	s_addc_u32 s53, s25, 0
	s_add_i32 s54, s44, s30
	global_load_lds_dwordx4 v[220:221], off
	v_lshl_add_u64 v[222:223], s[52:53], 0, v[132:133]
	s_mov_b32 m0, s54
	v_lshl_add_u64 v[224:225], s[26:27], 0, v[130:131]
	global_load_lds_dwordx4 v[222:223], off
	v_lshl_add_u64 v[222:223], s[52:53], 0, v[128:129]
	s_add_i32 m0, s54, 0x2000
	s_nop 0
	global_load_lds_dwordx4 v[222:223], off
	v_lshl_add_u64 v[222:223], s[26:27], 0, v[134:135]
	s_mov_b32 m0, s34
	s_nop 0
	global_load_lds_dwordx4 v[222:223], off
	s_mov_b32 m0, s35
	s_nop 0
	global_load_lds_dwordx4 v[224:225], off
	s_waitcnt vmcnt(8)
	s_waitcnt lgkmcnt(0)
	s_barrier
; #define PG8_STAGE(bufoff, gbase, voff) do { _Pragma("unroll") for (int _i = 0; _i < 2; ++_i) \
;         __builtin_amdgcn_global_load_lds((const unsigned*)((const char*)(gbase) + (voff)[_i]), (PG8_LAS unsigned*)(lds + (bufoff) + ldsw + _i * 8192), 16, 0, 0); } while (0)
; #define PG8_LDA(dst, b, h) do { _Pragma("unroll") for (int m = 0; m < 4; ++m) _Pragma("unroll") for (int k = 0; k < 2; ++k) dst[m][k] = *(const PG8_LAS bf16x8*)(lds + PG8_SA(b, h) + aoff + m * 2048 + k * 1024); } while (0)
; #define PG8_LDB(dst, b, h) do { _Pragma("unroll") for (int n = 0; n < 2; ++n) _Pragma("unroll") for (int k = 0; k < 2; ++k) dst[n][k] = *(const PG8_LAS bf16x8*)(lds + PG8_SB(b, h) + boff + n * 2048 + k * 1024); } while (0)
; #define PG8_MMA(ai, bj, At, Bt) do { __builtin_amdgcn_s_setprio(1); _Pragma("unroll") for (int m = 0; m < 4; ++m) _Pragma("unroll") for (int n = 0; n < 2; ++n) _Pragma("unroll") for (int k = 0; k < 2; ++k) \
;         acc[ai][bj][m][n] = __builtin_amdgcn_mfma_f32_16x16x32_bf16(Bt[n][k], At[m][k], acc[ai][bj][m][n], 0, 0, 0); __builtin_amdgcn_s_setprio(0); } while (0)
; #define PG8_WAIT_V(n) asm volatile("s_waitcnt vmcnt(" #n ")" ::: "memory")
; #define PG8_WAIT_L(n) asm volatile("s_waitcnt lgkmcnt(" #n ")" ::: "memory")
; #define PG8_BAR __builtin_amdgcn_s_barrier()
; #define PG8_SCHED __builtin_amdgcn_sched_barrier(0)
; template <class Epi, class Sched, bool ALIGN_EPI = false, bool SP2 = false>
; __device__ __forceinline__ void gemm_phase(PG8_LAS unsigned char* lds, const Gemm g, const Sched& S, const Epi& E) {
;     ...
;             PG8_WAIT_V(8); PG8_WAIT_L(0); PG8_BAR; PG8_MMA(1, 0, At, B0); PG8_MMA(1, 1, At, B1); PG8_BAR; PG8_SCHED;
;             PG8_LDB(B0, 1, 0); PG8_LDB(B1, 1, 1); PG8_SCHED; PG8_LDA(At, 1, 0); PG8_STAGE(PG8_SA(0, 1), a2 + hstep, voffA);
;             PG8_WAIT_V(8); PG8_WAIT_L(0); PG8_BAR; PG8_MMA(0, 0, At, B0); PG8_MMA(0, 1, At, B1); PG8_BAR; PG8_SCHED;
;             PG8_LDA(At, 1, 1); PG8_STAGE(PG8_SB(1, 0), b3, voffB); PG8_STAGE(PG8_SB(1, 1), b3 + hstep, voffB); PG8_STAGE(PG8_SA(1, 0), a3, voffA);
	s_setprio 1
	v_mfma_f32_16x16x32_bf16 v[56:59], v[144:147], v[184:187], v[56:59]
	v_mfma_f32_16x16x32_bf16 v[48:51], v[160:163], v[184:187], v[48:51]
	v_mfma_f32_16x16x32_bf16 v[40:43], v[144:147], v[194:197], v[40:43]
	v_mfma_f32_16x16x32_bf16 v[32:35], v[160:163], v[194:197], v[32:35]
	v_mfma_f32_16x16x32_bf16 v[24:27], v[144:147], v[202:205], v[24:27]
	v_mfma_f32_16x16x32_bf16 v[16:19], v[160:163], v[202:205], v[16:19]
	v_mfma_f32_16x16x32_bf16 v[8:11], v[144:147], v[210:213], v[8:11]
	v_mfma_f32_16x16x32_bf16 v[0:3], v[160:163], v[210:213], v[0:3]
	v_mfma_f32_16x16x32_bf16 v[56:59], v[156:159], v[190:193], v[56:59]
	v_mfma_f32_16x16x32_bf16 v[48:51], v[164:167], v[190:193], v[48:51]
	v_mfma_f32_16x16x32_bf16 v[40:43], v[156:159], v[198:201], v[40:43]
	v_mfma_f32_16x16x32_bf16 v[32:35], v[164:167], v[198:201], v[32:35]
	v_mfma_f32_16x16x32_bf16 v[24:27], v[156:159], v[206:209], v[24:27]
	v_mfma_f32_16x16x32_bf16 v[16:19], v[164:167], v[206:209], v[16:19]
	v_mfma_f32_16x16x32_bf16 v[8:11], v[156:159], v[214:217], v[8:11]
	v_mfma_f32_16x16x32_bf16 v[0:3], v[164:167], v[214:217], v[0:3]
	v_mfma_f32_16x16x32_bf16 v[60:63], v[168:171], v[184:187], v[60:63]
	v_mfma_f32_16x16x32_bf16 v[52:55], v[176:179], v[184:187], v[52:55]
	v_mfma_f32_16x16x32_bf16 v[44:47], v[168:171], v[194:197], v[44:47]
	v_mfma_f32_16x16x32_bf16 v[36:39], v[176:179], v[194:197], v[36:39]
	v_mfma_f32_16x16x32_bf16 v[28:31], v[168:171], v[202:205], v[28:31]
	v_mfma_f32_16x16x32_bf16 v[20:23], v[176:179], v[202:205], v[20:23]
	v_mfma_f32_16x16x32_bf16 v[12:15], v[168:171], v[210:213], v[12:15]
	v_mfma_f32_16x16x32_bf16 v[4:7], v[176:179], v[210:213], v[4:7]
	v_mfma_f32_16x16x32_bf16 v[60:63], v[172:175], v[190:193], v[60:63]
	v_mfma_f32_16x16x32_bf16 v[52:55], v[180:183], v[190:193], v[52:55]
	v_mfma_f32_16x16x32_bf16 v[44:47], v[172:175], v[198:201], v[44:47]
	v_mfma_f32_16x16x32_bf16 v[36:39], v[180:183], v[198:201], v[36:39]
	v_mfma_f32_16x16x32_bf16 v[28:31], v[172:175], v[206:209], v[28:31]
	v_mfma_f32_16x16x32_bf16 v[20:23], v[180:183], v[206:209], v[20:23]
	v_mfma_f32_16x16x32_bf16 v[12:15], v[172:175], v[214:217], v[12:15]
	v_mfma_f32_16x16x32_bf16 v[4:7], v[180:183], v[214:217], v[4:7]
	s_setprio 0
	s_barrier
	s_add_i32 s52, 0, 0x18000
	v_add_u32_e32 v155, s52, v149
	s_add_i32 s53, 0, 0x1c000
	ds_read_b128 v[144:147], v155
	ds_read_b128 v[156:159], v155 offset:1024
	ds_read_b128 v[160:163], v155 offset:2048
	ds_read_b128 v[164:167], v155 offset:3072
	v_add_u32_e32 v155, s53, v149
	ds_read_b128 v[168:171], v155
	ds_read_b128 v[172:175], v155 offset:1024
	ds_read_b128 v[176:179], v155 offset:2048
	ds_read_b128 v[180:183], v155 offset:3072
	s_add_u32 s26, s26, 0x40000
	s_addc_u32 s27, s27, 0
	s_mov_b32 m0, s36
	v_lshl_add_u64 v[226:227], s[26:27], 0, v[134:135]
	ds_read_b128 v[184:187], v153 offset:32768
	ds_read_b128 v[190:193], v153 offset:33792
	ds_read_b128 v[194:197], v153 offset:34816
	ds_read_b128 v[198:201], v153 offset:35840
	ds_read_b128 v[202:205], v153 offset:36864
	ds_read_b128 v[206:209], v153 offset:37888
	ds_read_b128 v[210:213], v153 offset:38912
	ds_read_b128 v[214:217], v153 offset:39936
	global_load_lds_dwordx4 v[226:227], off
	v_lshl_add_u64 v[226:227], s[26:27], 0, v[130:131]
	s_mov_b32 m0, s37
	s_nop 0
	global_load_lds_dwordx4 v[226:227], off
	s_waitcnt vmcnt(8)
	s_waitcnt lgkmcnt(0)
	s_barrier
	s_setprio 1
	v_mfma_f32_16x16x32_bf16 v[116:119], v[144:147], v[184:187], v[116:119]
	v_mfma_f32_16x16x32_bf16 v[112:115], v[160:163], v[184:187], v[112:115]
	v_mfma_f32_16x16x32_bf16 v[100:103], v[144:147], v[194:197], v[100:103]
	v_mfma_f32_16x16x32_bf16 v[96:99], v[160:163], v[194:197], v[96:99]
	v_mfma_f32_16x16x32_bf16 v[84:87], v[144:147], v[202:205], v[84:87]
	v_mfma_f32_16x16x32_bf16 v[80:83], v[160:163], v[202:205], v[80:83]
	v_mfma_f32_16x16x32_bf16 v[72:75], v[144:147], v[210:213], v[72:75]
	v_mfma_f32_16x16x32_bf16 v[64:67], v[160:163], v[210:213], v[64:67]
	v_mfma_f32_16x16x32_bf16 v[116:119], v[156:159], v[190:193], v[116:119]
	v_mfma_f32_16x16x32_bf16 v[112:115], v[164:167], v[190:193], v[112:115]
	v_mfma_f32_16x16x32_bf16 v[100:103], v[156:159], v[198:201], v[100:103]
	v_mfma_f32_16x16x32_bf16 v[96:99], v[164:167], v[198:201], v[96:99]
	v_mfma_f32_16x16x32_bf16 v[84:87], v[156:159], v[206:209], v[84:87]
	v_mfma_f32_16x16x32_bf16 v[80:83], v[164:167], v[206:209], v[80:83]
	v_mfma_f32_16x16x32_bf16 v[72:75], v[156:159], v[214:217], v[72:75]
	v_mfma_f32_16x16x32_bf16 v[64:67], v[164:167], v[214:217], v[64:67]
	v_mfma_f32_16x16x32_bf16 v[124:127], v[168:171], v[184:187], v[124:127]
	v_mfma_f32_16x16x32_bf16 v[120:123], v[176:179], v[184:187], v[120:123]
	v_mfma_f32_16x16x32_bf16 v[108:111], v[168:171], v[194:197], v[108:111]
	v_mfma_f32_16x16x32_bf16 v[104:107], v[176:179], v[194:197], v[104:107]
	v_mfma_f32_16x16x32_bf16 v[92:95], v[168:171], v[202:205], v[92:95]
	v_mfma_f32_16x16x32_bf16 v[88:91], v[176:179], v[202:205], v[88:91]
	v_mfma_f32_16x16x32_bf16 v[76:79], v[168:171], v[210:213], v[76:79]
	v_mfma_f32_16x16x32_bf16 v[68:71], v[176:179], v[210:213], v[68:71]
	v_mfma_f32_16x16x32_bf16 v[124:127], v[172:175], v[190:193], v[124:127]
	v_mfma_f32_16x16x32_bf16 v[120:123], v[180:183], v[190:193], v[120:123]
	v_mfma_f32_16x16x32_bf16 v[108:111], v[172:175], v[198:201], v[108:111]
	v_mfma_f32_16x16x32_bf16 v[104:107], v[180:183], v[198:201], v[104:107]
	v_mfma_f32_16x16x32_bf16 v[92:95], v[172:175], v[206:209], v[92:95]
	v_mfma_f32_16x16x32_bf16 v[88:91], v[180:183], v[206:209], v[88:91]
	v_mfma_f32_16x16x32_bf16 v[76:79], v[172:175], v[214:217], v[76:79]
	v_mfma_f32_16x16x32_bf16 v[68:71], v[180:183], v[214:217], v[68:71]
	s_setprio 0
	s_barrier
; #define PG8_STAGE(bufoff, gbase, voff) do { _Pragma("unroll") for (int _i = 0; _i < 2; ++_i) \
;         __builtin_amdgcn_global_load_lds((const unsigned*)((const char*)(gbase) + (voff)[_i]), (PG8_LAS unsigned*)(lds + (bufoff) + ldsw + _i * 8192), 16, 0, 0); } while (0)
; #define PG8_LDA(dst, b, h) do { _Pragma("unroll") for (int m = 0; m < 4; ++m) _Pragma("unroll") for (int k = 0; k < 2; ++k) dst[m][k] = *(const PG8_LAS bf16x8*)(lds + PG8_SA(b, h) + aoff + m * 2048 + k * 1024); } while (0)
; #define PG8_MMA(ai, bj, At, Bt) do { __builtin_amdgcn_s_setprio(1); _Pragma("unroll") for (int m = 0; m < 4; ++m) _Pragma("unroll") for (int n = 0; n < 2; ++n) _Pragma("unroll") for (int k = 0; k < 2; ++k) \
;         acc[ai][bj][m][n] = __builtin_amdgcn_mfma_f32_16x16x32_bf16(Bt[n][k], At[m][k], acc[ai][bj][m][n], 0, 0, 0); __builtin_amdgcn_s_setprio(0); } while (0)
; #define PG8_WAIT_V(n) asm volatile("s_waitcnt vmcnt(" #n ")" ::: "memory")
; #define PG8_WAIT_L(n) asm volatile("s_waitcnt lgkmcnt(" #n ")" ::: "memory")
; #define PG8_BAR __builtin_amdgcn_s_barrier()
; #define PG8_SCHED __builtin_amdgcn_sched_barrier(0)
; template <class Epi, class Sched, bool ALIGN_EPI = false, bool SP2 = false>
; __device__ __forceinline__ void gemm_phase(PG8_LAS unsigned char* lds, const Gemm g, const Sched& S, const Epi& E) {
;     ...
;         for (int t = 0; t < nt; t += 2) {
;             const bool last = (t == nt - 2);
;             const char* a1 = cA + (size_t)(t + 1) * kstep;
;             const char* a2 = last ? nA : cA + (size_t)(t + 2) * kstep; const char* b2 = last ? nB : cB + (size_t)(t + 2) * kstep;
;     ...
;             PG8_LDA(At, 1, 1); PG8_STAGE(PG8_SB(1, 0), b3, voffB); PG8_STAGE(PG8_SB(1, 1), b3 + hstep, voffB); PG8_STAGE(PG8_SA(1, 0), a3, voffA);
;             PG8_WAIT_V(8); PG8_WAIT_L(0); PG8_BAR; PG8_MMA(1, 0, At, B0); PG8_MMA(1, 1, At, B1); PG8_BAR; PG8_SCHED;
	s_add_i32 s26, s52, s30
	v_lshl_add_u64 v[218:219], v[218:219], 0, s[6:7]
	s_mov_b32 m0, s26
	ds_read_b128 v[184:187], v153 offset:49152
	ds_read_b128 v[190:193], v153 offset:50176
	ds_read_b128 v[194:197], v153 offset:51200
	ds_read_b128 v[198:201], v153 offset:52224
	ds_read_b128 v[202:205], v153 offset:53248
	ds_read_b128 v[206:209], v153 offset:54272
	ds_read_b128 v[210:213], v153 offset:55296
	ds_read_b128 v[214:217], v153 offset:56320
	global_load_lds_dwordx4 v[218:219], off
	s_add_i32 m0, s26, 0x2000
	s_add_u32 s24, s24, 0x40080
	v_lshl_add_u64 v[218:219], v[220:221], 0, s[6:7]
	s_addc_u32 s25, s25, 0
	s_add_i32 s26, s53, s30
	global_load_lds_dwordx4 v[218:219], off
	v_lshl_add_u64 v[218:219], s[24:25], 0, v[132:133]
	s_mov_b32 m0, s26
	s_nop 0
	global_load_lds_dwordx4 v[218:219], off
	v_lshl_add_u64 v[218:219], s[24:25], 0, v[128:129]
	s_add_i32 m0, s26, 0x2000
	s_nop 0
	global_load_lds_dwordx4 v[218:219], off
	v_lshl_add_u64 v[218:219], v[222:223], 0, s[6:7]
	s_mov_b32 m0, s39
	s_nop 0
	global_load_lds_dwordx4 v[218:219], off
	v_lshl_add_u64 v[218:219], v[224:225], 0, s[6:7]
	s_mov_b32 m0, s40
	s_nop 0
	global_load_lds_dwordx4 v[218:219], off
	s_waitcnt vmcnt(8)
	s_waitcnt lgkmcnt(0)
	s_barrier
	s_setprio 1
	v_mfma_f32_16x16x32_bf16 v[56:59], v[144:147], v[184:187], v[56:59]
	v_mfma_f32_16x16x32_bf16 v[48:51], v[160:163], v[184:187], v[48:51]
	v_mfma_f32_16x16x32_bf16 v[40:43], v[144:147], v[194:197], v[40:43]
	v_mfma_f32_16x16x32_bf16 v[32:35], v[160:163], v[194:197], v[32:35]
	v_mfma_f32_16x16x32_bf16 v[24:27], v[144:147], v[202:205], v[24:27]
	v_mfma_f32_16x16x32_bf16 v[16:19], v[160:163], v[202:205], v[16:19]
	v_mfma_f32_16x16x32_bf16 v[8:11], v[144:147], v[210:213], v[8:11]
	v_mfma_f32_16x16x32_bf16 v[0:3], v[160:163], v[210:213], v[0:3]
	v_mfma_f32_16x16x32_bf16 v[56:59], v[156:159], v[190:193], v[56:59]
	v_mfma_f32_16x16x32_bf16 v[48:51], v[164:167], v[190:193], v[48:51]
	v_mfma_f32_16x16x32_bf16 v[40:43], v[156:159], v[198:201], v[40:43]
	v_mfma_f32_16x16x32_bf16 v[32:35], v[164:167], v[198:201], v[32:35]
	v_mfma_f32_16x16x32_bf16 v[24:27], v[156:159], v[206:209], v[24:27]
	v_mfma_f32_16x16x32_bf16 v[16:19], v[164:167], v[206:209], v[16:19]
	v_mfma_f32_16x16x32_bf16 v[8:11], v[156:159], v[214:217], v[8:11]
	v_mfma_f32_16x16x32_bf16 v[0:3], v[164:167], v[214:217], v[0:3]
	v_mfma_f32_16x16x32_bf16 v[60:63], v[168:171], v[184:187], v[60:63]
	v_mfma_f32_16x16x32_bf16 v[52:55], v[176:179], v[184:187], v[52:55]
	v_mfma_f32_16x16x32_bf16 v[44:47], v[168:171], v[194:197], v[44:47]
	v_mfma_f32_16x16x32_bf16 v[36:39], v[176:179], v[194:197], v[36:39]
	v_mfma_f32_16x16x32_bf16 v[28:31], v[168:171], v[202:205], v[28:31]
	v_mfma_f32_16x16x32_bf16 v[20:23], v[176:179], v[202:205], v[20:23]
	v_mfma_f32_16x16x32_bf16 v[12:15], v[168:171], v[210:213], v[12:15]
	v_mfma_f32_16x16x32_bf16 v[4:7], v[176:179], v[210:213], v[4:7]
	v_mfma_f32_16x16x32_bf16 v[60:63], v[172:175], v[190:193], v[60:63]
	v_mfma_f32_16x16x32_bf16 v[52:55], v[180:183], v[190:193], v[52:55]
	v_mfma_f32_16x16x32_bf16 v[44:47], v[172:175], v[198:201], v[44:47]
	v_mfma_f32_16x16x32_bf16 v[36:39], v[180:183], v[198:201], v[36:39]
	v_mfma_f32_16x16x32_bf16 v[28:31], v[172:175], v[206:209], v[28:31]
	v_mfma_f32_16x16x32_bf16 v[20:23], v[180:183], v[206:209], v[20:23]
	v_mfma_f32_16x16x32_bf16 v[12:15], v[172:175], v[214:217], v[12:15]
	v_mfma_f32_16x16x32_bf16 v[4:7], v[180:183], v[214:217], v[4:7]
	s_setprio 0
	s_barrier
	s_add_i32 s51, s51, 2
	s_add_u32 s22, s22, 0x100
	s_addc_u32 s23, s23, 0
	s_add_u32 s49, s49, 0x100
	s_addc_u32 s50, s50, 0
	s_cmp_gt_u32 s51, 13
	s_cbranch_scc0 .LBB0_782
	s_and_b64 vcc, exec, s[12:13]
	s_cbranch_vccz .LBB0_785
	s_barrier

; #define PG8_STAGE(bufoff, gbase, voff) do { _Pragma("unroll") for (int _i = 0; _i < 2; ++_i) \
;         __builtin_amdgcn_global_load_lds((const unsigned*)((const char*)(gbase) + (voff)[_i]), (PG8_LAS unsigned*)(lds + (bufoff) + ldsw + _i * 8192), 16, 0, 0); } while (0)
; #define PG8_LDA(dst, b, h) do { _Pragma("unroll") for (int m = 0; m < 4; ++m) _Pragma("unroll") for (int k = 0; k < 2; ++k) dst[m][k] = *(const PG8_LAS bf16x8*)(lds + PG8_SA(b, h) + aoff + m * 2048 + k * 1024); } while (0)
; #define PG8_LDB(dst, b, h) do { _Pragma("unroll") for (int n = 0; n < 2; ++n) _Pragma("unroll") for (int k = 0; k < 2; ++k) dst[n][k] = *(const PG8_LAS bf16x8*)(lds + PG8_SB(b, h) + boff + n * 2048 + k * 1024); } while (0)
; #define PG8_MMA(ai, bj, At, Bt) do { __builtin_amdgcn_s_setprio(1); _Pragma("unroll") for (int m = 0; m < 4; ++m) _Pragma("unroll") for (int n = 0; n < 2; ++n) _Pragma("unroll") for (int k = 0; k < 2; ++k) \
;         acc[ai][bj][m][n] = __builtin_amdgcn_mfma_f32_16x16x32_bf16(Bt[n][k], At[m][k], acc[ai][bj][m][n], 0, 0, 0); __builtin_amdgcn_s_setprio(0); } while (0)
; #define PG8_WAIT_V(n) asm volatile("s_waitcnt vmcnt(" #n ")" ::: "memory")
; #define PG8_WAIT_L(n) asm volatile("s_waitcnt lgkmcnt(" #n ")" ::: "memory")
; #define PG8_BAR __builtin_amdgcn_s_barrier()
; #define PG8_SCHED __builtin_amdgcn_sched_barrier(0)
; template <class Epi, class Sched, bool ALIGN_EPI = false, bool SP2 = false>
; __device__ __forceinline__ void gemm_phase(PG8_LAS unsigned char* lds, const Gemm g, const Sched& S, const Epi& E) {
;     ...
;             PG8_LDB(B0, 0, 0); PG8_LDB(B1, 0, 1); PG8_SCHED; PG8_LDA(At, 0, 0); PG8_STAGE(PG8_SA(1, 1), a1 + hstep, voffA);
;             PG8_WAIT_V(8); PG8_WAIT_L(0); PG8_BAR; PG8_MMA(0, 0, At, B0); PG8_MMA(0, 1, At, B1); PG8_BAR; PG8_SCHED;
;             PG8_LDA(At, 0, 1); PG8_STAGE(PG8_SB(0, 0), b2, voffB); PG8_STAGE(PG8_SB(0, 1), b2 + hstep, voffB); PG8_STAGE(PG8_SA(0, 0), a2, voffA);
;             PG8_WAIT_V(8); PG8_WAIT_L(0); PG8_BAR; PG8_MMA(1, 0, At, B0); PG8_MMA(1, 1, At, B1); PG8_BAR; PG8_SCHED;
.LBB0_862:
	ds_read_b128 v[144:147], v153
	ds_read_b128 v[156:159], v153 offset:1024
	ds_read_b128 v[160:163], v153 offset:2048
	ds_read_b128 v[164:167], v153 offset:3072
	ds_read_b128 v[168:171], v154
	ds_read_b128 v[172:175], v154 offset:1024
	ds_read_b128 v[176:179], v154 offset:2048
	ds_read_b128 v[180:183], v154 offset:3072
	s_add_u32 s24, s22, 0x100
	s_addc_u32 s25, s23, 0
	s_cmp_eq_u32 s51, 40
	s_cselect_b32 s29, s5, s25
	s_cselect_b32 s28, s4, s24
	s_cselect_b32 s27, s21, s50
	s_cselect_b32 s26, s20, s49
	v_lshl_add_u64 v[148:149], s[22:23], 0, v[136:137]
	s_add_i32 m0, s35, 0xc000
	ds_read_b128 v[184:187], v155
	ds_read_b128 v[188:191], v155 offset:1024
	ds_read_b128 v[192:195], v155 offset:2048
	ds_read_b128 v[196:199], v155 offset:3072
	ds_read_b128 v[200:203], v155 offset:4096
	ds_read_b128 v[204:207], v155 offset:5120
	ds_read_b128 v[208:211], v155 offset:6144
	ds_read_b128 v[212:215], v155 offset:7168
	global_load_lds_dwordx4 v[148:149], off
	v_lshl_add_u64 v[148:149], s[22:23], 0, v[138:139]
	s_add_i32 m0, s35, 0xe000
	s_nop 0
	global_load_lds_dwordx4 v[148:149], off
	s_waitcnt vmcnt(8)
	s_waitcnt lgkmcnt(0)
	s_barrier
	s_setprio 1
	v_mfma_f32_16x16x32_bf16 v[124:127], v[144:147], v[184:187], v[124:127]
	v_mfma_f32_16x16x32_bf16 v[120:123], v[160:163], v[184:187], v[120:123]
	v_mfma_f32_16x16x32_bf16 v[108:111], v[144:147], v[192:195], v[108:111]
	v_mfma_f32_16x16x32_bf16 v[104:107], v[160:163], v[192:195], v[104:107]
	v_mfma_f32_16x16x32_bf16 v[92:95], v[144:147], v[200:203], v[92:95]
	v_mfma_f32_16x16x32_bf16 v[88:91], v[160:163], v[200:203], v[88:91]
	v_mfma_f32_16x16x32_bf16 v[76:79], v[144:147], v[208:211], v[76:79]
	v_mfma_f32_16x16x32_bf16 v[72:75], v[160:163], v[208:211], v[72:75]
	v_mfma_f32_16x16x32_bf16 v[124:127], v[156:159], v[188:191], v[124:127]
	v_mfma_f32_16x16x32_bf16 v[120:123], v[164:167], v[188:191], v[120:123]
	v_mfma_f32_16x16x32_bf16 v[108:111], v[156:159], v[196:199], v[108:111]
	v_mfma_f32_16x16x32_bf16 v[104:107], v[164:167], v[196:199], v[104:107]
	v_mfma_f32_16x16x32_bf16 v[92:95], v[156:159], v[204:207], v[92:95]
	v_mfma_f32_16x16x32_bf16 v[88:91], v[164:167], v[204:207], v[88:91]
	v_mfma_f32_16x16x32_bf16 v[76:79], v[156:159], v[212:215], v[76:79]
	v_mfma_f32_16x16x32_bf16 v[72:75], v[164:167], v[212:215], v[72:75]
	v_mfma_f32_16x16x32_bf16 v[116:119], v[168:171], v[184:187], v[116:119]
	v_mfma_f32_16x16x32_bf16 v[112:115], v[176:179], v[184:187], v[112:115]
	v_mfma_f32_16x16x32_bf16 v[100:103], v[168:171], v[192:195], v[100:103]
	v_mfma_f32_16x16x32_bf16 v[96:99], v[176:179], v[192:195], v[96:99]
	v_mfma_f32_16x16x32_bf16 v[84:87], v[168:171], v[200:203], v[84:87]
	v_mfma_f32_16x16x32_bf16 v[80:83], v[176:179], v[200:203], v[80:83]
	v_mfma_f32_16x16x32_bf16 v[68:71], v[168:171], v[208:211], v[68:71]
	v_mfma_f32_16x16x32_bf16 v[64:67], v[176:179], v[208:211], v[64:67]
	v_mfma_f32_16x16x32_bf16 v[116:119], v[172:175], v[188:191], v[116:119]
	v_mfma_f32_16x16x32_bf16 v[112:115], v[180:183], v[188:191], v[112:115]
	v_mfma_f32_16x16x32_bf16 v[100:103], v[172:175], v[196:199], v[100:103]
	v_mfma_f32_16x16x32_bf16 v[96:99], v[180:183], v[196:199], v[96:99]
	v_mfma_f32_16x16x32_bf16 v[84:87], v[172:175], v[204:207], v[84:87]
	v_mfma_f32_16x16x32_bf16 v[80:83], v[180:183], v[204:207], v[80:83]
	v_mfma_f32_16x16x32_bf16 v[68:71], v[172:175], v[212:215], v[68:71]
	v_mfma_f32_16x16x32_bf16 v[64:67], v[180:183], v[212:215], v[64:67]
	s_setprio 0
	s_barrier
	s_add_i32 s22, s43, s34
	v_lshl_add_u64 v[148:149], s[26:27], 0, v[130:131]
	s_mov_b32 m0, s22
	ds_read_b128 v[184:187], v155 offset:16384
	ds_read_b128 v[188:191], v155 offset:17408
	ds_read_b128 v[192:195], v155 offset:18432
	ds_read_b128 v[196:199], v155 offset:19456
	ds_read_b128 v[200:203], v155 offset:20480
	ds_read_b128 v[204:207], v155 offset:21504
	ds_read_b128 v[208:211], v155 offset:22528
	ds_read_b128 v[212:215], v155 offset:23552
	global_load_lds_dwordx4 v[148:149], off
	s_add_i32 m0, s22, 0x2000
	s_add_u32 s22, s26, 0xb0000
	v_lshl_add_u64 v[216:217], s[26:27], 0, v[134:135]
	s_addc_u32 s23, s27, 0
	s_add_i32 s52, s44, s34
	global_load_lds_dwordx4 v[216:217], off
	v_lshl_add_u64 v[218:219], s[22:23], 0, v[130:131]
	s_mov_b32 m0, s52
	v_lshl_add_u64 v[220:221], s[28:29], 0, v[132:133]
	global_load_lds_dwordx4 v[218:219], off
	v_lshl_add_u64 v[218:219], s[22:23], 0, v[134:135]
	s_add_i32 m0, s52, 0x2000
	s_nop 0
	global_load_lds_dwordx4 v[218:219], off
	v_lshl_add_u64 v[218:219], s[28:29], 0, v[128:129]
	s_mov_b32 m0, s35
	s_nop 0
	global_load_lds_dwordx4 v[218:219], off
	s_mov_b32 m0, s36
	s_nop 0
	global_load_lds_dwordx4 v[220:221], off
	s_waitcnt vmcnt(8)
	s_waitcnt lgkmcnt(0)
	s_barrier
; #define PG8_STAGE(bufoff, gbase, voff) do { _Pragma("unroll") for (int _i = 0; _i < 2; ++_i) \
;         __builtin_amdgcn_global_load_lds((const unsigned*)((const char*)(gbase) + (voff)[_i]), (PG8_LAS unsigned*)(lds + (bufoff) + ldsw + _i * 8192), 16, 0, 0); } while (0)
; #define PG8_LDA(dst, b, h) do { _Pragma("unroll") for (int m = 0; m < 4; ++m) _Pragma("unroll") for (int k = 0; k < 2; ++k) dst[m][k] = *(const PG8_LAS bf16x8*)(lds + PG8_SA(b, h) + aoff + m * 2048 + k * 1024); } while (0)
; #define PG8_LDB(dst, b, h) do { _Pragma("unroll") for (int n = 0; n < 2; ++n) _Pragma("unroll") for (int k = 0; k < 2; ++k) dst[n][k] = *(const PG8_LAS bf16x8*)(lds + PG8_SB(b, h) + boff + n * 2048 + k * 1024); } while (0)
; #define PG8_MMA(ai, bj, At, Bt) do { __builtin_amdgcn_s_setprio(1); _Pragma("unroll") for (int m = 0; m < 4; ++m) _Pragma("unroll") for (int n = 0; n < 2; ++n) _Pragma("unroll") for (int k = 0; k < 2; ++k) \
;         acc[ai][bj][m][n] = __builtin_amdgcn_mfma_f32_16x16x32_bf16(Bt[n][k], At[m][k], acc[ai][bj][m][n], 0, 0, 0); __builtin_amdgcn_s_setprio(0); } while (0)
; #define PG8_WAIT_V(n) asm volatile("s_waitcnt vmcnt(" #n ")" ::: "memory")
; #define PG8_WAIT_L(n) asm volatile("s_waitcnt lgkmcnt(" #n ")" ::: "memory")
; #define PG8_BAR __builtin_amdgcn_s_barrier()
; #define PG8_SCHED __builtin_amdgcn_sched_barrier(0)
; template <class Epi, class Sched, bool ALIGN_EPI = false, bool SP2 = false>
; __device__ __forceinline__ void gemm_phase(PG8_LAS unsigned char* lds, const Gemm g, const Sched& S, const Epi& E) {
;     ...
;             PG8_WAIT_V(8); PG8_WAIT_L(0); PG8_BAR; PG8_MMA(1, 0, At, B0); PG8_MMA(1, 1, At, B1); PG8_BAR; PG8_SCHED;
;             PG8_LDB(B0, 1, 0); PG8_LDB(B1, 1, 1); PG8_SCHED; PG8_LDA(At, 1, 0); PG8_STAGE(PG8_SA(0, 1), a2 + hstep, voffA);
;             PG8_WAIT_V(8); PG8_WAIT_L(0); PG8_BAR; PG8_MMA(0, 0, At, B0); PG8_MMA(0, 1, At, B1); PG8_BAR; PG8_SCHED;
	s_setprio 1
	v_mfma_f32_16x16x32_bf16 v[60:63], v[144:147], v[184:187], v[60:63]
	v_mfma_f32_16x16x32_bf16 v[56:59], v[160:163], v[184:187], v[56:59]
	v_mfma_f32_16x16x32_bf16 v[44:47], v[144:147], v[192:195], v[44:47]
	v_mfma_f32_16x16x32_bf16 v[40:43], v[160:163], v[192:195], v[40:43]
	v_mfma_f32_16x16x32_bf16 v[28:31], v[144:147], v[200:203], v[28:31]
	v_mfma_f32_16x16x32_bf16 v[24:27], v[160:163], v[200:203], v[24:27]
	v_mfma_f32_16x16x32_bf16 v[12:15], v[144:147], v[208:211], v[12:15]
	v_mfma_f32_16x16x32_bf16 v[8:11], v[160:163], v[208:211], v[8:11]
	v_mfma_f32_16x16x32_bf16 v[60:63], v[156:159], v[188:191], v[60:63]
	v_mfma_f32_16x16x32_bf16 v[56:59], v[164:167], v[188:191], v[56:59]
	v_mfma_f32_16x16x32_bf16 v[44:47], v[156:159], v[196:199], v[44:47]
	v_mfma_f32_16x16x32_bf16 v[40:43], v[164:167], v[196:199], v[40:43]
	v_mfma_f32_16x16x32_bf16 v[28:31], v[156:159], v[204:207], v[28:31]
	v_mfma_f32_16x16x32_bf16 v[24:27], v[164:167], v[204:207], v[24:27]
	v_mfma_f32_16x16x32_bf16 v[12:15], v[156:159], v[212:215], v[12:15]
	v_mfma_f32_16x16x32_bf16 v[8:11], v[164:167], v[212:215], v[8:11]
	v_mfma_f32_16x16x32_bf16 v[52:55], v[168:171], v[184:187], v[52:55]
	v_mfma_f32_16x16x32_bf16 v[48:51], v[176:179], v[184:187], v[48:51]
	v_mfma_f32_16x16x32_bf16 v[36:39], v[168:171], v[192:195], v[36:39]
	v_mfma_f32_16x16x32_bf16 v[32:35], v[176:179], v[192:195], v[32:35]
	v_mfma_f32_16x16x32_bf16 v[20:23], v[168:171], v[200:203], v[20:23]
	v_mfma_f32_16x16x32_bf16 v[16:19], v[176:179], v[200:203], v[16:19]
	v_mfma_f32_16x16x32_bf16 v[4:7], v[168:171], v[208:211], v[4:7]
	v_mfma_f32_16x16x32_bf16 v[0:3], v[176:179], v[208:211], v[0:3]
	v_mfma_f32_16x16x32_bf16 v[52:55], v[172:175], v[188:191], v[52:55]
	v_mfma_f32_16x16x32_bf16 v[48:51], v[180:183], v[188:191], v[48:51]
	v_mfma_f32_16x16x32_bf16 v[36:39], v[172:175], v[196:199], v[36:39]
	v_mfma_f32_16x16x32_bf16 v[32:35], v[180:183], v[196:199], v[32:35]
	v_mfma_f32_16x16x32_bf16 v[20:23], v[172:175], v[204:207], v[20:23]
	v_mfma_f32_16x16x32_bf16 v[16:19], v[180:183], v[204:207], v[16:19]
	v_mfma_f32_16x16x32_bf16 v[4:7], v[172:175], v[212:215], v[4:7]
	v_mfma_f32_16x16x32_bf16 v[0:3], v[180:183], v[212:215], v[0:3]
	s_setprio 0
	s_barrier
	s_add_i32 s52, 0, 0x18000
	s_add_i32 s53, 0, 0x1c000
	v_add_u32_e32 v164, s52, v151
	v_add_u32_e32 v180, s53, v151
	ds_read_b128 v[144:147], v164
	ds_read_b128 v[156:159], v164 offset:1024
	ds_read_b128 v[160:163], v164 offset:2048
	ds_read_b128 v[164:167], v164 offset:3072
	ds_read_b128 v[168:171], v180
	ds_read_b128 v[172:175], v180 offset:1024
	ds_read_b128 v[176:179], v180 offset:2048
	ds_read_b128 v[180:183], v180 offset:3072
	s_add_u32 s22, s28, 0xb0000
	s_addc_u32 s23, s29, 0
	s_mov_b32 m0, s37
	v_lshl_add_u64 v[222:223], s[22:23], 0, v[128:129]
	ds_read_b128 v[184:187], v155 offset:32768
	ds_read_b128 v[188:191], v155 offset:33792
	ds_read_b128 v[192:195], v155 offset:34816
	ds_read_b128 v[196:199], v155 offset:35840
	ds_read_b128 v[200:203], v155 offset:36864
	ds_read_b128 v[204:207], v155 offset:37888
	ds_read_b128 v[208:211], v155 offset:38912
	ds_read_b128 v[212:215], v155 offset:39936
	global_load_lds_dwordx4 v[222:223], off
	v_lshl_add_u64 v[222:223], s[22:23], 0, v[132:133]
	s_mov_b32 m0, s38
	s_nop 0
	global_load_lds_dwordx4 v[222:223], off
	s_waitcnt vmcnt(8)
	s_waitcnt lgkmcnt(0)
	s_barrier
	s_setprio 1
	v_mfma_f32_16x16x32_bf16 v[124:127], v[144:147], v[184:187], v[124:127]
	v_mfma_f32_16x16x32_bf16 v[120:123], v[160:163], v[184:187], v[120:123]
	v_mfma_f32_16x16x32_bf16 v[108:111], v[144:147], v[192:195], v[108:111]
	v_mfma_f32_16x16x32_bf16 v[104:107], v[160:163], v[192:195], v[104:107]
	v_mfma_f32_16x16x32_bf16 v[92:95], v[144:147], v[200:203], v[92:95]
	v_mfma_f32_16x16x32_bf16 v[88:91], v[160:163], v[200:203], v[88:91]
	v_mfma_f32_16x16x32_bf16 v[76:79], v[144:147], v[208:211], v[76:79]
	v_mfma_f32_16x16x32_bf16 v[72:75], v[160:163], v[208:211], v[72:75]
	v_mfma_f32_16x16x32_bf16 v[124:127], v[156:159], v[188:191], v[124:127]
	v_mfma_f32_16x16x32_bf16 v[120:123], v[164:167], v[188:191], v[120:123]
	v_mfma_f32_16x16x32_bf16 v[108:111], v[156:159], v[196:199], v[108:111]
	v_mfma_f32_16x16x32_bf16 v[104:107], v[164:167], v[196:199], v[104:107]
	v_mfma_f32_16x16x32_bf16 v[92:95], v[156:159], v[204:207], v[92:95]
	v_mfma_f32_16x16x32_bf16 v[88:91], v[164:167], v[204:207], v[88:91]
	v_mfma_f32_16x16x32_bf16 v[76:79], v[156:159], v[212:215], v[76:79]
	v_mfma_f32_16x16x32_bf16 v[72:75], v[164:167], v[212:215], v[72:75]
	v_mfma_f32_16x16x32_bf16 v[116:119], v[168:171], v[184:187], v[116:119]
	v_mfma_f32_16x16x32_bf16 v[112:115], v[176:179], v[184:187], v[112:115]
	v_mfma_f32_16x16x32_bf16 v[100:103], v[168:171], v[192:195], v[100:103]
	v_mfma_f32_16x16x32_bf16 v[96:99], v[176:179], v[192:195], v[96:99]
	v_mfma_f32_16x16x32_bf16 v[84:87], v[168:171], v[200:203], v[84:87]
	v_mfma_f32_16x16x32_bf16 v[80:83], v[176:179], v[200:203], v[80:83]
	v_mfma_f32_16x16x32_bf16 v[68:71], v[168:171], v[208:211], v[68:71]
	v_mfma_f32_16x16x32_bf16 v[64:67], v[176:179], v[208:211], v[64:67]
	v_mfma_f32_16x16x32_bf16 v[116:119], v[172:175], v[188:191], v[116:119]
	v_mfma_f32_16x16x32_bf16 v[112:115], v[180:183], v[188:191], v[112:115]
	v_mfma_f32_16x16x32_bf16 v[100:103], v[172:175], v[196:199], v[100:103]
	v_mfma_f32_16x16x32_bf16 v[96:99], v[180:183], v[196:199], v[96:99]
	v_mfma_f32_16x16x32_bf16 v[84:87], v[172:175], v[204:207], v[84:87]
	v_mfma_f32_16x16x32_bf16 v[80:83], v[180:183], v[204:207], v[80:83]
	v_mfma_f32_16x16x32_bf16 v[68:71], v[172:175], v[212:215], v[68:71]
	v_mfma_f32_16x16x32_bf16 v[64:67], v[180:183], v[212:215], v[64:67]
	s_setprio 0
	s_barrier
; #define PG8_STAGE(bufoff, gbase, voff) do { _Pragma("unroll") for (int _i = 0; _i < 2; ++_i) \
;         __builtin_amdgcn_global_load_lds((const unsigned*)((const char*)(gbase) + (voff)[_i]), (PG8_LAS unsigned*)(lds + (bufoff) + ldsw + _i * 8192), 16, 0, 0); } while (0)
; #define PG8_LDA(dst, b, h) do { _Pragma("unroll") for (int m = 0; m < 4; ++m) _Pragma("unroll") for (int k = 0; k < 2; ++k) dst[m][k] = *(const PG8_LAS bf16x8*)(lds + PG8_SA(b, h) + aoff + m * 2048 + k * 1024); } while (0)
; #define PG8_MMA(ai, bj, At, Bt) do { __builtin_amdgcn_s_setprio(1); _Pragma("unroll") for (int m = 0; m < 4; ++m) _Pragma("unroll") for (int n = 0; n < 2; ++n) _Pragma("unroll") for (int k = 0; k < 2; ++k) \
;         acc[ai][bj][m][n] = __builtin_amdgcn_mfma_f32_16x16x32_bf16(Bt[n][k], At[m][k], acc[ai][bj][m][n], 0, 0, 0); __builtin_amdgcn_s_setprio(0); } while (0)
; #define PG8_WAIT_V(n) asm volatile("s_waitcnt vmcnt(" #n ")" ::: "memory")
; #define PG8_WAIT_L(n) asm volatile("s_waitcnt lgkmcnt(" #n ")" ::: "memory")
; #define PG8_BAR __builtin_amdgcn_s_barrier()
; #define PG8_SCHED __builtin_amdgcn_sched_barrier(0)
; template <class Epi, class Sched, bool ALIGN_EPI = false, bool SP2 = false>
; __device__ __forceinline__ void gemm_phase(PG8_LAS unsigned char* lds, const Gemm g, const Sched& S, const Epi& E) {
;     ...
;         for (int t = 0; t < nt; t += 2) {
;             const bool last = (t == nt - 2);
;             const char* a1 = cA + (size_t)(t + 1) * kstep;
;             const char* a2 = last ? nA : cA + (size_t)(t + 2) * kstep; const char* b2 = last ? nB : cB + (size_t)(t + 2) * kstep;
;     ...
;             PG8_LDA(At, 1, 1); PG8_STAGE(PG8_SB(1, 0), b3, voffB); PG8_STAGE(PG8_SB(1, 1), b3 + hstep, voffB); PG8_STAGE(PG8_SA(1, 0), a3, voffA);
;             PG8_WAIT_V(8); PG8_WAIT_L(0); PG8_BAR; PG8_MMA(1, 0, At, B0); PG8_MMA(1, 1, At, B1); PG8_BAR; PG8_SCHED;
	s_add_i32 s22, s52, s34
	v_lshl_add_u64 v[148:149], v[148:149], 0, s[6:7]
	s_mov_b32 m0, s22
	ds_read_b128 v[184:187], v155 offset:49152
	ds_read_b128 v[188:191], v155 offset:50176
	ds_read_b128 v[192:195], v155 offset:51200
	ds_read_b128 v[196:199], v155 offset:52224
	ds_read_b128 v[200:203], v155 offset:53248
	ds_read_b128 v[204:207], v155 offset:54272
	ds_read_b128 v[208:211], v155 offset:55296
	ds_read_b128 v[212:215], v155 offset:56320
	global_load_lds_dwordx4 v[148:149], off
	s_add_i32 m0, s22, 0x2000
	s_add_u32 s22, s26, 0xb0080
	v_lshl_add_u64 v[148:149], v[216:217], 0, s[6:7]
	s_addc_u32 s23, s27, 0
	s_add_i32 s26, s53, s34
	global_load_lds_dwordx4 v[148:149], off
	v_lshl_add_u64 v[148:149], s[22:23], 0, v[130:131]
	s_mov_b32 m0, s26
	s_nop 0
	global_load_lds_dwordx4 v[148:149], off
	v_lshl_add_u64 v[148:149], s[22:23], 0, v[134:135]
	s_add_i32 m0, s26, 0x2000
	s_nop 0
	global_load_lds_dwordx4 v[148:149], off
	v_lshl_add_u64 v[148:149], v[218:219], 0, s[6:7]
	s_mov_b32 m0, s40
	s_nop 0
	global_load_lds_dwordx4 v[148:149], off
	v_lshl_add_u64 v[148:149], v[220:221], 0, s[6:7]
	s_mov_b32 m0, s41
	s_nop 0
	global_load_lds_dwordx4 v[148:149], off
	s_waitcnt vmcnt(8)
	s_waitcnt lgkmcnt(0)
	s_barrier
	s_setprio 1
	v_mfma_f32_16x16x32_bf16 v[60:63], v[144:147], v[184:187], v[60:63]
	v_mfma_f32_16x16x32_bf16 v[56:59], v[160:163], v[184:187], v[56:59]
	v_mfma_f32_16x16x32_bf16 v[44:47], v[144:147], v[192:195], v[44:47]
	v_mfma_f32_16x16x32_bf16 v[40:43], v[160:163], v[192:195], v[40:43]
	v_mfma_f32_16x16x32_bf16 v[28:31], v[144:147], v[200:203], v[28:31]
	v_mfma_f32_16x16x32_bf16 v[24:27], v[160:163], v[200:203], v[24:27]
	v_mfma_f32_16x16x32_bf16 v[12:15], v[144:147], v[208:211], v[12:15]
	v_mfma_f32_16x16x32_bf16 v[8:11], v[160:163], v[208:211], v[8:11]
	v_mfma_f32_16x16x32_bf16 v[60:63], v[156:159], v[188:191], v[60:63]
	v_mfma_f32_16x16x32_bf16 v[56:59], v[164:167], v[188:191], v[56:59]
	v_mfma_f32_16x16x32_bf16 v[44:47], v[156:159], v[196:199], v[44:47]
	v_mfma_f32_16x16x32_bf16 v[40:43], v[164:167], v[196:199], v[40:43]
	v_mfma_f32_16x16x32_bf16 v[28:31], v[156:159], v[204:207], v[28:31]
	v_mfma_f32_16x16x32_bf16 v[24:27], v[164:167], v[204:207], v[24:27]
	v_mfma_f32_16x16x32_bf16 v[12:15], v[156:159], v[212:215], v[12:15]
	v_mfma_f32_16x16x32_bf16 v[8:11], v[164:167], v[212:215], v[8:11]
	v_mfma_f32_16x16x32_bf16 v[52:55], v[168:171], v[184:187], v[52:55]
	v_mfma_f32_16x16x32_bf16 v[48:51], v[176:179], v[184:187], v[48:51]
	v_mfma_f32_16x16x32_bf16 v[36:39], v[168:171], v[192:195], v[36:39]
	v_mfma_f32_16x16x32_bf16 v[32:35], v[176:179], v[192:195], v[32:35]
	v_mfma_f32_16x16x32_bf16 v[20:23], v[168:171], v[200:203], v[20:23]
	v_mfma_f32_16x16x32_bf16 v[16:19], v[176:179], v[200:203], v[16:19]
	v_mfma_f32_16x16x32_bf16 v[4:7], v[168:171], v[208:211], v[4:7]
	v_mfma_f32_16x16x32_bf16 v[0:3], v[176:179], v[208:211], v[0:3]
	v_mfma_f32_16x16x32_bf16 v[52:55], v[172:175], v[188:191], v[52:55]
	v_mfma_f32_16x16x32_bf16 v[48:51], v[180:183], v[188:191], v[48:51]
	v_mfma_f32_16x16x32_bf16 v[36:39], v[172:175], v[196:199], v[36:39]
	v_mfma_f32_16x16x32_bf16 v[32:35], v[180:183], v[196:199], v[32:35]
	v_mfma_f32_16x16x32_bf16 v[20:23], v[172:175], v[204:207], v[20:23]
	v_mfma_f32_16x16x32_bf16 v[16:19], v[180:183], v[204:207], v[16:19]
	v_mfma_f32_16x16x32_bf16 v[4:7], v[172:175], v[212:215], v[4:7]
	v_mfma_f32_16x16x32_bf16 v[0:3], v[180:183], v[212:215], v[0:3]
	s_setprio 0
	s_barrier
	s_add_i32 s51, s51, 2
	s_add_u32 s49, s49, 0x100
	s_addc_u32 s50, s50, 0
	s_cmp_gt_u32 s51, 41
	s_mov_b64 s[22:23], s[24:25]
	s_cbranch_scc0 .LBB0_862
	s_and_b64 vcc, exec, s[10:11]
	s_cbranch_vccz .LBB0_865
	s_barrier
